# S5 phases: counted vmcnt waits, C x stage software-pipelined one quad behind (double-buffered LDS tile), packed-f32 complex recurrence via v_pk_mov of re/im accumulator pairs
# speedup vs baseline: 1.0267x; 1.0030x over previous
; __device__ __forceinline__ bf16x8 pack8(const float (&f)[8]) { u32x4 h; h.x = pk2(f[0], f[1]); h.y = pk2(f[2], f[3]); h.z = pk2(f[4], f[5]); h.w = pk2(f[6], f[7]); return __builtin_bit_cast(bf16x8, h); }
;     __device__ __forceinline__ bf16* R(int i) const { return (bf16*)(ws + OFF_R0 + (size_t)i * RSZ); }
; template <bool FINAL> __device__ __forceinline__ void phase_s5_scan(const Fr& F) {
;     const bf16* U = F.R(1); float* E = (float*)F.R(6);
;     float* BUl = (float*)(F.lds + F.wave * 16384);
;     const int lane = F.lane, l15 = lane & 15, lq = lane >> 4;
;     const float* BBf = (const float*)(F.ws + OFF_BB);
;     const int sg = F.gw >> 4, g = sg & 63, s = sg >> 6;
;     const f32x4 av = *(const f32x4*)((const float*)(F.ws + OFF_S5A) + (sg * 64 + lane) * 4);
;     const float ar = av.x, ai = av.y;
;     bf16x8 B1[8];
; #pragma unroll
;     for (int nt = 0; nt < 8; ++nt) {
;         const int n = 16 * nt + l15; const float* bp = BBf + (size_t)(sg * 64 + (n & 63)) * 32 + 16 * (n >> 6) + 8 * (lq & 1);
;         const f32x4 t0 = *(const f32x4*)bp, t1 = *(const f32x4*)(bp + 4); const float f[8] = {t0.x, t0.y, t0.z, t0.w, t1.x, t1.y, t1.z, t1.w};
;         B1[nt] = lq < 2 ? pack8(f) : (bf16x8){0, 0, 0, 0, 0, 0, 0, 0};
;     }
;     bf16x8 Chi[4];
;     if (FINAL) {
; #pragma unroll
;         for (int ks = 0; ks < 4; ++ks) {
;             const int k = 32 * ks + 8 * lq; const float* cp = (k < 64 ? F.a->in[32] : F.a->in[33]) + (size_t)g * 1024 + l15 * 64 + (k & 63); const float sg_ = k < 64 ? 1.f : -1.f;
;             const f32x4 t0 = *(const f32x4*)cp, t1 = *(const f32x4*)(cp + 4); const float f[8] = {sg_ * t0.x, sg_ * t0.y, sg_ * t0.z, sg_ * t0.w, sg_ * t1.x, sg_ * t1.y, sg_ * t1.z, sg_ * t1.w};
;             Chi[ks] = pack8(f);
;         }
;     }
;     u32x4 ua[4]; float e0 = 0.f, e1 = 0.f;
;     {   const int ti = F.gw & 15, b = ti / 68, chunk = ti - b * 68;
; #pragma unroll
;         for (int sb = 0; sb < 4; ++sb) ua[sb] = lq < 2 ? *(const u32x4*)(U + ((size_t)b * TB + tokof(s, chunk * 64 + sb * 16 + l15)) * D + g * 16 + 8 * lq) : (u32x4){0u, 0u, 0u, 0u};
;         if (FINAL) { const float* e = E + ((size_t)(((s * 4 + b) * 64 + g) * 68 + chunk) * 64 + lane) * 2; e0 = e[0]; e1 = e[1]; } }
.LBB0_1558:
	s_cmp_lt_i32 s34, 16
	s_cselect_b64 s[10:11], -1, 0
	s_cmp_gt_i32 s35, 15
	s_cselect_b64 s[6:7], -1, 0
	s_and_b64 s[6:7], s[10:11], s[6:7]
	s_andn2_b64 vcc, exec, s[6:7]
	v_cmp_gt_u32_e64 s[6:7], 32, v130
	s_cbranch_vccnz .LBB0_1604
	s_lshr_b32 s3, s36, 4
	s_and_b32 s8, s3, 63
	s_lshr_b32 s9, s3, 6
	s_and_b32 s55, s36, 15
	s_cmp_lt_u32 s55, 4
	s_cselect_b32 s56, 5, 4
	v_and_b32_e32 v236, 15, v130
	v_lshrrev_b32_e32 v237, 4, v130
	s_add_u32 s42, s26, 0x100000
	s_addc_u32 s43, s27, 0
	s_add_u32 s44, s26, 0x40000
	s_addc_u32 s45, s27, 0
	s_add_u32 s20, s26, 0x3400000
	s_addc_u32 s21, s27, 0
	s_add_u32 s22, s26, 0xde00000
	s_addc_u32 s23, s27, 0
	s_lshl_b32 s15, s3, 6
	v_add_u32_e32 v216, s15, v236
	v_and_b32_e32 v217, 1, v237
	v_lshlrev_b32_e32 v217, 5, v217
	v_lshl_add_u32 v218, v216, 7, v217
	v_add_u32_e32 v219, 0x1000, v218
	global_load_dwordx4 v[56:59], v218, s[42:43] offset:0
	global_load_dwordx4 v[60:63], v218, s[42:43] offset:16
	global_load_dwordx4 v[64:67], v218, s[42:43] offset:2048
	global_load_dwordx4 v[68:71], v218, s[42:43] offset:2064
	global_load_dwordx4 v[72:75], v219, s[42:43] offset:0
	global_load_dwordx4 v[76:79], v219, s[42:43] offset:16
	global_load_dwordx4 v[80:83], v219, s[42:43] offset:2048
	global_load_dwordx4 v[84:87], v219, s[42:43] offset:2064
	global_load_dwordx4 v[88:91], v218, s[42:43] offset:64
	global_load_dwordx4 v[92:95], v218, s[42:43] offset:80
	global_load_dwordx4 v[96:99], v218, s[42:43] offset:2112
	global_load_dwordx4 v[100:103], v218, s[42:43] offset:2128
	global_load_dwordx4 v[104:107], v219, s[42:43] offset:64
	global_load_dwordx4 v[108:111], v219, s[42:43] offset:80
	global_load_dwordx4 v[112:115], v219, s[42:43] offset:2112
	global_load_dwordx4 v[116:119], v219, s[42:43] offset:2128
	v_lshlrev_b32_e32 v220, 4, v216
	global_load_dwordx2 v[32:33], v220, s[44:45] offset:0
	global_load_dwordx2 v[34:35], v220, s[44:45] offset:256
	global_load_dwordx2 v[36:37], v220, s[44:45] offset:512
	global_load_dwordx2 v[38:39], v220, s[44:45] offset:768
	s_waitcnt vmcnt(0)
	v_cmp_gt_u32_e32 vcc, 2, v237
	v_cvt_pk_bf16_f32 v0, v56, v57
	v_cvt_pk_bf16_f32 v1, v58, v59
	v_cvt_pk_bf16_f32 v2, v60, v61
	v_cvt_pk_bf16_f32 v3, v62, v63
	v_cvt_pk_bf16_f32 v4, v64, v65
	v_cvt_pk_bf16_f32 v5, v66, v67
	v_cvt_pk_bf16_f32 v6, v68, v69
	v_cvt_pk_bf16_f32 v7, v70, v71
	v_cvt_pk_bf16_f32 v8, v72, v73
	v_cvt_pk_bf16_f32 v9, v74, v75
	v_cvt_pk_bf16_f32 v10, v76, v77
	v_cvt_pk_bf16_f32 v11, v78, v79
	v_cvt_pk_bf16_f32 v12, v80, v81
	v_cvt_pk_bf16_f32 v13, v82, v83
	v_cvt_pk_bf16_f32 v14, v84, v85
	v_cvt_pk_bf16_f32 v15, v86, v87
	v_cvt_pk_bf16_f32 v16, v88, v89
	v_cvt_pk_bf16_f32 v17, v90, v91
	v_cvt_pk_bf16_f32 v18, v92, v93
	v_cvt_pk_bf16_f32 v19, v94, v95
	v_cvt_pk_bf16_f32 v20, v96, v97
	v_cvt_pk_bf16_f32 v21, v98, v99
	v_cvt_pk_bf16_f32 v22, v100, v101
	v_cvt_pk_bf16_f32 v23, v102, v103
	v_cvt_pk_bf16_f32 v24, v104, v105
	v_cvt_pk_bf16_f32 v25, v106, v107
	v_cvt_pk_bf16_f32 v26, v108, v109
	v_cvt_pk_bf16_f32 v27, v110, v111
	v_cvt_pk_bf16_f32 v28, v112, v113
	v_cvt_pk_bf16_f32 v29, v114, v115
	v_cvt_pk_bf16_f32 v30, v116, v117
	v_cvt_pk_bf16_f32 v31, v118, v119
	v_cndmask_b32_e32 v0, 0, v0, vcc
	v_cndmask_b32_e32 v1, 0, v1, vcc
	v_cndmask_b32_e32 v2, 0, v2, vcc
	v_cndmask_b32_e32 v3, 0, v3, vcc
	v_cndmask_b32_e32 v4, 0, v4, vcc
	v_cndmask_b32_e32 v5, 0, v5, vcc
	v_cndmask_b32_e32 v6, 0, v6, vcc
	v_cndmask_b32_e32 v7, 0, v7, vcc
	v_cndmask_b32_e32 v8, 0, v8, vcc
	v_cndmask_b32_e32 v9, 0, v9, vcc
	v_cndmask_b32_e32 v10, 0, v10, vcc
	v_cndmask_b32_e32 v11, 0, v11, vcc
	v_cndmask_b32_e32 v12, 0, v12, vcc
	v_cndmask_b32_e32 v13, 0, v13, vcc
	v_cndmask_b32_e32 v14, 0, v14, vcc
	v_cndmask_b32_e32 v15, 0, v15, vcc
	v_cndmask_b32_e32 v16, 0, v16, vcc
	v_cndmask_b32_e32 v17, 0, v17, vcc
	v_cndmask_b32_e32 v18, 0, v18, vcc
	v_cndmask_b32_e32 v19, 0, v19, vcc
	v_cndmask_b32_e32 v20, 0, v20, vcc
	v_cndmask_b32_e32 v21, 0, v21, vcc
	v_cndmask_b32_e32 v22, 0, v22, vcc
	v_cndmask_b32_e32 v23, 0, v23, vcc
	v_cndmask_b32_e32 v24, 0, v24, vcc
	v_cndmask_b32_e32 v25, 0, v25, vcc
	v_cndmask_b32_e32 v26, 0, v26, vcc
	v_cndmask_b32_e32 v27, 0, v27, vcc
	v_cndmask_b32_e32 v28, 0, v28, vcc
	v_cndmask_b32_e32 v29, 0, v29, vcc
	v_cndmask_b32_e32 v30, 0, v30, vcc
	v_cndmask_b32_e32 v31, 0, v31, vcc
	s_cmp_eq_u32 s9, 0
	s_mov_b32 s18, 0xffffe000
	s_cselect_b32 s18, 0x2000, s18
	v_mov_b32_e32 v243, s18
	s_mov_b32 s14, s55
	s_lshl_b32 s15, s14, 2
	v_lshrrev_b32_e32 v244, 2, v236
	v_add_u32_e32 v244, s15, v244
	v_mul_u32_u24_e32 v245, 0xf1, v244
	v_lshrrev_b32_e32 v245, 14, v245
	v_mul_u32_u24_e32 v232, 68, v245
	v_sub_u32_e32 v244, v244, v232
	v_and_b32_e32 v232, 3, v236
	v_lshl_add_u32 v232, v244, 6, v232
	v_mov_b32_e32 v233, 0x11ff
	v_mov_b32_e32 v234, 0xff
	v_cmp_gt_u32_e32 vcc, 4, v244
	s_nop 1
	v_cndmask_b32_e32 v233, v233, v234, vcc
	v_sub_u32_e32 v233, v233, v232
	s_cmp_eq_u32 s9, 0
	s_cselect_b64 vcc, -1, 0
	s_nop 1
	v_cndmask_b32_e32 v232, v233, v232, vcc
	v_mul_u32_u24_e32 v245, 0x1100, v245
	v_add_u32_e32 v232, v232, v245
	s_lshl_b32 s16, s8, 5
	v_and_b32_e32 v233, 1, v237
	v_lshl_add_u32 v233, v233, 4, s16
	v_lshl_add_u32 v238, v232, 11, v233
	global_load_dwordx4 v[56:59], v238, s[20:21]
	v_add_u32_e32 v238, v238, v243
	global_load_dwordx4 v[60:63], v238, s[20:21]
	v_add_u32_e32 v238, v238, v243
	global_load_dwordx4 v[64:67], v238, s[20:21]
	v_add_u32_e32 v238, v238, v243
	global_load_dwordx4 v[68:71], v238, s[20:21]
	v_add_u32_e32 v238, v238, v243
	global_load_dwordx4 v[72:75], v238, s[20:21]
	v_add_u32_e32 v238, v238, v243
	global_load_dwordx4 v[76:79], v238, s[20:21]
	v_add_u32_e32 v238, v238, v243
	global_load_dwordx4 v[80:83], v238, s[20:21]
	v_add_u32_e32 v238, v238, v243
	global_load_dwordx4 v[84:87], v238, s[20:21]
	v_add_u32_e32 v238, v238, v243
	global_load_dwordx4 v[88:91], v238, s[20:21]
	v_add_u32_e32 v238, v238, v243
	global_load_dwordx4 v[92:95], v238, s[20:21]
	v_add_u32_e32 v238, v238, v243
	global_load_dwordx4 v[96:99], v238, s[20:21]
	v_add_u32_e32 v238, v238, v243
	global_load_dwordx4 v[100:103], v238, s[20:21]
	v_add_u32_e32 v238, v238, v243
	global_load_dwordx4 v[104:107], v238, s[20:21]
	v_add_u32_e32 v238, v238, v243
	global_load_dwordx4 v[108:111], v238, s[20:21]
	v_add_u32_e32 v238, v238, v243
	global_load_dwordx4 v[112:115], v238, s[20:21]
	v_add_u32_e32 v238, v238, v243
	global_load_dwordx4 v[116:119], v238, s[20:21]
	v_add_u32_e32 v238, v238, v243
	s_mov_b32 s19, 0
	s_waitcnt vmcnt(0)
;     __device__ __forceinline__ bf16* R(int i) const { return (bf16*)(ws + OFF_R0 + (size_t)i * RSZ); }
; template <bool FINAL> __device__ __forceinline__ void phase_s5_scan(const Fr& F) {
;     ...
;     for (int ti = (F.gw & 15); ti < NB * 68; ti += 16) {
;         const int b = ti / 68, chunk = ti - b * 68, sbg = (s * 4 + b) * 64 + g, task = sbg * 68 + chunk;
;         float xr = FINAL ? e0 : 0.f, xi = FINAL ? e1 : 0.f;
;         bf16* Yb = F.R(4 + s);
;         u32x4 uc[4];
; #pragma unroll
;         for (int sb = 0; sb < 4; ++sb) uc[sb] = ua[sb];
;         if (ti + 16 < NB * 68) {
;             const int tn = ti + 16, bn = tn / 68, cn = tn - bn * 68;
; #pragma unroll
;             for (int sb = 0; sb < 4; ++sb) ua[sb] = lq < 2 ? *(const u32x4*)(U + ((size_t)bn * TB + tokof(s, cn * 64 + sb * 16 + l15)) * D + g * 16 + 8 * lq) : (u32x4){0u, 0u, 0u, 0u};
;             if (FINAL) { const float* e = E + ((size_t)(((s * 4 + bn) * 64 + g) * 68 + cn) * 64 + lane) * 2; e0 = e[0]; e1 = e[1]; }
;         }
; #pragma unroll
;         for (int sub = 0; sub < 4; ++sub) {
;             const bf16x8 A1 = __builtin_bit_cast(bf16x8, uc[sub]);
; #pragma unroll
;             for (int nt = 0; nt < 8; ++nt) {
;                 f32x4 acc = {0.f, 0.f, 0.f, 0.f};
;                 acc = __builtin_amdgcn_mfma_f32_16x16x32_bf16(A1, B1[nt], acc, 0, 0, 0);
; #pragma unroll
;                 for (int reg = 0; reg < 4; ++reg) BUl[(4 * lq + reg) * 132 + 16 * nt + l15] = acc[reg];
;             }
;             asm volatile("s_waitcnt lgkmcnt(0)" ::: "memory");
; #pragma unroll 4
;             for (int jj = 0; jj < 16; ++jj) {
;                 const float br_ = BUl[jj * 132 + lane], bi_ = BUl[jj * 132 + 64 + lane];
;                 const float nr = ar * xr - ai * xi + br_, ni = ar * xi + ai * xr + bi_; xr = nr; xi = ni;
.Ls5a_grp:
	s_lshl_b32 s15, s14, 2
	v_lshrrev_b32_e32 v244, 2, v236
	v_add_u32_e32 v244, s15, v244
	v_mul_u32_u24_e32 v245, 0xf1, v244
	v_lshrrev_b32_e32 v245, 14, v245
	v_mul_u32_u24_e32 v232, 68, v245
	v_sub_u32_e32 v244, v244, v232
	v_and_b32_e32 v232, 3, v236
	v_lshl_add_u32 v232, v244, 6, v232
	v_mov_b32_e32 v233, 0x11ff
	v_mov_b32_e32 v234, 0xff
	v_cmp_gt_u32_e32 vcc, 4, v244
	s_nop 1
	v_cndmask_b32_e32 v233, v233, v234, vcc
	v_sub_u32_e32 v233, v233, v232
	s_cmp_eq_u32 s9, 0
	s_cselect_b64 vcc, -1, 0
	s_nop 1
	v_cndmask_b32_e32 v232, v233, v232, vcc
	v_mul_u32_u24_e32 v245, 0x1100, v245
	v_add_u32_e32 v232, v232, v245
	s_lshl_b32 s16, s8, 5
	v_and_b32_e32 v233, 1, v237
	v_lshl_add_u32 v233, v233, 4, s16
	v_lshl_add_u32 v235, v232, 11, v233
	v_add_u32_e32 v244, s15, v237
	v_mul_u32_u24_e32 v245, 0xf1, v244
	v_lshrrev_b32_e32 v245, 14, v245
	v_mul_u32_u24_e32 v232, 68, v245
	v_sub_u32_e32 v244, v244, v232
	s_lshl_b32 s17, s9, 2
	v_add_u32_e32 v245, s17, v245
	v_lshl_add_u32 v245, v245, 6, s8
	v_mul_u32_u24_e32 v245, 68, v245
	v_add_u32_e32 v245, v245, v244
	v_lshl_add_u32 v245, v245, 6, v236
	v_lshlrev_b32_e32 v240, 3, v245
	s_add_i32 s54, s14, 16
	s_lshl_b32 s15, s54, 2
	v_lshrrev_b32_e32 v244, 2, v236
	v_add_u32_e32 v244, s15, v244
	v_mul_u32_u24_e32 v245, 0xf1, v244
	v_lshrrev_b32_e32 v245, 14, v245
	v_mul_u32_u24_e32 v232, 68, v245
	v_sub_u32_e32 v244, v244, v232
	v_and_b32_e32 v232, 3, v236
	v_lshl_add_u32 v232, v244, 6, v232
	v_mov_b32_e32 v233, 0x11ff
	v_mov_b32_e32 v234, 0xff
	v_cmp_gt_u32_e32 vcc, 4, v244
	s_nop 1
	v_cndmask_b32_e32 v233, v233, v234, vcc
	v_sub_u32_e32 v233, v233, v232
	s_cmp_eq_u32 s9, 0
	s_cselect_b64 vcc, -1, 0
	s_nop 1
	v_cndmask_b32_e32 v232, v233, v232, vcc
	v_mul_u32_u24_e32 v245, 0x1100, v245
	v_add_u32_e32 v232, v232, v245
	s_lshl_b32 s16, s8, 5
	v_and_b32_e32 v233, 1, v237
	v_lshl_add_u32 v233, v233, 4, s16
	v_lshl_add_u32 v238, v232, 11, v233
	s_waitcnt vmcnt(19)
	v_mov_b32_e32 v200, 0
	v_mov_b32_e32 v201, 0
	v_mov_b32_e32 v202, 0
	v_mov_b32_e32 v203, 0
	v_mov_b32_e32 v204, 0
	v_mov_b32_e32 v205, 0
	v_mov_b32_e32 v206, 0
	v_mov_b32_e32 v207, 0
	v_mfma_f32_16x16x32_bf16 v[136:139], v[56:59], v[0:3], 0
	v_mfma_f32_16x16x32_bf16 v[140:143], v[56:59], v[4:7], 0
	v_mfma_f32_16x16x32_bf16 v[144:147], v[56:59], v[8:11], 0
	v_mfma_f32_16x16x32_bf16 v[148:151], v[56:59], v[12:15], 0
	v_mfma_f32_16x16x32_bf16 v[152:155], v[56:59], v[16:19], 0
	v_mfma_f32_16x16x32_bf16 v[156:159], v[56:59], v[20:23], 0
	v_mfma_f32_16x16x32_bf16 v[160:163], v[56:59], v[24:27], 0
	v_mfma_f32_16x16x32_bf16 v[164:167], v[56:59], v[28:31], 0
	s_waitcnt vmcnt(18)
	v_mfma_f32_16x16x32_bf16 v[168:171], v[60:63], v[0:3], 0
	v_mfma_f32_16x16x32_bf16 v[172:175], v[60:63], v[4:7], 0
	v_mfma_f32_16x16x32_bf16 v[176:179], v[60:63], v[8:11], 0
	v_mfma_f32_16x16x32_bf16 v[180:183], v[60:63], v[12:15], 0
	v_mfma_f32_16x16x32_bf16 v[184:187], v[60:63], v[16:19], 0
	v_mfma_f32_16x16x32_bf16 v[188:191], v[60:63], v[20:23], 0
	v_mfma_f32_16x16x32_bf16 v[192:195], v[60:63], v[24:27], 0
	v_mfma_f32_16x16x32_bf16 v[196:199], v[60:63], v[28:31], 0
	v_pk_mov_b32 v[232:233], v[136:137], v[152:153] op_sel:[0,0]
	v_pk_mov_b32 v[234:235], v[140:141], v[156:157] op_sel:[0,0]
	v_pk_mov_b32 v[244:245], v[144:145], v[160:161] op_sel:[0,0]
	v_pk_mov_b32 v[254:255], v[148:149], v[164:165] op_sel:[0,0]
	v_pk_fma_f32 v[232:233], v[32:33], v[200:201], v[232:233] op_sel_hi:[0,1,1]
	v_pk_fma_f32 v[234:235], v[34:35], v[202:203], v[234:235] op_sel_hi:[0,1,1]
	v_pk_fma_f32 v[244:245], v[36:37], v[204:205], v[244:245] op_sel_hi:[0,1,1]
	v_pk_fma_f32 v[254:255], v[38:39], v[206:207], v[254:255] op_sel_hi:[0,1,1]
	v_pk_fma_f32 v[200:201], v[32:33], v[200:201], v[232:233] op_sel:[1,1,0] op_sel_hi:[1,0,1] neg_lo:[1,0,0]
	v_pk_fma_f32 v[202:203], v[34:35], v[202:203], v[234:235] op_sel:[1,1,0] op_sel_hi:[1,0,1] neg_lo:[1,0,0]
	v_pk_fma_f32 v[204:205], v[36:37], v[204:205], v[244:245] op_sel:[1,1,0] op_sel_hi:[1,0,1] neg_lo:[1,0,0]
	v_pk_fma_f32 v[206:207], v[38:39], v[206:207], v[254:255] op_sel:[1,1,0] op_sel_hi:[1,0,1] neg_lo:[1,0,0]
	v_pk_mov_b32 v[232:233], v[136:137], v[152:153] op_sel:[1,1]
	v_pk_mov_b32 v[234:235], v[140:141], v[156:157] op_sel:[1,1]
	v_pk_mov_b32 v[244:245], v[144:145], v[160:161] op_sel:[1,1]
	v_pk_mov_b32 v[254:255], v[148:149], v[164:165] op_sel:[1,1]
	v_pk_fma_f32 v[232:233], v[32:33], v[200:201], v[232:233] op_sel_hi:[0,1,1]
	v_pk_fma_f32 v[234:235], v[34:35], v[202:203], v[234:235] op_sel_hi:[0,1,1]
	v_pk_fma_f32 v[244:245], v[36:37], v[204:205], v[244:245] op_sel_hi:[0,1,1]
	v_pk_fma_f32 v[254:255], v[38:39], v[206:207], v[254:255] op_sel_hi:[0,1,1]
	v_pk_fma_f32 v[200:201], v[32:33], v[200:201], v[232:233] op_sel:[1,1,0] op_sel_hi:[1,0,1] neg_lo:[1,0,0]
	v_pk_fma_f32 v[202:203], v[34:35], v[202:203], v[234:235] op_sel:[1,1,0] op_sel_hi:[1,0,1] neg_lo:[1,0,0]
	v_pk_fma_f32 v[204:205], v[36:37], v[204:205], v[244:245] op_sel:[1,1,0] op_sel_hi:[1,0,1] neg_lo:[1,0,0]
	v_pk_fma_f32 v[206:207], v[38:39], v[206:207], v[254:255] op_sel:[1,1,0] op_sel_hi:[1,0,1] neg_lo:[1,0,0]
	v_pk_mov_b32 v[232:233], v[138:139], v[154:155] op_sel:[0,0]
	v_pk_mov_b32 v[234:235], v[142:143], v[158:159] op_sel:[0,0]
	v_pk_mov_b32 v[244:245], v[146:147], v[162:163] op_sel:[0,0]
	v_pk_mov_b32 v[254:255], v[150:151], v[166:167] op_sel:[0,0]
	v_pk_fma_f32 v[232:233], v[32:33], v[200:201], v[232:233] op_sel_hi:[0,1,1]
	v_pk_fma_f32 v[234:235], v[34:35], v[202:203], v[234:235] op_sel_hi:[0,1,1]
	v_pk_fma_f32 v[244:245], v[36:37], v[204:205], v[244:245] op_sel_hi:[0,1,1]
	v_pk_fma_f32 v[254:255], v[38:39], v[206:207], v[254:255] op_sel_hi:[0,1,1]
; template <bool FINAL> __device__ __forceinline__ void phase_s5_scan(const Fr& F) {
;     ...
; #pragma unroll
;         for (int sub = 0; sub < 4; ++sub) {
;             const bf16x8 A1 = __builtin_bit_cast(bf16x8, uc[sub]);
; #pragma unroll
;             for (int nt = 0; nt < 8; ++nt) {
;                 f32x4 acc = {0.f, 0.f, 0.f, 0.f};
;                 acc = __builtin_amdgcn_mfma_f32_16x16x32_bf16(A1, B1[nt], acc, 0, 0, 0);
; #pragma unroll
;                 for (int reg = 0; reg < 4; ++reg) BUl[(4 * lq + reg) * 132 + 16 * nt + l15] = acc[reg];
;             }
;             asm volatile("s_waitcnt lgkmcnt(0)" ::: "memory");
; #pragma unroll 4
;             for (int jj = 0; jj < 16; ++jj) {
;                 const float br_ = BUl[jj * 132 + lane], bi_ = BUl[jj * 132 + 64 + lane];
;                 const float nr = ar * xr - ai * xi + br_, ni = ar * xi + ai * xr + bi_; xr = nr; xi = ni;
	v_pk_fma_f32 v[200:201], v[32:33], v[200:201], v[232:233] op_sel:[1,1,0] op_sel_hi:[1,0,1] neg_lo:[1,0,0]
	v_pk_fma_f32 v[202:203], v[34:35], v[202:203], v[234:235] op_sel:[1,1,0] op_sel_hi:[1,0,1] neg_lo:[1,0,0]
	v_pk_fma_f32 v[204:205], v[36:37], v[204:205], v[244:245] op_sel:[1,1,0] op_sel_hi:[1,0,1] neg_lo:[1,0,0]
	v_pk_fma_f32 v[206:207], v[38:39], v[206:207], v[254:255] op_sel:[1,1,0] op_sel_hi:[1,0,1] neg_lo:[1,0,0]
	v_pk_mov_b32 v[232:233], v[138:139], v[154:155] op_sel:[1,1]
	v_pk_mov_b32 v[234:235], v[142:143], v[158:159] op_sel:[1,1]
	v_pk_mov_b32 v[244:245], v[146:147], v[162:163] op_sel:[1,1]
	v_pk_mov_b32 v[254:255], v[150:151], v[166:167] op_sel:[1,1]
	v_pk_fma_f32 v[232:233], v[32:33], v[200:201], v[232:233] op_sel_hi:[0,1,1]
	v_pk_fma_f32 v[234:235], v[34:35], v[202:203], v[234:235] op_sel_hi:[0,1,1]
	v_pk_fma_f32 v[244:245], v[36:37], v[204:205], v[244:245] op_sel_hi:[0,1,1]
	v_pk_fma_f32 v[254:255], v[38:39], v[206:207], v[254:255] op_sel_hi:[0,1,1]
	v_pk_fma_f32 v[200:201], v[32:33], v[200:201], v[232:233] op_sel:[1,1,0] op_sel_hi:[1,0,1] neg_lo:[1,0,0]
	v_pk_fma_f32 v[202:203], v[34:35], v[202:203], v[234:235] op_sel:[1,1,0] op_sel_hi:[1,0,1] neg_lo:[1,0,0]
	v_pk_fma_f32 v[204:205], v[36:37], v[204:205], v[244:245] op_sel:[1,1,0] op_sel_hi:[1,0,1] neg_lo:[1,0,0]
	v_pk_fma_f32 v[206:207], v[38:39], v[206:207], v[254:255] op_sel:[1,1,0] op_sel_hi:[1,0,1] neg_lo:[1,0,0]
	global_load_dwordx4 v[56:59], v238, s[20:21]
	v_add_u32_e32 v238, v238, v243
	s_waitcnt vmcnt(18)
	v_mfma_f32_16x16x32_bf16 v[136:139], v[64:67], v[0:3], 0
	v_mfma_f32_16x16x32_bf16 v[140:143], v[64:67], v[4:7], 0
	v_mfma_f32_16x16x32_bf16 v[144:147], v[64:67], v[8:11], 0
	v_mfma_f32_16x16x32_bf16 v[148:151], v[64:67], v[12:15], 0
	v_mfma_f32_16x16x32_bf16 v[152:155], v[64:67], v[16:19], 0
	v_mfma_f32_16x16x32_bf16 v[156:159], v[64:67], v[20:23], 0
	v_mfma_f32_16x16x32_bf16 v[160:163], v[64:67], v[24:27], 0
	v_mfma_f32_16x16x32_bf16 v[164:167], v[64:67], v[28:31], 0
	v_pk_mov_b32 v[232:233], v[168:169], v[184:185] op_sel:[0,0]
	v_pk_mov_b32 v[234:235], v[172:173], v[188:189] op_sel:[0,0]
	v_pk_mov_b32 v[244:245], v[176:177], v[192:193] op_sel:[0,0]
	v_pk_mov_b32 v[254:255], v[180:181], v[196:197] op_sel:[0,0]
	v_pk_fma_f32 v[232:233], v[32:33], v[200:201], v[232:233] op_sel_hi:[0,1,1]
	v_pk_fma_f32 v[234:235], v[34:35], v[202:203], v[234:235] op_sel_hi:[0,1,1]
	v_pk_fma_f32 v[244:245], v[36:37], v[204:205], v[244:245] op_sel_hi:[0,1,1]
	v_pk_fma_f32 v[254:255], v[38:39], v[206:207], v[254:255] op_sel_hi:[0,1,1]
	v_pk_fma_f32 v[200:201], v[32:33], v[200:201], v[232:233] op_sel:[1,1,0] op_sel_hi:[1,0,1] neg_lo:[1,0,0]
	v_pk_fma_f32 v[202:203], v[34:35], v[202:203], v[234:235] op_sel:[1,1,0] op_sel_hi:[1,0,1] neg_lo:[1,0,0]
	v_pk_fma_f32 v[204:205], v[36:37], v[204:205], v[244:245] op_sel:[1,1,0] op_sel_hi:[1,0,1] neg_lo:[1,0,0]
	v_pk_fma_f32 v[206:207], v[38:39], v[206:207], v[254:255] op_sel:[1,1,0] op_sel_hi:[1,0,1] neg_lo:[1,0,0]
	v_pk_mov_b32 v[232:233], v[168:169], v[184:185] op_sel:[1,1]
	v_pk_mov_b32 v[234:235], v[172:173], v[188:189] op_sel:[1,1]
	v_pk_mov_b32 v[244:245], v[176:177], v[192:193] op_sel:[1,1]
	v_pk_mov_b32 v[254:255], v[180:181], v[196:197] op_sel:[1,1]
	v_pk_fma_f32 v[232:233], v[32:33], v[200:201], v[232:233] op_sel_hi:[0,1,1]
	v_pk_fma_f32 v[234:235], v[34:35], v[202:203], v[234:235] op_sel_hi:[0,1,1]
	v_pk_fma_f32 v[244:245], v[36:37], v[204:205], v[244:245] op_sel_hi:[0,1,1]
	v_pk_fma_f32 v[254:255], v[38:39], v[206:207], v[254:255] op_sel_hi:[0,1,1]
	v_pk_fma_f32 v[200:201], v[32:33], v[200:201], v[232:233] op_sel:[1,1,0] op_sel_hi:[1,0,1] neg_lo:[1,0,0]
	v_pk_fma_f32 v[202:203], v[34:35], v[202:203], v[234:235] op_sel:[1,1,0] op_sel_hi:[1,0,1] neg_lo:[1,0,0]
	v_pk_fma_f32 v[204:205], v[36:37], v[204:205], v[244:245] op_sel:[1,1,0] op_sel_hi:[1,0,1] neg_lo:[1,0,0]
	v_pk_fma_f32 v[206:207], v[38:39], v[206:207], v[254:255] op_sel:[1,1,0] op_sel_hi:[1,0,1] neg_lo:[1,0,0]
	v_pk_mov_b32 v[232:233], v[170:171], v[186:187] op_sel:[0,0]
	v_pk_mov_b32 v[234:235], v[174:175], v[190:191] op_sel:[0,0]
	v_pk_mov_b32 v[244:245], v[178:179], v[194:195] op_sel:[0,0]
	v_pk_mov_b32 v[254:255], v[182:183], v[198:199] op_sel:[0,0]
	v_pk_fma_f32 v[232:233], v[32:33], v[200:201], v[232:233] op_sel_hi:[0,1,1]
	v_pk_fma_f32 v[234:235], v[34:35], v[202:203], v[234:235] op_sel_hi:[0,1,1]
	v_pk_fma_f32 v[244:245], v[36:37], v[204:205], v[244:245] op_sel_hi:[0,1,1]
	v_pk_fma_f32 v[254:255], v[38:39], v[206:207], v[254:255] op_sel_hi:[0,1,1]
	v_pk_fma_f32 v[200:201], v[32:33], v[200:201], v[232:233] op_sel:[1,1,0] op_sel_hi:[1,0,1] neg_lo:[1,0,0]
	v_pk_fma_f32 v[202:203], v[34:35], v[202:203], v[234:235] op_sel:[1,1,0] op_sel_hi:[1,0,1] neg_lo:[1,0,0]
	v_pk_fma_f32 v[204:205], v[36:37], v[204:205], v[244:245] op_sel:[1,1,0] op_sel_hi:[1,0,1] neg_lo:[1,0,0]
	v_pk_fma_f32 v[206:207], v[38:39], v[206:207], v[254:255] op_sel:[1,1,0] op_sel_hi:[1,0,1] neg_lo:[1,0,0]
	v_pk_mov_b32 v[232:233], v[170:171], v[186:187] op_sel:[1,1]
	v_pk_mov_b32 v[234:235], v[174:175], v[190:191] op_sel:[1,1]
	v_pk_mov_b32 v[244:245], v[178:179], v[194:195] op_sel:[1,1]
	v_pk_mov_b32 v[254:255], v[182:183], v[198:199] op_sel:[1,1]
	v_pk_fma_f32 v[232:233], v[32:33], v[200:201], v[232:233] op_sel_hi:[0,1,1]
	v_pk_fma_f32 v[234:235], v[34:35], v[202:203], v[234:235] op_sel_hi:[0,1,1]
	v_pk_fma_f32 v[244:245], v[36:37], v[204:205], v[244:245] op_sel_hi:[0,1,1]
	v_pk_fma_f32 v[254:255], v[38:39], v[206:207], v[254:255] op_sel_hi:[0,1,1]
	v_pk_fma_f32 v[200:201], v[32:33], v[200:201], v[232:233] op_sel:[1,1,0] op_sel_hi:[1,0,1] neg_lo:[1,0,0]
	v_pk_fma_f32 v[202:203], v[34:35], v[202:203], v[234:235] op_sel:[1,1,0] op_sel_hi:[1,0,1] neg_lo:[1,0,0]
	v_pk_fma_f32 v[204:205], v[36:37], v[204:205], v[244:245] op_sel:[1,1,0] op_sel_hi:[1,0,1] neg_lo:[1,0,0]
	v_pk_fma_f32 v[206:207], v[38:39], v[206:207], v[254:255] op_sel:[1,1,0] op_sel_hi:[1,0,1] neg_lo:[1,0,0]
	global_load_dwordx4 v[60:63], v238, s[20:21]
	v_add_u32_e32 v238, v238, v243
	s_waitcnt vmcnt(18)
; template <bool FINAL> __device__ __forceinline__ void phase_s5_scan(const Fr& F) {
;     ...
; #pragma unroll
;         for (int sub = 0; sub < 4; ++sub) {
;             const bf16x8 A1 = __builtin_bit_cast(bf16x8, uc[sub]);
; #pragma unroll
;             for (int nt = 0; nt < 8; ++nt) {
;                 f32x4 acc = {0.f, 0.f, 0.f, 0.f};
;                 acc = __builtin_amdgcn_mfma_f32_16x16x32_bf16(A1, B1[nt], acc, 0, 0, 0);
; #pragma unroll
;                 for (int reg = 0; reg < 4; ++reg) BUl[(4 * lq + reg) * 132 + 16 * nt + l15] = acc[reg];
;             }
;             asm volatile("s_waitcnt lgkmcnt(0)" ::: "memory");
; #pragma unroll 4
;             for (int jj = 0; jj < 16; ++jj) {
;                 const float br_ = BUl[jj * 132 + lane], bi_ = BUl[jj * 132 + 64 + lane];
;                 const float nr = ar * xr - ai * xi + br_, ni = ar * xi + ai * xr + bi_; xr = nr; xi = ni;
	v_mfma_f32_16x16x32_bf16 v[168:171], v[68:71], v[0:3], 0
	v_mfma_f32_16x16x32_bf16 v[172:175], v[68:71], v[4:7], 0
	v_mfma_f32_16x16x32_bf16 v[176:179], v[68:71], v[8:11], 0
	v_mfma_f32_16x16x32_bf16 v[180:183], v[68:71], v[12:15], 0
	v_mfma_f32_16x16x32_bf16 v[184:187], v[68:71], v[16:19], 0
	v_mfma_f32_16x16x32_bf16 v[188:191], v[68:71], v[20:23], 0
	v_mfma_f32_16x16x32_bf16 v[192:195], v[68:71], v[24:27], 0
	v_mfma_f32_16x16x32_bf16 v[196:199], v[68:71], v[28:31], 0
	v_pk_mov_b32 v[232:233], v[136:137], v[152:153] op_sel:[0,0]
	v_pk_mov_b32 v[234:235], v[140:141], v[156:157] op_sel:[0,0]
	v_pk_mov_b32 v[244:245], v[144:145], v[160:161] op_sel:[0,0]
	v_pk_mov_b32 v[254:255], v[148:149], v[164:165] op_sel:[0,0]
	v_pk_fma_f32 v[232:233], v[32:33], v[200:201], v[232:233] op_sel_hi:[0,1,1]
	v_pk_fma_f32 v[234:235], v[34:35], v[202:203], v[234:235] op_sel_hi:[0,1,1]
	v_pk_fma_f32 v[244:245], v[36:37], v[204:205], v[244:245] op_sel_hi:[0,1,1]
	v_pk_fma_f32 v[254:255], v[38:39], v[206:207], v[254:255] op_sel_hi:[0,1,1]
	v_pk_fma_f32 v[200:201], v[32:33], v[200:201], v[232:233] op_sel:[1,1,0] op_sel_hi:[1,0,1] neg_lo:[1,0,0]
	v_pk_fma_f32 v[202:203], v[34:35], v[202:203], v[234:235] op_sel:[1,1,0] op_sel_hi:[1,0,1] neg_lo:[1,0,0]
	v_pk_fma_f32 v[204:205], v[36:37], v[204:205], v[244:245] op_sel:[1,1,0] op_sel_hi:[1,0,1] neg_lo:[1,0,0]
	v_pk_fma_f32 v[206:207], v[38:39], v[206:207], v[254:255] op_sel:[1,1,0] op_sel_hi:[1,0,1] neg_lo:[1,0,0]
	v_pk_mov_b32 v[232:233], v[136:137], v[152:153] op_sel:[1,1]
	v_pk_mov_b32 v[234:235], v[140:141], v[156:157] op_sel:[1,1]
	v_pk_mov_b32 v[244:245], v[144:145], v[160:161] op_sel:[1,1]
	v_pk_mov_b32 v[254:255], v[148:149], v[164:165] op_sel:[1,1]
	v_pk_fma_f32 v[232:233], v[32:33], v[200:201], v[232:233] op_sel_hi:[0,1,1]
	v_pk_fma_f32 v[234:235], v[34:35], v[202:203], v[234:235] op_sel_hi:[0,1,1]
	v_pk_fma_f32 v[244:245], v[36:37], v[204:205], v[244:245] op_sel_hi:[0,1,1]
	v_pk_fma_f32 v[254:255], v[38:39], v[206:207], v[254:255] op_sel_hi:[0,1,1]
	v_pk_fma_f32 v[200:201], v[32:33], v[200:201], v[232:233] op_sel:[1,1,0] op_sel_hi:[1,0,1] neg_lo:[1,0,0]
	v_pk_fma_f32 v[202:203], v[34:35], v[202:203], v[234:235] op_sel:[1,1,0] op_sel_hi:[1,0,1] neg_lo:[1,0,0]
	v_pk_fma_f32 v[204:205], v[36:37], v[204:205], v[244:245] op_sel:[1,1,0] op_sel_hi:[1,0,1] neg_lo:[1,0,0]
	v_pk_fma_f32 v[206:207], v[38:39], v[206:207], v[254:255] op_sel:[1,1,0] op_sel_hi:[1,0,1] neg_lo:[1,0,0]
	v_pk_mov_b32 v[232:233], v[138:139], v[154:155] op_sel:[0,0]
	v_pk_mov_b32 v[234:235], v[142:143], v[158:159] op_sel:[0,0]
	v_pk_mov_b32 v[244:245], v[146:147], v[162:163] op_sel:[0,0]
	v_pk_mov_b32 v[254:255], v[150:151], v[166:167] op_sel:[0,0]
	v_pk_fma_f32 v[232:233], v[32:33], v[200:201], v[232:233] op_sel_hi:[0,1,1]
	v_pk_fma_f32 v[234:235], v[34:35], v[202:203], v[234:235] op_sel_hi:[0,1,1]
	v_pk_fma_f32 v[244:245], v[36:37], v[204:205], v[244:245] op_sel_hi:[0,1,1]
	v_pk_fma_f32 v[254:255], v[38:39], v[206:207], v[254:255] op_sel_hi:[0,1,1]
	v_pk_fma_f32 v[200:201], v[32:33], v[200:201], v[232:233] op_sel:[1,1,0] op_sel_hi:[1,0,1] neg_lo:[1,0,0]
	v_pk_fma_f32 v[202:203], v[34:35], v[202:203], v[234:235] op_sel:[1,1,0] op_sel_hi:[1,0,1] neg_lo:[1,0,0]
	v_pk_fma_f32 v[204:205], v[36:37], v[204:205], v[244:245] op_sel:[1,1,0] op_sel_hi:[1,0,1] neg_lo:[1,0,0]
	v_pk_fma_f32 v[206:207], v[38:39], v[206:207], v[254:255] op_sel:[1,1,0] op_sel_hi:[1,0,1] neg_lo:[1,0,0]
	v_pk_mov_b32 v[232:233], v[138:139], v[154:155] op_sel:[1,1]
	v_pk_mov_b32 v[234:235], v[142:143], v[158:159] op_sel:[1,1]
	v_pk_mov_b32 v[244:245], v[146:147], v[162:163] op_sel:[1,1]
	v_pk_mov_b32 v[254:255], v[150:151], v[166:167] op_sel:[1,1]
	v_pk_fma_f32 v[232:233], v[32:33], v[200:201], v[232:233] op_sel_hi:[0,1,1]
	v_pk_fma_f32 v[234:235], v[34:35], v[202:203], v[234:235] op_sel_hi:[0,1,1]
	v_pk_fma_f32 v[244:245], v[36:37], v[204:205], v[244:245] op_sel_hi:[0,1,1]
	v_pk_fma_f32 v[254:255], v[38:39], v[206:207], v[254:255] op_sel_hi:[0,1,1]
	v_pk_fma_f32 v[200:201], v[32:33], v[200:201], v[232:233] op_sel:[1,1,0] op_sel_hi:[1,0,1] neg_lo:[1,0,0]
	v_pk_fma_f32 v[202:203], v[34:35], v[202:203], v[234:235] op_sel:[1,1,0] op_sel_hi:[1,0,1] neg_lo:[1,0,0]
	v_pk_fma_f32 v[204:205], v[36:37], v[204:205], v[244:245] op_sel:[1,1,0] op_sel_hi:[1,0,1] neg_lo:[1,0,0]
	v_pk_fma_f32 v[206:207], v[38:39], v[206:207], v[254:255] op_sel:[1,1,0] op_sel_hi:[1,0,1] neg_lo:[1,0,0]
	global_load_dwordx4 v[64:67], v238, s[20:21]
	v_add_u32_e32 v238, v238, v243
	s_waitcnt vmcnt(18)
; template <bool FINAL> __device__ __forceinline__ void phase_s5_scan(const Fr& F) {
;     ...
; #pragma unroll
;         for (int sub = 0; sub < 4; ++sub) {
;             const bf16x8 A1 = __builtin_bit_cast(bf16x8, uc[sub]);
; #pragma unroll
;             for (int nt = 0; nt < 8; ++nt) {
;                 f32x4 acc = {0.f, 0.f, 0.f, 0.f};
;                 acc = __builtin_amdgcn_mfma_f32_16x16x32_bf16(A1, B1[nt], acc, 0, 0, 0);
; #pragma unroll
;                 for (int reg = 0; reg < 4; ++reg) BUl[(4 * lq + reg) * 132 + 16 * nt + l15] = acc[reg];
;             }
;             asm volatile("s_waitcnt lgkmcnt(0)" ::: "memory");
; #pragma unroll 4
;             for (int jj = 0; jj < 16; ++jj) {
;                 const float br_ = BUl[jj * 132 + lane], bi_ = BUl[jj * 132 + 64 + lane];
;                 const float nr = ar * xr - ai * xi + br_, ni = ar * xi + ai * xr + bi_; xr = nr; xi = ni;
	v_mfma_f32_16x16x32_bf16 v[136:139], v[72:75], v[0:3], 0
	v_mfma_f32_16x16x32_bf16 v[140:143], v[72:75], v[4:7], 0
	v_mfma_f32_16x16x32_bf16 v[144:147], v[72:75], v[8:11], 0
	v_mfma_f32_16x16x32_bf16 v[148:151], v[72:75], v[12:15], 0
	v_mfma_f32_16x16x32_bf16 v[152:155], v[72:75], v[16:19], 0
	v_mfma_f32_16x16x32_bf16 v[156:159], v[72:75], v[20:23], 0
	v_mfma_f32_16x16x32_bf16 v[160:163], v[72:75], v[24:27], 0
	v_mfma_f32_16x16x32_bf16 v[164:167], v[72:75], v[28:31], 0
	v_pk_mov_b32 v[232:233], v[168:169], v[184:185] op_sel:[0,0]
	v_pk_mov_b32 v[234:235], v[172:173], v[188:189] op_sel:[0,0]
	v_pk_mov_b32 v[244:245], v[176:177], v[192:193] op_sel:[0,0]
	v_pk_mov_b32 v[254:255], v[180:181], v[196:197] op_sel:[0,0]
	v_pk_fma_f32 v[232:233], v[32:33], v[200:201], v[232:233] op_sel_hi:[0,1,1]
	v_pk_fma_f32 v[234:235], v[34:35], v[202:203], v[234:235] op_sel_hi:[0,1,1]
	v_pk_fma_f32 v[244:245], v[36:37], v[204:205], v[244:245] op_sel_hi:[0,1,1]
	v_pk_fma_f32 v[254:255], v[38:39], v[206:207], v[254:255] op_sel_hi:[0,1,1]
	v_pk_fma_f32 v[200:201], v[32:33], v[200:201], v[232:233] op_sel:[1,1,0] op_sel_hi:[1,0,1] neg_lo:[1,0,0]
	v_pk_fma_f32 v[202:203], v[34:35], v[202:203], v[234:235] op_sel:[1,1,0] op_sel_hi:[1,0,1] neg_lo:[1,0,0]
	v_pk_fma_f32 v[204:205], v[36:37], v[204:205], v[244:245] op_sel:[1,1,0] op_sel_hi:[1,0,1] neg_lo:[1,0,0]
	v_pk_fma_f32 v[206:207], v[38:39], v[206:207], v[254:255] op_sel:[1,1,0] op_sel_hi:[1,0,1] neg_lo:[1,0,0]
	v_pk_mov_b32 v[232:233], v[168:169], v[184:185] op_sel:[1,1]
	v_pk_mov_b32 v[234:235], v[172:173], v[188:189] op_sel:[1,1]
	v_pk_mov_b32 v[244:245], v[176:177], v[192:193] op_sel:[1,1]
	v_pk_mov_b32 v[254:255], v[180:181], v[196:197] op_sel:[1,1]
	v_pk_fma_f32 v[232:233], v[32:33], v[200:201], v[232:233] op_sel_hi:[0,1,1]
	v_pk_fma_f32 v[234:235], v[34:35], v[202:203], v[234:235] op_sel_hi:[0,1,1]
	v_pk_fma_f32 v[244:245], v[36:37], v[204:205], v[244:245] op_sel_hi:[0,1,1]
	v_pk_fma_f32 v[254:255], v[38:39], v[206:207], v[254:255] op_sel_hi:[0,1,1]
	v_pk_fma_f32 v[200:201], v[32:33], v[200:201], v[232:233] op_sel:[1,1,0] op_sel_hi:[1,0,1] neg_lo:[1,0,0]
	v_pk_fma_f32 v[202:203], v[34:35], v[202:203], v[234:235] op_sel:[1,1,0] op_sel_hi:[1,0,1] neg_lo:[1,0,0]
	v_pk_fma_f32 v[204:205], v[36:37], v[204:205], v[244:245] op_sel:[1,1,0] op_sel_hi:[1,0,1] neg_lo:[1,0,0]
	v_pk_fma_f32 v[206:207], v[38:39], v[206:207], v[254:255] op_sel:[1,1,0] op_sel_hi:[1,0,1] neg_lo:[1,0,0]
	v_pk_mov_b32 v[232:233], v[170:171], v[186:187] op_sel:[0,0]
	v_pk_mov_b32 v[234:235], v[174:175], v[190:191] op_sel:[0,0]
	v_pk_mov_b32 v[244:245], v[178:179], v[194:195] op_sel:[0,0]
	v_pk_mov_b32 v[254:255], v[182:183], v[198:199] op_sel:[0,0]
	v_pk_fma_f32 v[232:233], v[32:33], v[200:201], v[232:233] op_sel_hi:[0,1,1]
	v_pk_fma_f32 v[234:235], v[34:35], v[202:203], v[234:235] op_sel_hi:[0,1,1]
	v_pk_fma_f32 v[244:245], v[36:37], v[204:205], v[244:245] op_sel_hi:[0,1,1]
	v_pk_fma_f32 v[254:255], v[38:39], v[206:207], v[254:255] op_sel_hi:[0,1,1]
	v_pk_fma_f32 v[200:201], v[32:33], v[200:201], v[232:233] op_sel:[1,1,0] op_sel_hi:[1,0,1] neg_lo:[1,0,0]
	v_pk_fma_f32 v[202:203], v[34:35], v[202:203], v[234:235] op_sel:[1,1,0] op_sel_hi:[1,0,1] neg_lo:[1,0,0]
	v_pk_fma_f32 v[204:205], v[36:37], v[204:205], v[244:245] op_sel:[1,1,0] op_sel_hi:[1,0,1] neg_lo:[1,0,0]
	v_pk_fma_f32 v[206:207], v[38:39], v[206:207], v[254:255] op_sel:[1,1,0] op_sel_hi:[1,0,1] neg_lo:[1,0,0]
	v_pk_mov_b32 v[232:233], v[170:171], v[186:187] op_sel:[1,1]
	v_pk_mov_b32 v[234:235], v[174:175], v[190:191] op_sel:[1,1]
	v_pk_mov_b32 v[244:245], v[178:179], v[194:195] op_sel:[1,1]
	v_pk_mov_b32 v[254:255], v[182:183], v[198:199] op_sel:[1,1]
	v_pk_fma_f32 v[232:233], v[32:33], v[200:201], v[232:233] op_sel_hi:[0,1,1]
	v_pk_fma_f32 v[234:235], v[34:35], v[202:203], v[234:235] op_sel_hi:[0,1,1]
	v_pk_fma_f32 v[244:245], v[36:37], v[204:205], v[244:245] op_sel_hi:[0,1,1]
	v_pk_fma_f32 v[254:255], v[38:39], v[206:207], v[254:255] op_sel_hi:[0,1,1]
	v_pk_fma_f32 v[200:201], v[32:33], v[200:201], v[232:233] op_sel:[1,1,0] op_sel_hi:[1,0,1] neg_lo:[1,0,0]
	v_pk_fma_f32 v[202:203], v[34:35], v[202:203], v[234:235] op_sel:[1,1,0] op_sel_hi:[1,0,1] neg_lo:[1,0,0]
	v_pk_fma_f32 v[204:205], v[36:37], v[204:205], v[244:245] op_sel:[1,1,0] op_sel_hi:[1,0,1] neg_lo:[1,0,0]
	v_pk_fma_f32 v[206:207], v[38:39], v[206:207], v[254:255] op_sel:[1,1,0] op_sel_hi:[1,0,1] neg_lo:[1,0,0]
	global_load_dwordx4 v[68:71], v238, s[20:21]
	v_add_u32_e32 v238, v238, v243
	s_waitcnt vmcnt(18)
; template <bool FINAL> __device__ __forceinline__ void phase_s5_scan(const Fr& F) {
;     ...
;             for (int sb = 0; sb < 4; ++sb) ua[sb] = lq < 2 ? *(const u32x4*)(U + ((size_t)bn * TB + tokof(s, cn * 64 + sb * 16 + l15)) * D + g * 16 + 8 * lq) : (u32x4){0u, 0u, 0u, 0u};
;             if (FINAL) { const float* e = E + ((size_t)(((s * 4 + bn) * 64 + g) * 68 + cn) * 64 + lane) * 2; e0 = e[0]; e1 = e[1]; }
;         }
; #pragma unroll
;         for (int sub = 0; sub < 4; ++sub) {
;             const bf16x8 A1 = __builtin_bit_cast(bf16x8, uc[sub]);
; #pragma unroll
;             for (int nt = 0; nt < 8; ++nt) {
;                 f32x4 acc = {0.f, 0.f, 0.f, 0.f};
;                 acc = __builtin_amdgcn_mfma_f32_16x16x32_bf16(A1, B1[nt], acc, 0, 0, 0);
; #pragma unroll
;                 for (int reg = 0; reg < 4; ++reg) BUl[(4 * lq + reg) * 132 + 16 * nt + l15] = acc[reg];
;             }
;             asm volatile("s_waitcnt lgkmcnt(0)" ::: "memory");
; #pragma unroll 4
;             for (int jj = 0; jj < 16; ++jj) {
;                 const float br_ = BUl[jj * 132 + lane], bi_ = BUl[jj * 132 + 64 + lane];
;                 const float nr = ar * xr - ai * xi + br_, ni = ar * xi + ai * xr + bi_; xr = nr; xi = ni;
;                 if (FINAL) { BUl[jj * 132 + lane] = xr; BUl[jj * 132 + 64 + lane] = xi; }
;             }
	v_mfma_f32_16x16x32_bf16 v[168:171], v[76:79], v[0:3], 0
	v_mfma_f32_16x16x32_bf16 v[172:175], v[76:79], v[4:7], 0
	v_mfma_f32_16x16x32_bf16 v[176:179], v[76:79], v[8:11], 0
	v_mfma_f32_16x16x32_bf16 v[180:183], v[76:79], v[12:15], 0
	v_mfma_f32_16x16x32_bf16 v[184:187], v[76:79], v[16:19], 0
	v_mfma_f32_16x16x32_bf16 v[188:191], v[76:79], v[20:23], 0
	v_mfma_f32_16x16x32_bf16 v[192:195], v[76:79], v[24:27], 0
	v_mfma_f32_16x16x32_bf16 v[196:199], v[76:79], v[28:31], 0
	v_pk_mov_b32 v[232:233], v[136:137], v[152:153] op_sel:[0,0]
	v_pk_mov_b32 v[234:235], v[140:141], v[156:157] op_sel:[0,0]
	v_pk_mov_b32 v[244:245], v[144:145], v[160:161] op_sel:[0,0]
	v_pk_mov_b32 v[254:255], v[148:149], v[164:165] op_sel:[0,0]
	v_pk_fma_f32 v[232:233], v[32:33], v[200:201], v[232:233] op_sel_hi:[0,1,1]
	v_pk_fma_f32 v[234:235], v[34:35], v[202:203], v[234:235] op_sel_hi:[0,1,1]
	v_pk_fma_f32 v[244:245], v[36:37], v[204:205], v[244:245] op_sel_hi:[0,1,1]
	v_pk_fma_f32 v[254:255], v[38:39], v[206:207], v[254:255] op_sel_hi:[0,1,1]
	v_pk_fma_f32 v[200:201], v[32:33], v[200:201], v[232:233] op_sel:[1,1,0] op_sel_hi:[1,0,1] neg_lo:[1,0,0]
	v_pk_fma_f32 v[202:203], v[34:35], v[202:203], v[234:235] op_sel:[1,1,0] op_sel_hi:[1,0,1] neg_lo:[1,0,0]
	v_pk_fma_f32 v[204:205], v[36:37], v[204:205], v[244:245] op_sel:[1,1,0] op_sel_hi:[1,0,1] neg_lo:[1,0,0]
	v_pk_fma_f32 v[206:207], v[38:39], v[206:207], v[254:255] op_sel:[1,1,0] op_sel_hi:[1,0,1] neg_lo:[1,0,0]
	v_pk_mov_b32 v[232:233], v[136:137], v[152:153] op_sel:[1,1]
	v_pk_mov_b32 v[234:235], v[140:141], v[156:157] op_sel:[1,1]
	v_pk_mov_b32 v[244:245], v[144:145], v[160:161] op_sel:[1,1]
	v_pk_mov_b32 v[254:255], v[148:149], v[164:165] op_sel:[1,1]
	v_pk_fma_f32 v[232:233], v[32:33], v[200:201], v[232:233] op_sel_hi:[0,1,1]
	v_pk_fma_f32 v[234:235], v[34:35], v[202:203], v[234:235] op_sel_hi:[0,1,1]
	v_pk_fma_f32 v[244:245], v[36:37], v[204:205], v[244:245] op_sel_hi:[0,1,1]
	v_pk_fma_f32 v[254:255], v[38:39], v[206:207], v[254:255] op_sel_hi:[0,1,1]
	v_pk_fma_f32 v[200:201], v[32:33], v[200:201], v[232:233] op_sel:[1,1,0] op_sel_hi:[1,0,1] neg_lo:[1,0,0]
	v_pk_fma_f32 v[202:203], v[34:35], v[202:203], v[234:235] op_sel:[1,1,0] op_sel_hi:[1,0,1] neg_lo:[1,0,0]
	v_pk_fma_f32 v[204:205], v[36:37], v[204:205], v[244:245] op_sel:[1,1,0] op_sel_hi:[1,0,1] neg_lo:[1,0,0]
	v_pk_fma_f32 v[206:207], v[38:39], v[206:207], v[254:255] op_sel:[1,1,0] op_sel_hi:[1,0,1] neg_lo:[1,0,0]
	v_pk_mov_b32 v[232:233], v[138:139], v[154:155] op_sel:[0,0]
	v_pk_mov_b32 v[234:235], v[142:143], v[158:159] op_sel:[0,0]
	v_pk_mov_b32 v[244:245], v[146:147], v[162:163] op_sel:[0,0]
	v_pk_mov_b32 v[254:255], v[150:151], v[166:167] op_sel:[0,0]
	v_pk_fma_f32 v[232:233], v[32:33], v[200:201], v[232:233] op_sel_hi:[0,1,1]
	v_pk_fma_f32 v[234:235], v[34:35], v[202:203], v[234:235] op_sel_hi:[0,1,1]
	v_pk_fma_f32 v[244:245], v[36:37], v[204:205], v[244:245] op_sel_hi:[0,1,1]
	v_pk_fma_f32 v[254:255], v[38:39], v[206:207], v[254:255] op_sel_hi:[0,1,1]
	v_pk_fma_f32 v[200:201], v[32:33], v[200:201], v[232:233] op_sel:[1,1,0] op_sel_hi:[1,0,1] neg_lo:[1,0,0]
	v_pk_fma_f32 v[202:203], v[34:35], v[202:203], v[234:235] op_sel:[1,1,0] op_sel_hi:[1,0,1] neg_lo:[1,0,0]
	v_pk_fma_f32 v[204:205], v[36:37], v[204:205], v[244:245] op_sel:[1,1,0] op_sel_hi:[1,0,1] neg_lo:[1,0,0]
	v_pk_fma_f32 v[206:207], v[38:39], v[206:207], v[254:255] op_sel:[1,1,0] op_sel_hi:[1,0,1] neg_lo:[1,0,0]
	v_pk_mov_b32 v[232:233], v[138:139], v[154:155] op_sel:[1,1]
	v_pk_mov_b32 v[234:235], v[142:143], v[158:159] op_sel:[1,1]
	v_pk_mov_b32 v[244:245], v[146:147], v[162:163] op_sel:[1,1]
	v_pk_mov_b32 v[254:255], v[150:151], v[166:167] op_sel:[1,1]
	v_pk_fma_f32 v[232:233], v[32:33], v[200:201], v[232:233] op_sel_hi:[0,1,1]
	v_pk_fma_f32 v[234:235], v[34:35], v[202:203], v[234:235] op_sel_hi:[0,1,1]
	v_pk_fma_f32 v[244:245], v[36:37], v[204:205], v[244:245] op_sel_hi:[0,1,1]
	v_pk_fma_f32 v[254:255], v[38:39], v[206:207], v[254:255] op_sel_hi:[0,1,1]
	v_pk_fma_f32 v[200:201], v[32:33], v[200:201], v[232:233] op_sel:[1,1,0] op_sel_hi:[1,0,1] neg_lo:[1,0,0]
	v_pk_fma_f32 v[202:203], v[34:35], v[202:203], v[234:235] op_sel:[1,1,0] op_sel_hi:[1,0,1] neg_lo:[1,0,0]
	v_pk_fma_f32 v[204:205], v[36:37], v[204:205], v[244:245] op_sel:[1,1,0] op_sel_hi:[1,0,1] neg_lo:[1,0,0]
	v_pk_fma_f32 v[206:207], v[38:39], v[206:207], v[254:255] op_sel:[1,1,0] op_sel_hi:[1,0,1] neg_lo:[1,0,0]
	global_load_dwordx4 v[72:75], v238, s[20:21]
	v_add_u32_e32 v238, v238, v243
	s_waitcnt vmcnt(18)
; template <bool FINAL> __device__ __forceinline__ void phase_s5_scan(const Fr& F) {
;     ...
;             for (int sb = 0; sb < 4; ++sb) ua[sb] = lq < 2 ? *(const u32x4*)(U + ((size_t)bn * TB + tokof(s, cn * 64 + sb * 16 + l15)) * D + g * 16 + 8 * lq) : (u32x4){0u, 0u, 0u, 0u};
;             if (FINAL) { const float* e = E + ((size_t)(((s * 4 + bn) * 64 + g) * 68 + cn) * 64 + lane) * 2; e0 = e[0]; e1 = e[1]; }
;         }
; #pragma unroll
;         for (int sub = 0; sub < 4; ++sub) {
;             const bf16x8 A1 = __builtin_bit_cast(bf16x8, uc[sub]);
; #pragma unroll
;             for (int nt = 0; nt < 8; ++nt) {
;                 f32x4 acc = {0.f, 0.f, 0.f, 0.f};
;                 acc = __builtin_amdgcn_mfma_f32_16x16x32_bf16(A1, B1[nt], acc, 0, 0, 0);
; #pragma unroll
;                 for (int reg = 0; reg < 4; ++reg) BUl[(4 * lq + reg) * 132 + 16 * nt + l15] = acc[reg];
;             }
;             asm volatile("s_waitcnt lgkmcnt(0)" ::: "memory");
; #pragma unroll 4
;             for (int jj = 0; jj < 16; ++jj) {
;                 const float br_ = BUl[jj * 132 + lane], bi_ = BUl[jj * 132 + 64 + lane];
;                 const float nr = ar * xr - ai * xi + br_, ni = ar * xi + ai * xr + bi_; xr = nr; xi = ni;
;                 if (FINAL) { BUl[jj * 132 + lane] = xr; BUl[jj * 132 + 64 + lane] = xi; }
;             }
	v_mfma_f32_16x16x32_bf16 v[136:139], v[80:83], v[0:3], 0
	v_mfma_f32_16x16x32_bf16 v[140:143], v[80:83], v[4:7], 0
	v_mfma_f32_16x16x32_bf16 v[144:147], v[80:83], v[8:11], 0
	v_mfma_f32_16x16x32_bf16 v[148:151], v[80:83], v[12:15], 0
	v_mfma_f32_16x16x32_bf16 v[152:155], v[80:83], v[16:19], 0
	v_mfma_f32_16x16x32_bf16 v[156:159], v[80:83], v[20:23], 0
	v_mfma_f32_16x16x32_bf16 v[160:163], v[80:83], v[24:27], 0
	v_mfma_f32_16x16x32_bf16 v[164:167], v[80:83], v[28:31], 0
	v_pk_mov_b32 v[232:233], v[168:169], v[184:185] op_sel:[0,0]
	v_pk_mov_b32 v[234:235], v[172:173], v[188:189] op_sel:[0,0]
	v_pk_mov_b32 v[244:245], v[176:177], v[192:193] op_sel:[0,0]
	v_pk_mov_b32 v[254:255], v[180:181], v[196:197] op_sel:[0,0]
	v_pk_fma_f32 v[232:233], v[32:33], v[200:201], v[232:233] op_sel_hi:[0,1,1]
	v_pk_fma_f32 v[234:235], v[34:35], v[202:203], v[234:235] op_sel_hi:[0,1,1]
	v_pk_fma_f32 v[244:245], v[36:37], v[204:205], v[244:245] op_sel_hi:[0,1,1]
	v_pk_fma_f32 v[254:255], v[38:39], v[206:207], v[254:255] op_sel_hi:[0,1,1]
	v_pk_fma_f32 v[200:201], v[32:33], v[200:201], v[232:233] op_sel:[1,1,0] op_sel_hi:[1,0,1] neg_lo:[1,0,0]
	v_pk_fma_f32 v[202:203], v[34:35], v[202:203], v[234:235] op_sel:[1,1,0] op_sel_hi:[1,0,1] neg_lo:[1,0,0]
	v_pk_fma_f32 v[204:205], v[36:37], v[204:205], v[244:245] op_sel:[1,1,0] op_sel_hi:[1,0,1] neg_lo:[1,0,0]
	v_pk_fma_f32 v[206:207], v[38:39], v[206:207], v[254:255] op_sel:[1,1,0] op_sel_hi:[1,0,1] neg_lo:[1,0,0]
	v_pk_mov_b32 v[232:233], v[168:169], v[184:185] op_sel:[1,1]
	v_pk_mov_b32 v[234:235], v[172:173], v[188:189] op_sel:[1,1]
	v_pk_mov_b32 v[244:245], v[176:177], v[192:193] op_sel:[1,1]
	v_pk_mov_b32 v[254:255], v[180:181], v[196:197] op_sel:[1,1]
	v_pk_fma_f32 v[232:233], v[32:33], v[200:201], v[232:233] op_sel_hi:[0,1,1]
	v_pk_fma_f32 v[234:235], v[34:35], v[202:203], v[234:235] op_sel_hi:[0,1,1]
	v_pk_fma_f32 v[244:245], v[36:37], v[204:205], v[244:245] op_sel_hi:[0,1,1]
	v_pk_fma_f32 v[254:255], v[38:39], v[206:207], v[254:255] op_sel_hi:[0,1,1]
	v_pk_fma_f32 v[200:201], v[32:33], v[200:201], v[232:233] op_sel:[1,1,0] op_sel_hi:[1,0,1] neg_lo:[1,0,0]
	v_pk_fma_f32 v[202:203], v[34:35], v[202:203], v[234:235] op_sel:[1,1,0] op_sel_hi:[1,0,1] neg_lo:[1,0,0]
	v_pk_fma_f32 v[204:205], v[36:37], v[204:205], v[244:245] op_sel:[1,1,0] op_sel_hi:[1,0,1] neg_lo:[1,0,0]
	v_pk_fma_f32 v[206:207], v[38:39], v[206:207], v[254:255] op_sel:[1,1,0] op_sel_hi:[1,0,1] neg_lo:[1,0,0]
	v_pk_mov_b32 v[232:233], v[170:171], v[186:187] op_sel:[0,0]
	v_pk_mov_b32 v[234:235], v[174:175], v[190:191] op_sel:[0,0]
	v_pk_mov_b32 v[244:245], v[178:179], v[194:195] op_sel:[0,0]
	v_pk_mov_b32 v[254:255], v[182:183], v[198:199] op_sel:[0,0]
	v_pk_fma_f32 v[232:233], v[32:33], v[200:201], v[232:233] op_sel_hi:[0,1,1]
	v_pk_fma_f32 v[234:235], v[34:35], v[202:203], v[234:235] op_sel_hi:[0,1,1]
	v_pk_fma_f32 v[244:245], v[36:37], v[204:205], v[244:245] op_sel_hi:[0,1,1]
	v_pk_fma_f32 v[254:255], v[38:39], v[206:207], v[254:255] op_sel_hi:[0,1,1]
	v_pk_fma_f32 v[200:201], v[32:33], v[200:201], v[232:233] op_sel:[1,1,0] op_sel_hi:[1,0,1] neg_lo:[1,0,0]
	v_pk_fma_f32 v[202:203], v[34:35], v[202:203], v[234:235] op_sel:[1,1,0] op_sel_hi:[1,0,1] neg_lo:[1,0,0]
	v_pk_fma_f32 v[204:205], v[36:37], v[204:205], v[244:245] op_sel:[1,1,0] op_sel_hi:[1,0,1] neg_lo:[1,0,0]
	v_pk_fma_f32 v[206:207], v[38:39], v[206:207], v[254:255] op_sel:[1,1,0] op_sel_hi:[1,0,1] neg_lo:[1,0,0]
	v_pk_mov_b32 v[232:233], v[170:171], v[186:187] op_sel:[1,1]
	v_pk_mov_b32 v[234:235], v[174:175], v[190:191] op_sel:[1,1]
	v_pk_mov_b32 v[244:245], v[178:179], v[194:195] op_sel:[1,1]
	v_pk_mov_b32 v[254:255], v[182:183], v[198:199] op_sel:[1,1]
	v_pk_fma_f32 v[232:233], v[32:33], v[200:201], v[232:233] op_sel_hi:[0,1,1]
	v_pk_fma_f32 v[234:235], v[34:35], v[202:203], v[234:235] op_sel_hi:[0,1,1]
	v_pk_fma_f32 v[244:245], v[36:37], v[204:205], v[244:245] op_sel_hi:[0,1,1]
	v_pk_fma_f32 v[254:255], v[38:39], v[206:207], v[254:255] op_sel_hi:[0,1,1]
	v_pk_fma_f32 v[200:201], v[32:33], v[200:201], v[232:233] op_sel:[1,1,0] op_sel_hi:[1,0,1] neg_lo:[1,0,0]
	v_pk_fma_f32 v[202:203], v[34:35], v[202:203], v[234:235] op_sel:[1,1,0] op_sel_hi:[1,0,1] neg_lo:[1,0,0]
	v_pk_fma_f32 v[204:205], v[36:37], v[204:205], v[244:245] op_sel:[1,1,0] op_sel_hi:[1,0,1] neg_lo:[1,0,0]
	v_pk_fma_f32 v[206:207], v[38:39], v[206:207], v[254:255] op_sel:[1,1,0] op_sel_hi:[1,0,1] neg_lo:[1,0,0]
	global_load_dwordx4 v[76:79], v238, s[20:21]
	v_add_u32_e32 v238, v238, v243
	s_waitcnt vmcnt(18)
; template <bool FINAL> __device__ __forceinline__ void phase_s5_scan(const Fr& F) {
;     ...
;             for (int sb = 0; sb < 4; ++sb) ua[sb] = lq < 2 ? *(const u32x4*)(U + ((size_t)bn * TB + tokof(s, cn * 64 + sb * 16 + l15)) * D + g * 16 + 8 * lq) : (u32x4){0u, 0u, 0u, 0u};
;             if (FINAL) { const float* e = E + ((size_t)(((s * 4 + bn) * 64 + g) * 68 + cn) * 64 + lane) * 2; e0 = e[0]; e1 = e[1]; }
;         }
; #pragma unroll
;         for (int sub = 0; sub < 4; ++sub) {
;             const bf16x8 A1 = __builtin_bit_cast(bf16x8, uc[sub]);
; #pragma unroll
;             for (int nt = 0; nt < 8; ++nt) {
;                 f32x4 acc = {0.f, 0.f, 0.f, 0.f};
;                 acc = __builtin_amdgcn_mfma_f32_16x16x32_bf16(A1, B1[nt], acc, 0, 0, 0);
; #pragma unroll
;                 for (int reg = 0; reg < 4; ++reg) BUl[(4 * lq + reg) * 132 + 16 * nt + l15] = acc[reg];
;             }
;             asm volatile("s_waitcnt lgkmcnt(0)" ::: "memory");
; #pragma unroll 4
;             for (int jj = 0; jj < 16; ++jj) {
;                 const float br_ = BUl[jj * 132 + lane], bi_ = BUl[jj * 132 + 64 + lane];
;                 const float nr = ar * xr - ai * xi + br_, ni = ar * xi + ai * xr + bi_; xr = nr; xi = ni;
;                 if (FINAL) { BUl[jj * 132 + lane] = xr; BUl[jj * 132 + 64 + lane] = xi; }
;             }
	v_mfma_f32_16x16x32_bf16 v[168:171], v[84:87], v[0:3], 0
	v_mfma_f32_16x16x32_bf16 v[172:175], v[84:87], v[4:7], 0
	v_mfma_f32_16x16x32_bf16 v[176:179], v[84:87], v[8:11], 0
	v_mfma_f32_16x16x32_bf16 v[180:183], v[84:87], v[12:15], 0
	v_mfma_f32_16x16x32_bf16 v[184:187], v[84:87], v[16:19], 0
	v_mfma_f32_16x16x32_bf16 v[188:191], v[84:87], v[20:23], 0
	v_mfma_f32_16x16x32_bf16 v[192:195], v[84:87], v[24:27], 0
	v_mfma_f32_16x16x32_bf16 v[196:199], v[84:87], v[28:31], 0
	v_pk_mov_b32 v[232:233], v[136:137], v[152:153] op_sel:[0,0]
	v_pk_mov_b32 v[234:235], v[140:141], v[156:157] op_sel:[0,0]
	v_pk_mov_b32 v[244:245], v[144:145], v[160:161] op_sel:[0,0]
	v_pk_mov_b32 v[254:255], v[148:149], v[164:165] op_sel:[0,0]
	v_pk_fma_f32 v[232:233], v[32:33], v[200:201], v[232:233] op_sel_hi:[0,1,1]
	v_pk_fma_f32 v[234:235], v[34:35], v[202:203], v[234:235] op_sel_hi:[0,1,1]
	v_pk_fma_f32 v[244:245], v[36:37], v[204:205], v[244:245] op_sel_hi:[0,1,1]
	v_pk_fma_f32 v[254:255], v[38:39], v[206:207], v[254:255] op_sel_hi:[0,1,1]
	v_pk_fma_f32 v[200:201], v[32:33], v[200:201], v[232:233] op_sel:[1,1,0] op_sel_hi:[1,0,1] neg_lo:[1,0,0]
	v_pk_fma_f32 v[202:203], v[34:35], v[202:203], v[234:235] op_sel:[1,1,0] op_sel_hi:[1,0,1] neg_lo:[1,0,0]
	v_pk_fma_f32 v[204:205], v[36:37], v[204:205], v[244:245] op_sel:[1,1,0] op_sel_hi:[1,0,1] neg_lo:[1,0,0]
	v_pk_fma_f32 v[206:207], v[38:39], v[206:207], v[254:255] op_sel:[1,1,0] op_sel_hi:[1,0,1] neg_lo:[1,0,0]
	v_pk_mov_b32 v[232:233], v[136:137], v[152:153] op_sel:[1,1]
	v_pk_mov_b32 v[234:235], v[140:141], v[156:157] op_sel:[1,1]
	v_pk_mov_b32 v[244:245], v[144:145], v[160:161] op_sel:[1,1]
	v_pk_mov_b32 v[254:255], v[148:149], v[164:165] op_sel:[1,1]
	v_pk_fma_f32 v[232:233], v[32:33], v[200:201], v[232:233] op_sel_hi:[0,1,1]
	v_pk_fma_f32 v[234:235], v[34:35], v[202:203], v[234:235] op_sel_hi:[0,1,1]
	v_pk_fma_f32 v[244:245], v[36:37], v[204:205], v[244:245] op_sel_hi:[0,1,1]
	v_pk_fma_f32 v[254:255], v[38:39], v[206:207], v[254:255] op_sel_hi:[0,1,1]
	v_pk_fma_f32 v[200:201], v[32:33], v[200:201], v[232:233] op_sel:[1,1,0] op_sel_hi:[1,0,1] neg_lo:[1,0,0]
	v_pk_fma_f32 v[202:203], v[34:35], v[202:203], v[234:235] op_sel:[1,1,0] op_sel_hi:[1,0,1] neg_lo:[1,0,0]
	v_pk_fma_f32 v[204:205], v[36:37], v[204:205], v[244:245] op_sel:[1,1,0] op_sel_hi:[1,0,1] neg_lo:[1,0,0]
	v_pk_fma_f32 v[206:207], v[38:39], v[206:207], v[254:255] op_sel:[1,1,0] op_sel_hi:[1,0,1] neg_lo:[1,0,0]
	v_pk_mov_b32 v[232:233], v[138:139], v[154:155] op_sel:[0,0]
	v_pk_mov_b32 v[234:235], v[142:143], v[158:159] op_sel:[0,0]
	v_pk_mov_b32 v[244:245], v[146:147], v[162:163] op_sel:[0,0]
	v_pk_mov_b32 v[254:255], v[150:151], v[166:167] op_sel:[0,0]
	v_pk_fma_f32 v[232:233], v[32:33], v[200:201], v[232:233] op_sel_hi:[0,1,1]
	v_pk_fma_f32 v[234:235], v[34:35], v[202:203], v[234:235] op_sel_hi:[0,1,1]
	v_pk_fma_f32 v[244:245], v[36:37], v[204:205], v[244:245] op_sel_hi:[0,1,1]
	v_pk_fma_f32 v[254:255], v[38:39], v[206:207], v[254:255] op_sel_hi:[0,1,1]
	v_pk_fma_f32 v[200:201], v[32:33], v[200:201], v[232:233] op_sel:[1,1,0] op_sel_hi:[1,0,1] neg_lo:[1,0,0]
	v_pk_fma_f32 v[202:203], v[34:35], v[202:203], v[234:235] op_sel:[1,1,0] op_sel_hi:[1,0,1] neg_lo:[1,0,0]
	v_pk_fma_f32 v[204:205], v[36:37], v[204:205], v[244:245] op_sel:[1,1,0] op_sel_hi:[1,0,1] neg_lo:[1,0,0]
	v_pk_fma_f32 v[206:207], v[38:39], v[206:207], v[254:255] op_sel:[1,1,0] op_sel_hi:[1,0,1] neg_lo:[1,0,0]
	v_pk_mov_b32 v[232:233], v[138:139], v[154:155] op_sel:[1,1]
	v_pk_mov_b32 v[234:235], v[142:143], v[158:159] op_sel:[1,1]
	v_pk_mov_b32 v[244:245], v[146:147], v[162:163] op_sel:[1,1]
	v_pk_mov_b32 v[254:255], v[150:151], v[166:167] op_sel:[1,1]
	v_pk_fma_f32 v[232:233], v[32:33], v[200:201], v[232:233] op_sel_hi:[0,1,1]
	v_pk_fma_f32 v[234:235], v[34:35], v[202:203], v[234:235] op_sel_hi:[0,1,1]
	v_pk_fma_f32 v[244:245], v[36:37], v[204:205], v[244:245] op_sel_hi:[0,1,1]
	v_pk_fma_f32 v[254:255], v[38:39], v[206:207], v[254:255] op_sel_hi:[0,1,1]
	v_pk_fma_f32 v[200:201], v[32:33], v[200:201], v[232:233] op_sel:[1,1,0] op_sel_hi:[1,0,1] neg_lo:[1,0,0]
	v_pk_fma_f32 v[202:203], v[34:35], v[202:203], v[234:235] op_sel:[1,1,0] op_sel_hi:[1,0,1] neg_lo:[1,0,0]
	v_pk_fma_f32 v[204:205], v[36:37], v[204:205], v[244:245] op_sel:[1,1,0] op_sel_hi:[1,0,1] neg_lo:[1,0,0]
	v_pk_fma_f32 v[206:207], v[38:39], v[206:207], v[254:255] op_sel:[1,1,0] op_sel_hi:[1,0,1] neg_lo:[1,0,0]
	global_load_dwordx4 v[80:83], v238, s[20:21]
	v_add_u32_e32 v238, v238, v243
	s_waitcnt vmcnt(18)
; template <bool FINAL> __device__ __forceinline__ void phase_s5_scan(const Fr& F) {
;     ...
;             for (int sb = 0; sb < 4; ++sb) ua[sb] = lq < 2 ? *(const u32x4*)(U + ((size_t)bn * TB + tokof(s, cn * 64 + sb * 16 + l15)) * D + g * 16 + 8 * lq) : (u32x4){0u, 0u, 0u, 0u};
;             if (FINAL) { const float* e = E + ((size_t)(((s * 4 + bn) * 64 + g) * 68 + cn) * 64 + lane) * 2; e0 = e[0]; e1 = e[1]; }
;         }
; #pragma unroll
;         for (int sub = 0; sub < 4; ++sub) {
;             const bf16x8 A1 = __builtin_bit_cast(bf16x8, uc[sub]);
; #pragma unroll
;             for (int nt = 0; nt < 8; ++nt) {
;                 f32x4 acc = {0.f, 0.f, 0.f, 0.f};
;                 acc = __builtin_amdgcn_mfma_f32_16x16x32_bf16(A1, B1[nt], acc, 0, 0, 0);
; #pragma unroll
;                 for (int reg = 0; reg < 4; ++reg) BUl[(4 * lq + reg) * 132 + 16 * nt + l15] = acc[reg];
;             }
;             asm volatile("s_waitcnt lgkmcnt(0)" ::: "memory");
; #pragma unroll 4
;             for (int jj = 0; jj < 16; ++jj) {
;                 const float br_ = BUl[jj * 132 + lane], bi_ = BUl[jj * 132 + 64 + lane];
;                 const float nr = ar * xr - ai * xi + br_, ni = ar * xi + ai * xr + bi_; xr = nr; xi = ni;
;                 if (FINAL) { BUl[jj * 132 + lane] = xr; BUl[jj * 132 + 64 + lane] = xi; }
;             }
	v_mfma_f32_16x16x32_bf16 v[136:139], v[88:91], v[0:3], 0
	v_mfma_f32_16x16x32_bf16 v[140:143], v[88:91], v[4:7], 0
	v_mfma_f32_16x16x32_bf16 v[144:147], v[88:91], v[8:11], 0
	v_mfma_f32_16x16x32_bf16 v[148:151], v[88:91], v[12:15], 0
	v_mfma_f32_16x16x32_bf16 v[152:155], v[88:91], v[16:19], 0
	v_mfma_f32_16x16x32_bf16 v[156:159], v[88:91], v[20:23], 0
	v_mfma_f32_16x16x32_bf16 v[160:163], v[88:91], v[24:27], 0
	v_mfma_f32_16x16x32_bf16 v[164:167], v[88:91], v[28:31], 0
	v_pk_mov_b32 v[232:233], v[168:169], v[184:185] op_sel:[0,0]
	v_pk_mov_b32 v[234:235], v[172:173], v[188:189] op_sel:[0,0]
	v_pk_mov_b32 v[244:245], v[176:177], v[192:193] op_sel:[0,0]
	v_pk_mov_b32 v[254:255], v[180:181], v[196:197] op_sel:[0,0]
	v_pk_fma_f32 v[232:233], v[32:33], v[200:201], v[232:233] op_sel_hi:[0,1,1]
	v_pk_fma_f32 v[234:235], v[34:35], v[202:203], v[234:235] op_sel_hi:[0,1,1]
	v_pk_fma_f32 v[244:245], v[36:37], v[204:205], v[244:245] op_sel_hi:[0,1,1]
	v_pk_fma_f32 v[254:255], v[38:39], v[206:207], v[254:255] op_sel_hi:[0,1,1]
	v_pk_fma_f32 v[200:201], v[32:33], v[200:201], v[232:233] op_sel:[1,1,0] op_sel_hi:[1,0,1] neg_lo:[1,0,0]
	v_pk_fma_f32 v[202:203], v[34:35], v[202:203], v[234:235] op_sel:[1,1,0] op_sel_hi:[1,0,1] neg_lo:[1,0,0]
	v_pk_fma_f32 v[204:205], v[36:37], v[204:205], v[244:245] op_sel:[1,1,0] op_sel_hi:[1,0,1] neg_lo:[1,0,0]
	v_pk_fma_f32 v[206:207], v[38:39], v[206:207], v[254:255] op_sel:[1,1,0] op_sel_hi:[1,0,1] neg_lo:[1,0,0]
	v_pk_mov_b32 v[232:233], v[168:169], v[184:185] op_sel:[1,1]
	v_pk_mov_b32 v[234:235], v[172:173], v[188:189] op_sel:[1,1]
	v_pk_mov_b32 v[244:245], v[176:177], v[192:193] op_sel:[1,1]
	v_pk_mov_b32 v[254:255], v[180:181], v[196:197] op_sel:[1,1]
	v_pk_fma_f32 v[232:233], v[32:33], v[200:201], v[232:233] op_sel_hi:[0,1,1]
	v_pk_fma_f32 v[234:235], v[34:35], v[202:203], v[234:235] op_sel_hi:[0,1,1]
	v_pk_fma_f32 v[244:245], v[36:37], v[204:205], v[244:245] op_sel_hi:[0,1,1]
	v_pk_fma_f32 v[254:255], v[38:39], v[206:207], v[254:255] op_sel_hi:[0,1,1]
	v_pk_fma_f32 v[200:201], v[32:33], v[200:201], v[232:233] op_sel:[1,1,0] op_sel_hi:[1,0,1] neg_lo:[1,0,0]
	v_pk_fma_f32 v[202:203], v[34:35], v[202:203], v[234:235] op_sel:[1,1,0] op_sel_hi:[1,0,1] neg_lo:[1,0,0]
	v_pk_fma_f32 v[204:205], v[36:37], v[204:205], v[244:245] op_sel:[1,1,0] op_sel_hi:[1,0,1] neg_lo:[1,0,0]
	v_pk_fma_f32 v[206:207], v[38:39], v[206:207], v[254:255] op_sel:[1,1,0] op_sel_hi:[1,0,1] neg_lo:[1,0,0]
	v_pk_mov_b32 v[232:233], v[170:171], v[186:187] op_sel:[0,0]
	v_pk_mov_b32 v[234:235], v[174:175], v[190:191] op_sel:[0,0]
	v_pk_mov_b32 v[244:245], v[178:179], v[194:195] op_sel:[0,0]
	v_pk_mov_b32 v[254:255], v[182:183], v[198:199] op_sel:[0,0]
	v_pk_fma_f32 v[232:233], v[32:33], v[200:201], v[232:233] op_sel_hi:[0,1,1]
	v_pk_fma_f32 v[234:235], v[34:35], v[202:203], v[234:235] op_sel_hi:[0,1,1]
	v_pk_fma_f32 v[244:245], v[36:37], v[204:205], v[244:245] op_sel_hi:[0,1,1]
	v_pk_fma_f32 v[254:255], v[38:39], v[206:207], v[254:255] op_sel_hi:[0,1,1]
	v_pk_fma_f32 v[200:201], v[32:33], v[200:201], v[232:233] op_sel:[1,1,0] op_sel_hi:[1,0,1] neg_lo:[1,0,0]
	v_pk_fma_f32 v[202:203], v[34:35], v[202:203], v[234:235] op_sel:[1,1,0] op_sel_hi:[1,0,1] neg_lo:[1,0,0]
	v_pk_fma_f32 v[204:205], v[36:37], v[204:205], v[244:245] op_sel:[1,1,0] op_sel_hi:[1,0,1] neg_lo:[1,0,0]
	v_pk_fma_f32 v[206:207], v[38:39], v[206:207], v[254:255] op_sel:[1,1,0] op_sel_hi:[1,0,1] neg_lo:[1,0,0]
	v_pk_mov_b32 v[232:233], v[170:171], v[186:187] op_sel:[1,1]
	v_pk_mov_b32 v[234:235], v[174:175], v[190:191] op_sel:[1,1]
	v_pk_mov_b32 v[244:245], v[178:179], v[194:195] op_sel:[1,1]
	v_pk_mov_b32 v[254:255], v[182:183], v[198:199] op_sel:[1,1]
	v_pk_fma_f32 v[232:233], v[32:33], v[200:201], v[232:233] op_sel_hi:[0,1,1]
	v_pk_fma_f32 v[234:235], v[34:35], v[202:203], v[234:235] op_sel_hi:[0,1,1]
	v_pk_fma_f32 v[244:245], v[36:37], v[204:205], v[244:245] op_sel_hi:[0,1,1]
	v_pk_fma_f32 v[254:255], v[38:39], v[206:207], v[254:255] op_sel_hi:[0,1,1]
	v_pk_fma_f32 v[200:201], v[32:33], v[200:201], v[232:233] op_sel:[1,1,0] op_sel_hi:[1,0,1] neg_lo:[1,0,0]
	v_pk_fma_f32 v[202:203], v[34:35], v[202:203], v[234:235] op_sel:[1,1,0] op_sel_hi:[1,0,1] neg_lo:[1,0,0]
	v_pk_fma_f32 v[204:205], v[36:37], v[204:205], v[244:245] op_sel:[1,1,0] op_sel_hi:[1,0,1] neg_lo:[1,0,0]
	v_pk_fma_f32 v[206:207], v[38:39], v[206:207], v[254:255] op_sel:[1,1,0] op_sel_hi:[1,0,1] neg_lo:[1,0,0]
	global_load_dwordx4 v[84:87], v238, s[20:21]
	v_add_u32_e32 v238, v238, v243
	s_waitcnt vmcnt(18)
; template <bool FINAL> __device__ __forceinline__ void phase_s5_scan(const Fr& F) {
;     ...
;             for (int sb = 0; sb < 4; ++sb) ua[sb] = lq < 2 ? *(const u32x4*)(U + ((size_t)bn * TB + tokof(s, cn * 64 + sb * 16 + l15)) * D + g * 16 + 8 * lq) : (u32x4){0u, 0u, 0u, 0u};
;             if (FINAL) { const float* e = E + ((size_t)(((s * 4 + bn) * 64 + g) * 68 + cn) * 64 + lane) * 2; e0 = e[0]; e1 = e[1]; }
;         }
; #pragma unroll
;         for (int sub = 0; sub < 4; ++sub) {
;             const bf16x8 A1 = __builtin_bit_cast(bf16x8, uc[sub]);
; #pragma unroll
;             for (int nt = 0; nt < 8; ++nt) {
;                 f32x4 acc = {0.f, 0.f, 0.f, 0.f};
;                 acc = __builtin_amdgcn_mfma_f32_16x16x32_bf16(A1, B1[nt], acc, 0, 0, 0);
; #pragma unroll
;                 for (int reg = 0; reg < 4; ++reg) BUl[(4 * lq + reg) * 132 + 16 * nt + l15] = acc[reg];
;             }
;             asm volatile("s_waitcnt lgkmcnt(0)" ::: "memory");
; #pragma unroll 4
;             for (int jj = 0; jj < 16; ++jj) {
;                 const float br_ = BUl[jj * 132 + lane], bi_ = BUl[jj * 132 + 64 + lane];
;                 const float nr = ar * xr - ai * xi + br_, ni = ar * xi + ai * xr + bi_; xr = nr; xi = ni;
;                 if (FINAL) { BUl[jj * 132 + lane] = xr; BUl[jj * 132 + 64 + lane] = xi; }
;             }
	v_mfma_f32_16x16x32_bf16 v[168:171], v[92:95], v[0:3], 0
	v_mfma_f32_16x16x32_bf16 v[172:175], v[92:95], v[4:7], 0
	v_mfma_f32_16x16x32_bf16 v[176:179], v[92:95], v[8:11], 0
	v_mfma_f32_16x16x32_bf16 v[180:183], v[92:95], v[12:15], 0
	v_mfma_f32_16x16x32_bf16 v[184:187], v[92:95], v[16:19], 0
	v_mfma_f32_16x16x32_bf16 v[188:191], v[92:95], v[20:23], 0
	v_mfma_f32_16x16x32_bf16 v[192:195], v[92:95], v[24:27], 0
	v_mfma_f32_16x16x32_bf16 v[196:199], v[92:95], v[28:31], 0
	v_pk_mov_b32 v[232:233], v[136:137], v[152:153] op_sel:[0,0]
	v_pk_mov_b32 v[234:235], v[140:141], v[156:157] op_sel:[0,0]
	v_pk_mov_b32 v[244:245], v[144:145], v[160:161] op_sel:[0,0]
	v_pk_mov_b32 v[254:255], v[148:149], v[164:165] op_sel:[0,0]
	v_pk_fma_f32 v[232:233], v[32:33], v[200:201], v[232:233] op_sel_hi:[0,1,1]
	v_pk_fma_f32 v[234:235], v[34:35], v[202:203], v[234:235] op_sel_hi:[0,1,1]
	v_pk_fma_f32 v[244:245], v[36:37], v[204:205], v[244:245] op_sel_hi:[0,1,1]
	v_pk_fma_f32 v[254:255], v[38:39], v[206:207], v[254:255] op_sel_hi:[0,1,1]
	v_pk_fma_f32 v[200:201], v[32:33], v[200:201], v[232:233] op_sel:[1,1,0] op_sel_hi:[1,0,1] neg_lo:[1,0,0]
	v_pk_fma_f32 v[202:203], v[34:35], v[202:203], v[234:235] op_sel:[1,1,0] op_sel_hi:[1,0,1] neg_lo:[1,0,0]
	v_pk_fma_f32 v[204:205], v[36:37], v[204:205], v[244:245] op_sel:[1,1,0] op_sel_hi:[1,0,1] neg_lo:[1,0,0]
	v_pk_fma_f32 v[206:207], v[38:39], v[206:207], v[254:255] op_sel:[1,1,0] op_sel_hi:[1,0,1] neg_lo:[1,0,0]
	v_pk_mov_b32 v[232:233], v[136:137], v[152:153] op_sel:[1,1]
	v_pk_mov_b32 v[234:235], v[140:141], v[156:157] op_sel:[1,1]
	v_pk_mov_b32 v[244:245], v[144:145], v[160:161] op_sel:[1,1]
	v_pk_mov_b32 v[254:255], v[148:149], v[164:165] op_sel:[1,1]
	v_pk_fma_f32 v[232:233], v[32:33], v[200:201], v[232:233] op_sel_hi:[0,1,1]
	v_pk_fma_f32 v[234:235], v[34:35], v[202:203], v[234:235] op_sel_hi:[0,1,1]
	v_pk_fma_f32 v[244:245], v[36:37], v[204:205], v[244:245] op_sel_hi:[0,1,1]
	v_pk_fma_f32 v[254:255], v[38:39], v[206:207], v[254:255] op_sel_hi:[0,1,1]
	v_pk_fma_f32 v[200:201], v[32:33], v[200:201], v[232:233] op_sel:[1,1,0] op_sel_hi:[1,0,1] neg_lo:[1,0,0]
	v_pk_fma_f32 v[202:203], v[34:35], v[202:203], v[234:235] op_sel:[1,1,0] op_sel_hi:[1,0,1] neg_lo:[1,0,0]
	v_pk_fma_f32 v[204:205], v[36:37], v[204:205], v[244:245] op_sel:[1,1,0] op_sel_hi:[1,0,1] neg_lo:[1,0,0]
	v_pk_fma_f32 v[206:207], v[38:39], v[206:207], v[254:255] op_sel:[1,1,0] op_sel_hi:[1,0,1] neg_lo:[1,0,0]
	v_pk_mov_b32 v[232:233], v[138:139], v[154:155] op_sel:[0,0]
	v_pk_mov_b32 v[234:235], v[142:143], v[158:159] op_sel:[0,0]
	v_pk_mov_b32 v[244:245], v[146:147], v[162:163] op_sel:[0,0]
	v_pk_mov_b32 v[254:255], v[150:151], v[166:167] op_sel:[0,0]
	v_pk_fma_f32 v[232:233], v[32:33], v[200:201], v[232:233] op_sel_hi:[0,1,1]
	v_pk_fma_f32 v[234:235], v[34:35], v[202:203], v[234:235] op_sel_hi:[0,1,1]
	v_pk_fma_f32 v[244:245], v[36:37], v[204:205], v[244:245] op_sel_hi:[0,1,1]
	v_pk_fma_f32 v[254:255], v[38:39], v[206:207], v[254:255] op_sel_hi:[0,1,1]
	v_pk_fma_f32 v[200:201], v[32:33], v[200:201], v[232:233] op_sel:[1,1,0] op_sel_hi:[1,0,1] neg_lo:[1,0,0]
	v_pk_fma_f32 v[202:203], v[34:35], v[202:203], v[234:235] op_sel:[1,1,0] op_sel_hi:[1,0,1] neg_lo:[1,0,0]
	v_pk_fma_f32 v[204:205], v[36:37], v[204:205], v[244:245] op_sel:[1,1,0] op_sel_hi:[1,0,1] neg_lo:[1,0,0]
	v_pk_fma_f32 v[206:207], v[38:39], v[206:207], v[254:255] op_sel:[1,1,0] op_sel_hi:[1,0,1] neg_lo:[1,0,0]
	v_pk_mov_b32 v[232:233], v[138:139], v[154:155] op_sel:[1,1]
	v_pk_mov_b32 v[234:235], v[142:143], v[158:159] op_sel:[1,1]
	v_pk_mov_b32 v[244:245], v[146:147], v[162:163] op_sel:[1,1]
	v_pk_mov_b32 v[254:255], v[150:151], v[166:167] op_sel:[1,1]
	v_pk_fma_f32 v[232:233], v[32:33], v[200:201], v[232:233] op_sel_hi:[0,1,1]
	v_pk_fma_f32 v[234:235], v[34:35], v[202:203], v[234:235] op_sel_hi:[0,1,1]
	v_pk_fma_f32 v[244:245], v[36:37], v[204:205], v[244:245] op_sel_hi:[0,1,1]
	v_pk_fma_f32 v[254:255], v[38:39], v[206:207], v[254:255] op_sel_hi:[0,1,1]
	v_pk_fma_f32 v[200:201], v[32:33], v[200:201], v[232:233] op_sel:[1,1,0] op_sel_hi:[1,0,1] neg_lo:[1,0,0]
	v_pk_fma_f32 v[202:203], v[34:35], v[202:203], v[234:235] op_sel:[1,1,0] op_sel_hi:[1,0,1] neg_lo:[1,0,0]
	v_pk_fma_f32 v[204:205], v[36:37], v[204:205], v[244:245] op_sel:[1,1,0] op_sel_hi:[1,0,1] neg_lo:[1,0,0]
	v_pk_fma_f32 v[206:207], v[38:39], v[206:207], v[254:255] op_sel:[1,1,0] op_sel_hi:[1,0,1] neg_lo:[1,0,0]
	global_load_dwordx4 v[88:91], v238, s[20:21]
	v_add_u32_e32 v238, v238, v243
	s_waitcnt vmcnt(18)
; template <bool FINAL> __device__ __forceinline__ void phase_s5_scan(const Fr& F) {
;     ...
;             for (int sb = 0; sb < 4; ++sb) ua[sb] = lq < 2 ? *(const u32x4*)(U + ((size_t)bn * TB + tokof(s, cn * 64 + sb * 16 + l15)) * D + g * 16 + 8 * lq) : (u32x4){0u, 0u, 0u, 0u};
;             if (FINAL) { const float* e = E + ((size_t)(((s * 4 + bn) * 64 + g) * 68 + cn) * 64 + lane) * 2; e0 = e[0]; e1 = e[1]; }
;         }
; #pragma unroll
;         for (int sub = 0; sub < 4; ++sub) {
;             const bf16x8 A1 = __builtin_bit_cast(bf16x8, uc[sub]);
; #pragma unroll
;             for (int nt = 0; nt < 8; ++nt) {
;                 f32x4 acc = {0.f, 0.f, 0.f, 0.f};
;                 acc = __builtin_amdgcn_mfma_f32_16x16x32_bf16(A1, B1[nt], acc, 0, 0, 0);
; #pragma unroll
;                 for (int reg = 0; reg < 4; ++reg) BUl[(4 * lq + reg) * 132 + 16 * nt + l15] = acc[reg];
;             }
;             asm volatile("s_waitcnt lgkmcnt(0)" ::: "memory");
; #pragma unroll 4
;             for (int jj = 0; jj < 16; ++jj) {
;                 const float br_ = BUl[jj * 132 + lane], bi_ = BUl[jj * 132 + 64 + lane];
;                 const float nr = ar * xr - ai * xi + br_, ni = ar * xi + ai * xr + bi_; xr = nr; xi = ni;
;                 if (FINAL) { BUl[jj * 132 + lane] = xr; BUl[jj * 132 + 64 + lane] = xi; }
;             }
	v_mfma_f32_16x16x32_bf16 v[136:139], v[96:99], v[0:3], 0
	v_mfma_f32_16x16x32_bf16 v[140:143], v[96:99], v[4:7], 0
	v_mfma_f32_16x16x32_bf16 v[144:147], v[96:99], v[8:11], 0
	v_mfma_f32_16x16x32_bf16 v[148:151], v[96:99], v[12:15], 0
	v_mfma_f32_16x16x32_bf16 v[152:155], v[96:99], v[16:19], 0
	v_mfma_f32_16x16x32_bf16 v[156:159], v[96:99], v[20:23], 0
	v_mfma_f32_16x16x32_bf16 v[160:163], v[96:99], v[24:27], 0
	v_mfma_f32_16x16x32_bf16 v[164:167], v[96:99], v[28:31], 0
	v_pk_mov_b32 v[232:233], v[168:169], v[184:185] op_sel:[0,0]
	v_pk_mov_b32 v[234:235], v[172:173], v[188:189] op_sel:[0,0]
	v_pk_mov_b32 v[244:245], v[176:177], v[192:193] op_sel:[0,0]
	v_pk_mov_b32 v[254:255], v[180:181], v[196:197] op_sel:[0,0]
	v_pk_fma_f32 v[232:233], v[32:33], v[200:201], v[232:233] op_sel_hi:[0,1,1]
	v_pk_fma_f32 v[234:235], v[34:35], v[202:203], v[234:235] op_sel_hi:[0,1,1]
	v_pk_fma_f32 v[244:245], v[36:37], v[204:205], v[244:245] op_sel_hi:[0,1,1]
	v_pk_fma_f32 v[254:255], v[38:39], v[206:207], v[254:255] op_sel_hi:[0,1,1]
	v_pk_fma_f32 v[200:201], v[32:33], v[200:201], v[232:233] op_sel:[1,1,0] op_sel_hi:[1,0,1] neg_lo:[1,0,0]
	v_pk_fma_f32 v[202:203], v[34:35], v[202:203], v[234:235] op_sel:[1,1,0] op_sel_hi:[1,0,1] neg_lo:[1,0,0]
	v_pk_fma_f32 v[204:205], v[36:37], v[204:205], v[244:245] op_sel:[1,1,0] op_sel_hi:[1,0,1] neg_lo:[1,0,0]
	v_pk_fma_f32 v[206:207], v[38:39], v[206:207], v[254:255] op_sel:[1,1,0] op_sel_hi:[1,0,1] neg_lo:[1,0,0]
	v_pk_mov_b32 v[232:233], v[168:169], v[184:185] op_sel:[1,1]
	v_pk_mov_b32 v[234:235], v[172:173], v[188:189] op_sel:[1,1]
	v_pk_mov_b32 v[244:245], v[176:177], v[192:193] op_sel:[1,1]
	v_pk_mov_b32 v[254:255], v[180:181], v[196:197] op_sel:[1,1]
	v_pk_fma_f32 v[232:233], v[32:33], v[200:201], v[232:233] op_sel_hi:[0,1,1]
	v_pk_fma_f32 v[234:235], v[34:35], v[202:203], v[234:235] op_sel_hi:[0,1,1]
	v_pk_fma_f32 v[244:245], v[36:37], v[204:205], v[244:245] op_sel_hi:[0,1,1]
	v_pk_fma_f32 v[254:255], v[38:39], v[206:207], v[254:255] op_sel_hi:[0,1,1]
	v_pk_fma_f32 v[200:201], v[32:33], v[200:201], v[232:233] op_sel:[1,1,0] op_sel_hi:[1,0,1] neg_lo:[1,0,0]
	v_pk_fma_f32 v[202:203], v[34:35], v[202:203], v[234:235] op_sel:[1,1,0] op_sel_hi:[1,0,1] neg_lo:[1,0,0]
	v_pk_fma_f32 v[204:205], v[36:37], v[204:205], v[244:245] op_sel:[1,1,0] op_sel_hi:[1,0,1] neg_lo:[1,0,0]
	v_pk_fma_f32 v[206:207], v[38:39], v[206:207], v[254:255] op_sel:[1,1,0] op_sel_hi:[1,0,1] neg_lo:[1,0,0]
	v_pk_mov_b32 v[232:233], v[170:171], v[186:187] op_sel:[0,0]
	v_pk_mov_b32 v[234:235], v[174:175], v[190:191] op_sel:[0,0]
	v_pk_mov_b32 v[244:245], v[178:179], v[194:195] op_sel:[0,0]
	v_pk_mov_b32 v[254:255], v[182:183], v[198:199] op_sel:[0,0]
	v_pk_fma_f32 v[232:233], v[32:33], v[200:201], v[232:233] op_sel_hi:[0,1,1]
	v_pk_fma_f32 v[234:235], v[34:35], v[202:203], v[234:235] op_sel_hi:[0,1,1]
	v_pk_fma_f32 v[244:245], v[36:37], v[204:205], v[244:245] op_sel_hi:[0,1,1]
	v_pk_fma_f32 v[254:255], v[38:39], v[206:207], v[254:255] op_sel_hi:[0,1,1]
	v_pk_fma_f32 v[200:201], v[32:33], v[200:201], v[232:233] op_sel:[1,1,0] op_sel_hi:[1,0,1] neg_lo:[1,0,0]
	v_pk_fma_f32 v[202:203], v[34:35], v[202:203], v[234:235] op_sel:[1,1,0] op_sel_hi:[1,0,1] neg_lo:[1,0,0]
	v_pk_fma_f32 v[204:205], v[36:37], v[204:205], v[244:245] op_sel:[1,1,0] op_sel_hi:[1,0,1] neg_lo:[1,0,0]
	v_pk_fma_f32 v[206:207], v[38:39], v[206:207], v[254:255] op_sel:[1,1,0] op_sel_hi:[1,0,1] neg_lo:[1,0,0]
	v_pk_mov_b32 v[232:233], v[170:171], v[186:187] op_sel:[1,1]
	v_pk_mov_b32 v[234:235], v[174:175], v[190:191] op_sel:[1,1]
	v_pk_mov_b32 v[244:245], v[178:179], v[194:195] op_sel:[1,1]
	v_pk_mov_b32 v[254:255], v[182:183], v[198:199] op_sel:[1,1]
	v_pk_fma_f32 v[232:233], v[32:33], v[200:201], v[232:233] op_sel_hi:[0,1,1]
	v_pk_fma_f32 v[234:235], v[34:35], v[202:203], v[234:235] op_sel_hi:[0,1,1]
	v_pk_fma_f32 v[244:245], v[36:37], v[204:205], v[244:245] op_sel_hi:[0,1,1]
	v_pk_fma_f32 v[254:255], v[38:39], v[206:207], v[254:255] op_sel_hi:[0,1,1]
	v_pk_fma_f32 v[200:201], v[32:33], v[200:201], v[232:233] op_sel:[1,1,0] op_sel_hi:[1,0,1] neg_lo:[1,0,0]
	v_pk_fma_f32 v[202:203], v[34:35], v[202:203], v[234:235] op_sel:[1,1,0] op_sel_hi:[1,0,1] neg_lo:[1,0,0]
	v_pk_fma_f32 v[204:205], v[36:37], v[204:205], v[244:245] op_sel:[1,1,0] op_sel_hi:[1,0,1] neg_lo:[1,0,0]
	v_pk_fma_f32 v[206:207], v[38:39], v[206:207], v[254:255] op_sel:[1,1,0] op_sel_hi:[1,0,1] neg_lo:[1,0,0]
	global_load_dwordx4 v[92:95], v238, s[20:21]
	v_add_u32_e32 v238, v238, v243
	s_waitcnt vmcnt(18)
; template <bool FINAL> __device__ __forceinline__ void phase_s5_scan(const Fr& F) {
;     ...
;             for (int sb = 0; sb < 4; ++sb) ua[sb] = lq < 2 ? *(const u32x4*)(U + ((size_t)bn * TB + tokof(s, cn * 64 + sb * 16 + l15)) * D + g * 16 + 8 * lq) : (u32x4){0u, 0u, 0u, 0u};
;             if (FINAL) { const float* e = E + ((size_t)(((s * 4 + bn) * 64 + g) * 68 + cn) * 64 + lane) * 2; e0 = e[0]; e1 = e[1]; }
;         }
; #pragma unroll
;         for (int sub = 0; sub < 4; ++sub) {
;             const bf16x8 A1 = __builtin_bit_cast(bf16x8, uc[sub]);
; #pragma unroll
;             for (int nt = 0; nt < 8; ++nt) {
;                 f32x4 acc = {0.f, 0.f, 0.f, 0.f};
;                 acc = __builtin_amdgcn_mfma_f32_16x16x32_bf16(A1, B1[nt], acc, 0, 0, 0);
; #pragma unroll
;                 for (int reg = 0; reg < 4; ++reg) BUl[(4 * lq + reg) * 132 + 16 * nt + l15] = acc[reg];
;             }
;             asm volatile("s_waitcnt lgkmcnt(0)" ::: "memory");
; #pragma unroll 4
;             for (int jj = 0; jj < 16; ++jj) {
;                 const float br_ = BUl[jj * 132 + lane], bi_ = BUl[jj * 132 + 64 + lane];
;                 const float nr = ar * xr - ai * xi + br_, ni = ar * xi + ai * xr + bi_; xr = nr; xi = ni;
;                 if (FINAL) { BUl[jj * 132 + lane] = xr; BUl[jj * 132 + 64 + lane] = xi; }
;             }
	v_mfma_f32_16x16x32_bf16 v[168:171], v[100:103], v[0:3], 0
	v_mfma_f32_16x16x32_bf16 v[172:175], v[100:103], v[4:7], 0
	v_mfma_f32_16x16x32_bf16 v[176:179], v[100:103], v[8:11], 0
	v_mfma_f32_16x16x32_bf16 v[180:183], v[100:103], v[12:15], 0
	v_mfma_f32_16x16x32_bf16 v[184:187], v[100:103], v[16:19], 0
	v_mfma_f32_16x16x32_bf16 v[188:191], v[100:103], v[20:23], 0
	v_mfma_f32_16x16x32_bf16 v[192:195], v[100:103], v[24:27], 0
	v_mfma_f32_16x16x32_bf16 v[196:199], v[100:103], v[28:31], 0
	v_pk_mov_b32 v[232:233], v[136:137], v[152:153] op_sel:[0,0]
	v_pk_mov_b32 v[234:235], v[140:141], v[156:157] op_sel:[0,0]
	v_pk_mov_b32 v[244:245], v[144:145], v[160:161] op_sel:[0,0]
	v_pk_mov_b32 v[254:255], v[148:149], v[164:165] op_sel:[0,0]
	v_pk_fma_f32 v[232:233], v[32:33], v[200:201], v[232:233] op_sel_hi:[0,1,1]
	v_pk_fma_f32 v[234:235], v[34:35], v[202:203], v[234:235] op_sel_hi:[0,1,1]
	v_pk_fma_f32 v[244:245], v[36:37], v[204:205], v[244:245] op_sel_hi:[0,1,1]
	v_pk_fma_f32 v[254:255], v[38:39], v[206:207], v[254:255] op_sel_hi:[0,1,1]
	v_pk_fma_f32 v[200:201], v[32:33], v[200:201], v[232:233] op_sel:[1,1,0] op_sel_hi:[1,0,1] neg_lo:[1,0,0]
	v_pk_fma_f32 v[202:203], v[34:35], v[202:203], v[234:235] op_sel:[1,1,0] op_sel_hi:[1,0,1] neg_lo:[1,0,0]
	v_pk_fma_f32 v[204:205], v[36:37], v[204:205], v[244:245] op_sel:[1,1,0] op_sel_hi:[1,0,1] neg_lo:[1,0,0]
	v_pk_fma_f32 v[206:207], v[38:39], v[206:207], v[254:255] op_sel:[1,1,0] op_sel_hi:[1,0,1] neg_lo:[1,0,0]
	v_pk_mov_b32 v[232:233], v[136:137], v[152:153] op_sel:[1,1]
	v_pk_mov_b32 v[234:235], v[140:141], v[156:157] op_sel:[1,1]
	v_pk_mov_b32 v[244:245], v[144:145], v[160:161] op_sel:[1,1]
	v_pk_mov_b32 v[254:255], v[148:149], v[164:165] op_sel:[1,1]
	v_pk_fma_f32 v[232:233], v[32:33], v[200:201], v[232:233] op_sel_hi:[0,1,1]
	v_pk_fma_f32 v[234:235], v[34:35], v[202:203], v[234:235] op_sel_hi:[0,1,1]
	v_pk_fma_f32 v[244:245], v[36:37], v[204:205], v[244:245] op_sel_hi:[0,1,1]
	v_pk_fma_f32 v[254:255], v[38:39], v[206:207], v[254:255] op_sel_hi:[0,1,1]
	v_pk_fma_f32 v[200:201], v[32:33], v[200:201], v[232:233] op_sel:[1,1,0] op_sel_hi:[1,0,1] neg_lo:[1,0,0]
	v_pk_fma_f32 v[202:203], v[34:35], v[202:203], v[234:235] op_sel:[1,1,0] op_sel_hi:[1,0,1] neg_lo:[1,0,0]
	v_pk_fma_f32 v[204:205], v[36:37], v[204:205], v[244:245] op_sel:[1,1,0] op_sel_hi:[1,0,1] neg_lo:[1,0,0]
	v_pk_fma_f32 v[206:207], v[38:39], v[206:207], v[254:255] op_sel:[1,1,0] op_sel_hi:[1,0,1] neg_lo:[1,0,0]
	v_pk_mov_b32 v[232:233], v[138:139], v[154:155] op_sel:[0,0]
	v_pk_mov_b32 v[234:235], v[142:143], v[158:159] op_sel:[0,0]
	v_pk_mov_b32 v[244:245], v[146:147], v[162:163] op_sel:[0,0]
	v_pk_mov_b32 v[254:255], v[150:151], v[166:167] op_sel:[0,0]
	v_pk_fma_f32 v[232:233], v[32:33], v[200:201], v[232:233] op_sel_hi:[0,1,1]
	v_pk_fma_f32 v[234:235], v[34:35], v[202:203], v[234:235] op_sel_hi:[0,1,1]
	v_pk_fma_f32 v[244:245], v[36:37], v[204:205], v[244:245] op_sel_hi:[0,1,1]
	v_pk_fma_f32 v[254:255], v[38:39], v[206:207], v[254:255] op_sel_hi:[0,1,1]
	v_pk_fma_f32 v[200:201], v[32:33], v[200:201], v[232:233] op_sel:[1,1,0] op_sel_hi:[1,0,1] neg_lo:[1,0,0]
	v_pk_fma_f32 v[202:203], v[34:35], v[202:203], v[234:235] op_sel:[1,1,0] op_sel_hi:[1,0,1] neg_lo:[1,0,0]
	v_pk_fma_f32 v[204:205], v[36:37], v[204:205], v[244:245] op_sel:[1,1,0] op_sel_hi:[1,0,1] neg_lo:[1,0,0]
	v_pk_fma_f32 v[206:207], v[38:39], v[206:207], v[254:255] op_sel:[1,1,0] op_sel_hi:[1,0,1] neg_lo:[1,0,0]
	v_pk_mov_b32 v[232:233], v[138:139], v[154:155] op_sel:[1,1]
	v_pk_mov_b32 v[234:235], v[142:143], v[158:159] op_sel:[1,1]
	v_pk_mov_b32 v[244:245], v[146:147], v[162:163] op_sel:[1,1]
	v_pk_mov_b32 v[254:255], v[150:151], v[166:167] op_sel:[1,1]
	v_pk_fma_f32 v[232:233], v[32:33], v[200:201], v[232:233] op_sel_hi:[0,1,1]
	v_pk_fma_f32 v[234:235], v[34:35], v[202:203], v[234:235] op_sel_hi:[0,1,1]
	v_pk_fma_f32 v[244:245], v[36:37], v[204:205], v[244:245] op_sel_hi:[0,1,1]
	v_pk_fma_f32 v[254:255], v[38:39], v[206:207], v[254:255] op_sel_hi:[0,1,1]
	v_pk_fma_f32 v[200:201], v[32:33], v[200:201], v[232:233] op_sel:[1,1,0] op_sel_hi:[1,0,1] neg_lo:[1,0,0]
	v_pk_fma_f32 v[202:203], v[34:35], v[202:203], v[234:235] op_sel:[1,1,0] op_sel_hi:[1,0,1] neg_lo:[1,0,0]
	v_pk_fma_f32 v[204:205], v[36:37], v[204:205], v[244:245] op_sel:[1,1,0] op_sel_hi:[1,0,1] neg_lo:[1,0,0]
	v_pk_fma_f32 v[206:207], v[38:39], v[206:207], v[254:255] op_sel:[1,1,0] op_sel_hi:[1,0,1] neg_lo:[1,0,0]
	global_load_dwordx4 v[96:99], v238, s[20:21]
	v_add_u32_e32 v238, v238, v243
	s_waitcnt vmcnt(18)
; template <bool FINAL> __device__ __forceinline__ void phase_s5_scan(const Fr& F) {
;     ...
;             for (int sb = 0; sb < 4; ++sb) ua[sb] = lq < 2 ? *(const u32x4*)(U + ((size_t)bn * TB + tokof(s, cn * 64 + sb * 16 + l15)) * D + g * 16 + 8 * lq) : (u32x4){0u, 0u, 0u, 0u};
;             if (FINAL) { const float* e = E + ((size_t)(((s * 4 + bn) * 64 + g) * 68 + cn) * 64 + lane) * 2; e0 = e[0]; e1 = e[1]; }
;         }
; #pragma unroll
;         for (int sub = 0; sub < 4; ++sub) {
;             const bf16x8 A1 = __builtin_bit_cast(bf16x8, uc[sub]);
; #pragma unroll
;             for (int nt = 0; nt < 8; ++nt) {
;                 f32x4 acc = {0.f, 0.f, 0.f, 0.f};
;                 acc = __builtin_amdgcn_mfma_f32_16x16x32_bf16(A1, B1[nt], acc, 0, 0, 0);
; #pragma unroll
;                 for (int reg = 0; reg < 4; ++reg) BUl[(4 * lq + reg) * 132 + 16 * nt + l15] = acc[reg];
;             }
;             asm volatile("s_waitcnt lgkmcnt(0)" ::: "memory");
; #pragma unroll 4
;             for (int jj = 0; jj < 16; ++jj) {
;                 const float br_ = BUl[jj * 132 + lane], bi_ = BUl[jj * 132 + 64 + lane];
;                 const float nr = ar * xr - ai * xi + br_, ni = ar * xi + ai * xr + bi_; xr = nr; xi = ni;
;                 if (FINAL) { BUl[jj * 132 + lane] = xr; BUl[jj * 132 + 64 + lane] = xi; }
;             }
	v_mfma_f32_16x16x32_bf16 v[136:139], v[104:107], v[0:3], 0
	v_mfma_f32_16x16x32_bf16 v[140:143], v[104:107], v[4:7], 0
	v_mfma_f32_16x16x32_bf16 v[144:147], v[104:107], v[8:11], 0
	v_mfma_f32_16x16x32_bf16 v[148:151], v[104:107], v[12:15], 0
	v_mfma_f32_16x16x32_bf16 v[152:155], v[104:107], v[16:19], 0
	v_mfma_f32_16x16x32_bf16 v[156:159], v[104:107], v[20:23], 0
	v_mfma_f32_16x16x32_bf16 v[160:163], v[104:107], v[24:27], 0
	v_mfma_f32_16x16x32_bf16 v[164:167], v[104:107], v[28:31], 0
	v_pk_mov_b32 v[232:233], v[168:169], v[184:185] op_sel:[0,0]
	v_pk_mov_b32 v[234:235], v[172:173], v[188:189] op_sel:[0,0]
	v_pk_mov_b32 v[244:245], v[176:177], v[192:193] op_sel:[0,0]
	v_pk_mov_b32 v[254:255], v[180:181], v[196:197] op_sel:[0,0]
	v_pk_fma_f32 v[232:233], v[32:33], v[200:201], v[232:233] op_sel_hi:[0,1,1]
	v_pk_fma_f32 v[234:235], v[34:35], v[202:203], v[234:235] op_sel_hi:[0,1,1]
	v_pk_fma_f32 v[244:245], v[36:37], v[204:205], v[244:245] op_sel_hi:[0,1,1]
	v_pk_fma_f32 v[254:255], v[38:39], v[206:207], v[254:255] op_sel_hi:[0,1,1]
	v_pk_fma_f32 v[200:201], v[32:33], v[200:201], v[232:233] op_sel:[1,1,0] op_sel_hi:[1,0,1] neg_lo:[1,0,0]
	v_pk_fma_f32 v[202:203], v[34:35], v[202:203], v[234:235] op_sel:[1,1,0] op_sel_hi:[1,0,1] neg_lo:[1,0,0]
	v_pk_fma_f32 v[204:205], v[36:37], v[204:205], v[244:245] op_sel:[1,1,0] op_sel_hi:[1,0,1] neg_lo:[1,0,0]
	v_pk_fma_f32 v[206:207], v[38:39], v[206:207], v[254:255] op_sel:[1,1,0] op_sel_hi:[1,0,1] neg_lo:[1,0,0]
	v_pk_mov_b32 v[232:233], v[168:169], v[184:185] op_sel:[1,1]
	v_pk_mov_b32 v[234:235], v[172:173], v[188:189] op_sel:[1,1]
	v_pk_mov_b32 v[244:245], v[176:177], v[192:193] op_sel:[1,1]
	v_pk_mov_b32 v[254:255], v[180:181], v[196:197] op_sel:[1,1]
	v_pk_fma_f32 v[232:233], v[32:33], v[200:201], v[232:233] op_sel_hi:[0,1,1]
	v_pk_fma_f32 v[234:235], v[34:35], v[202:203], v[234:235] op_sel_hi:[0,1,1]
	v_pk_fma_f32 v[244:245], v[36:37], v[204:205], v[244:245] op_sel_hi:[0,1,1]
	v_pk_fma_f32 v[254:255], v[38:39], v[206:207], v[254:255] op_sel_hi:[0,1,1]
	v_pk_fma_f32 v[200:201], v[32:33], v[200:201], v[232:233] op_sel:[1,1,0] op_sel_hi:[1,0,1] neg_lo:[1,0,0]
	v_pk_fma_f32 v[202:203], v[34:35], v[202:203], v[234:235] op_sel:[1,1,0] op_sel_hi:[1,0,1] neg_lo:[1,0,0]
	v_pk_fma_f32 v[204:205], v[36:37], v[204:205], v[244:245] op_sel:[1,1,0] op_sel_hi:[1,0,1] neg_lo:[1,0,0]
	v_pk_fma_f32 v[206:207], v[38:39], v[206:207], v[254:255] op_sel:[1,1,0] op_sel_hi:[1,0,1] neg_lo:[1,0,0]
	v_pk_mov_b32 v[232:233], v[170:171], v[186:187] op_sel:[0,0]
	v_pk_mov_b32 v[234:235], v[174:175], v[190:191] op_sel:[0,0]
	v_pk_mov_b32 v[244:245], v[178:179], v[194:195] op_sel:[0,0]
	v_pk_mov_b32 v[254:255], v[182:183], v[198:199] op_sel:[0,0]
	v_pk_fma_f32 v[232:233], v[32:33], v[200:201], v[232:233] op_sel_hi:[0,1,1]
	v_pk_fma_f32 v[234:235], v[34:35], v[202:203], v[234:235] op_sel_hi:[0,1,1]
	v_pk_fma_f32 v[244:245], v[36:37], v[204:205], v[244:245] op_sel_hi:[0,1,1]
	v_pk_fma_f32 v[254:255], v[38:39], v[206:207], v[254:255] op_sel_hi:[0,1,1]
	v_pk_fma_f32 v[200:201], v[32:33], v[200:201], v[232:233] op_sel:[1,1,0] op_sel_hi:[1,0,1] neg_lo:[1,0,0]
	v_pk_fma_f32 v[202:203], v[34:35], v[202:203], v[234:235] op_sel:[1,1,0] op_sel_hi:[1,0,1] neg_lo:[1,0,0]
	v_pk_fma_f32 v[204:205], v[36:37], v[204:205], v[244:245] op_sel:[1,1,0] op_sel_hi:[1,0,1] neg_lo:[1,0,0]
	v_pk_fma_f32 v[206:207], v[38:39], v[206:207], v[254:255] op_sel:[1,1,0] op_sel_hi:[1,0,1] neg_lo:[1,0,0]
	v_pk_mov_b32 v[232:233], v[170:171], v[186:187] op_sel:[1,1]
	v_pk_mov_b32 v[234:235], v[174:175], v[190:191] op_sel:[1,1]
	v_pk_mov_b32 v[244:245], v[178:179], v[194:195] op_sel:[1,1]
	v_pk_mov_b32 v[254:255], v[182:183], v[198:199] op_sel:[1,1]
	v_pk_fma_f32 v[232:233], v[32:33], v[200:201], v[232:233] op_sel_hi:[0,1,1]
	v_pk_fma_f32 v[234:235], v[34:35], v[202:203], v[234:235] op_sel_hi:[0,1,1]
	v_pk_fma_f32 v[244:245], v[36:37], v[204:205], v[244:245] op_sel_hi:[0,1,1]
	v_pk_fma_f32 v[254:255], v[38:39], v[206:207], v[254:255] op_sel_hi:[0,1,1]
	v_pk_fma_f32 v[200:201], v[32:33], v[200:201], v[232:233] op_sel:[1,1,0] op_sel_hi:[1,0,1] neg_lo:[1,0,0]
	v_pk_fma_f32 v[202:203], v[34:35], v[202:203], v[234:235] op_sel:[1,1,0] op_sel_hi:[1,0,1] neg_lo:[1,0,0]
	v_pk_fma_f32 v[204:205], v[36:37], v[204:205], v[244:245] op_sel:[1,1,0] op_sel_hi:[1,0,1] neg_lo:[1,0,0]
	v_pk_fma_f32 v[206:207], v[38:39], v[206:207], v[254:255] op_sel:[1,1,0] op_sel_hi:[1,0,1] neg_lo:[1,0,0]
	global_load_dwordx4 v[100:103], v238, s[20:21]
	v_add_u32_e32 v238, v238, v243
	s_waitcnt vmcnt(18)
; template <bool FINAL> __device__ __forceinline__ void phase_s5_scan(const Fr& F) {
;     ...
;             for (int sb = 0; sb < 4; ++sb) ua[sb] = lq < 2 ? *(const u32x4*)(U + ((size_t)bn * TB + tokof(s, cn * 64 + sb * 16 + l15)) * D + g * 16 + 8 * lq) : (u32x4){0u, 0u, 0u, 0u};
;             if (FINAL) { const float* e = E + ((size_t)(((s * 4 + bn) * 64 + g) * 68 + cn) * 64 + lane) * 2; e0 = e[0]; e1 = e[1]; }
;         }
; #pragma unroll
;         for (int sub = 0; sub < 4; ++sub) {
;             const bf16x8 A1 = __builtin_bit_cast(bf16x8, uc[sub]);
; #pragma unroll
;             for (int nt = 0; nt < 8; ++nt) {
;                 f32x4 acc = {0.f, 0.f, 0.f, 0.f};
;                 acc = __builtin_amdgcn_mfma_f32_16x16x32_bf16(A1, B1[nt], acc, 0, 0, 0);
; #pragma unroll
;                 for (int reg = 0; reg < 4; ++reg) BUl[(4 * lq + reg) * 132 + 16 * nt + l15] = acc[reg];
;             }
;             asm volatile("s_waitcnt lgkmcnt(0)" ::: "memory");
; #pragma unroll 4
;             for (int jj = 0; jj < 16; ++jj) {
;                 const float br_ = BUl[jj * 132 + lane], bi_ = BUl[jj * 132 + 64 + lane];
;                 const float nr = ar * xr - ai * xi + br_, ni = ar * xi + ai * xr + bi_; xr = nr; xi = ni;
;                 if (FINAL) { BUl[jj * 132 + lane] = xr; BUl[jj * 132 + 64 + lane] = xi; }
;             }
	v_mfma_f32_16x16x32_bf16 v[168:171], v[108:111], v[0:3], 0
	v_mfma_f32_16x16x32_bf16 v[172:175], v[108:111], v[4:7], 0
	v_mfma_f32_16x16x32_bf16 v[176:179], v[108:111], v[8:11], 0
	v_mfma_f32_16x16x32_bf16 v[180:183], v[108:111], v[12:15], 0
	v_mfma_f32_16x16x32_bf16 v[184:187], v[108:111], v[16:19], 0
	v_mfma_f32_16x16x32_bf16 v[188:191], v[108:111], v[20:23], 0
	v_mfma_f32_16x16x32_bf16 v[192:195], v[108:111], v[24:27], 0
	v_mfma_f32_16x16x32_bf16 v[196:199], v[108:111], v[28:31], 0
	v_pk_mov_b32 v[232:233], v[136:137], v[152:153] op_sel:[0,0]
	v_pk_mov_b32 v[234:235], v[140:141], v[156:157] op_sel:[0,0]
	v_pk_mov_b32 v[244:245], v[144:145], v[160:161] op_sel:[0,0]
	v_pk_mov_b32 v[254:255], v[148:149], v[164:165] op_sel:[0,0]
	v_pk_fma_f32 v[232:233], v[32:33], v[200:201], v[232:233] op_sel_hi:[0,1,1]
	v_pk_fma_f32 v[234:235], v[34:35], v[202:203], v[234:235] op_sel_hi:[0,1,1]
	v_pk_fma_f32 v[244:245], v[36:37], v[204:205], v[244:245] op_sel_hi:[0,1,1]
	v_pk_fma_f32 v[254:255], v[38:39], v[206:207], v[254:255] op_sel_hi:[0,1,1]
	v_pk_fma_f32 v[200:201], v[32:33], v[200:201], v[232:233] op_sel:[1,1,0] op_sel_hi:[1,0,1] neg_lo:[1,0,0]
	v_pk_fma_f32 v[202:203], v[34:35], v[202:203], v[234:235] op_sel:[1,1,0] op_sel_hi:[1,0,1] neg_lo:[1,0,0]
	v_pk_fma_f32 v[204:205], v[36:37], v[204:205], v[244:245] op_sel:[1,1,0] op_sel_hi:[1,0,1] neg_lo:[1,0,0]
	v_pk_fma_f32 v[206:207], v[38:39], v[206:207], v[254:255] op_sel:[1,1,0] op_sel_hi:[1,0,1] neg_lo:[1,0,0]
	v_pk_mov_b32 v[232:233], v[136:137], v[152:153] op_sel:[1,1]
	v_pk_mov_b32 v[234:235], v[140:141], v[156:157] op_sel:[1,1]
	v_pk_mov_b32 v[244:245], v[144:145], v[160:161] op_sel:[1,1]
	v_pk_mov_b32 v[254:255], v[148:149], v[164:165] op_sel:[1,1]
	v_pk_fma_f32 v[232:233], v[32:33], v[200:201], v[232:233] op_sel_hi:[0,1,1]
	v_pk_fma_f32 v[234:235], v[34:35], v[202:203], v[234:235] op_sel_hi:[0,1,1]
	v_pk_fma_f32 v[244:245], v[36:37], v[204:205], v[244:245] op_sel_hi:[0,1,1]
	v_pk_fma_f32 v[254:255], v[38:39], v[206:207], v[254:255] op_sel_hi:[0,1,1]
	v_pk_fma_f32 v[200:201], v[32:33], v[200:201], v[232:233] op_sel:[1,1,0] op_sel_hi:[1,0,1] neg_lo:[1,0,0]
	v_pk_fma_f32 v[202:203], v[34:35], v[202:203], v[234:235] op_sel:[1,1,0] op_sel_hi:[1,0,1] neg_lo:[1,0,0]
	v_pk_fma_f32 v[204:205], v[36:37], v[204:205], v[244:245] op_sel:[1,1,0] op_sel_hi:[1,0,1] neg_lo:[1,0,0]
	v_pk_fma_f32 v[206:207], v[38:39], v[206:207], v[254:255] op_sel:[1,1,0] op_sel_hi:[1,0,1] neg_lo:[1,0,0]
	v_pk_mov_b32 v[232:233], v[138:139], v[154:155] op_sel:[0,0]
	v_pk_mov_b32 v[234:235], v[142:143], v[158:159] op_sel:[0,0]
	v_pk_mov_b32 v[244:245], v[146:147], v[162:163] op_sel:[0,0]
	v_pk_mov_b32 v[254:255], v[150:151], v[166:167] op_sel:[0,0]
	v_pk_fma_f32 v[232:233], v[32:33], v[200:201], v[232:233] op_sel_hi:[0,1,1]
	v_pk_fma_f32 v[234:235], v[34:35], v[202:203], v[234:235] op_sel_hi:[0,1,1]
	v_pk_fma_f32 v[244:245], v[36:37], v[204:205], v[244:245] op_sel_hi:[0,1,1]
	v_pk_fma_f32 v[254:255], v[38:39], v[206:207], v[254:255] op_sel_hi:[0,1,1]
	v_pk_fma_f32 v[200:201], v[32:33], v[200:201], v[232:233] op_sel:[1,1,0] op_sel_hi:[1,0,1] neg_lo:[1,0,0]
	v_pk_fma_f32 v[202:203], v[34:35], v[202:203], v[234:235] op_sel:[1,1,0] op_sel_hi:[1,0,1] neg_lo:[1,0,0]
	v_pk_fma_f32 v[204:205], v[36:37], v[204:205], v[244:245] op_sel:[1,1,0] op_sel_hi:[1,0,1] neg_lo:[1,0,0]
	v_pk_fma_f32 v[206:207], v[38:39], v[206:207], v[254:255] op_sel:[1,1,0] op_sel_hi:[1,0,1] neg_lo:[1,0,0]
	v_pk_mov_b32 v[232:233], v[138:139], v[154:155] op_sel:[1,1]
	v_pk_mov_b32 v[234:235], v[142:143], v[158:159] op_sel:[1,1]
	v_pk_mov_b32 v[244:245], v[146:147], v[162:163] op_sel:[1,1]
	v_pk_mov_b32 v[254:255], v[150:151], v[166:167] op_sel:[1,1]
	v_pk_fma_f32 v[232:233], v[32:33], v[200:201], v[232:233] op_sel_hi:[0,1,1]
	v_pk_fma_f32 v[234:235], v[34:35], v[202:203], v[234:235] op_sel_hi:[0,1,1]
	v_pk_fma_f32 v[244:245], v[36:37], v[204:205], v[244:245] op_sel_hi:[0,1,1]
	v_pk_fma_f32 v[254:255], v[38:39], v[206:207], v[254:255] op_sel_hi:[0,1,1]
	v_pk_fma_f32 v[200:201], v[32:33], v[200:201], v[232:233] op_sel:[1,1,0] op_sel_hi:[1,0,1] neg_lo:[1,0,0]
	v_pk_fma_f32 v[202:203], v[34:35], v[202:203], v[234:235] op_sel:[1,1,0] op_sel_hi:[1,0,1] neg_lo:[1,0,0]
	v_pk_fma_f32 v[204:205], v[36:37], v[204:205], v[244:245] op_sel:[1,1,0] op_sel_hi:[1,0,1] neg_lo:[1,0,0]
	v_pk_fma_f32 v[206:207], v[38:39], v[206:207], v[254:255] op_sel:[1,1,0] op_sel_hi:[1,0,1] neg_lo:[1,0,0]
	global_load_dwordx4 v[104:107], v238, s[20:21]
	v_add_u32_e32 v238, v238, v243
	s_waitcnt vmcnt(18)
; template <bool FINAL> __device__ __forceinline__ void phase_s5_scan(const Fr& F) {
;     ...
;             for (int sb = 0; sb < 4; ++sb) ua[sb] = lq < 2 ? *(const u32x4*)(U + ((size_t)bn * TB + tokof(s, cn * 64 + sb * 16 + l15)) * D + g * 16 + 8 * lq) : (u32x4){0u, 0u, 0u, 0u};
;             if (FINAL) { const float* e = E + ((size_t)(((s * 4 + bn) * 64 + g) * 68 + cn) * 64 + lane) * 2; e0 = e[0]; e1 = e[1]; }
;         }
; #pragma unroll
;         for (int sub = 0; sub < 4; ++sub) {
;             const bf16x8 A1 = __builtin_bit_cast(bf16x8, uc[sub]);
; #pragma unroll
;             for (int nt = 0; nt < 8; ++nt) {
;                 f32x4 acc = {0.f, 0.f, 0.f, 0.f};
;                 acc = __builtin_amdgcn_mfma_f32_16x16x32_bf16(A1, B1[nt], acc, 0, 0, 0);
; #pragma unroll
;                 for (int reg = 0; reg < 4; ++reg) BUl[(4 * lq + reg) * 132 + 16 * nt + l15] = acc[reg];
;             }
;             asm volatile("s_waitcnt lgkmcnt(0)" ::: "memory");
; #pragma unroll 4
;             for (int jj = 0; jj < 16; ++jj) {
;                 const float br_ = BUl[jj * 132 + lane], bi_ = BUl[jj * 132 + 64 + lane];
;                 const float nr = ar * xr - ai * xi + br_, ni = ar * xi + ai * xr + bi_; xr = nr; xi = ni;
;                 if (FINAL) { BUl[jj * 132 + lane] = xr; BUl[jj * 132 + 64 + lane] = xi; }
;             }
	v_mfma_f32_16x16x32_bf16 v[136:139], v[112:115], v[0:3], 0
	v_mfma_f32_16x16x32_bf16 v[140:143], v[112:115], v[4:7], 0
	v_mfma_f32_16x16x32_bf16 v[144:147], v[112:115], v[8:11], 0
	v_mfma_f32_16x16x32_bf16 v[148:151], v[112:115], v[12:15], 0
	v_mfma_f32_16x16x32_bf16 v[152:155], v[112:115], v[16:19], 0
	v_mfma_f32_16x16x32_bf16 v[156:159], v[112:115], v[20:23], 0
	v_mfma_f32_16x16x32_bf16 v[160:163], v[112:115], v[24:27], 0
	v_mfma_f32_16x16x32_bf16 v[164:167], v[112:115], v[28:31], 0
	v_pk_mov_b32 v[232:233], v[168:169], v[184:185] op_sel:[0,0]
	v_pk_mov_b32 v[234:235], v[172:173], v[188:189] op_sel:[0,0]
	v_pk_mov_b32 v[244:245], v[176:177], v[192:193] op_sel:[0,0]
	v_pk_mov_b32 v[254:255], v[180:181], v[196:197] op_sel:[0,0]
	v_pk_fma_f32 v[232:233], v[32:33], v[200:201], v[232:233] op_sel_hi:[0,1,1]
	v_pk_fma_f32 v[234:235], v[34:35], v[202:203], v[234:235] op_sel_hi:[0,1,1]
	v_pk_fma_f32 v[244:245], v[36:37], v[204:205], v[244:245] op_sel_hi:[0,1,1]
	v_pk_fma_f32 v[254:255], v[38:39], v[206:207], v[254:255] op_sel_hi:[0,1,1]
	v_pk_fma_f32 v[200:201], v[32:33], v[200:201], v[232:233] op_sel:[1,1,0] op_sel_hi:[1,0,1] neg_lo:[1,0,0]
	v_pk_fma_f32 v[202:203], v[34:35], v[202:203], v[234:235] op_sel:[1,1,0] op_sel_hi:[1,0,1] neg_lo:[1,0,0]
	v_pk_fma_f32 v[204:205], v[36:37], v[204:205], v[244:245] op_sel:[1,1,0] op_sel_hi:[1,0,1] neg_lo:[1,0,0]
	v_pk_fma_f32 v[206:207], v[38:39], v[206:207], v[254:255] op_sel:[1,1,0] op_sel_hi:[1,0,1] neg_lo:[1,0,0]
	v_pk_mov_b32 v[232:233], v[168:169], v[184:185] op_sel:[1,1]
	v_pk_mov_b32 v[234:235], v[172:173], v[188:189] op_sel:[1,1]
	v_pk_mov_b32 v[244:245], v[176:177], v[192:193] op_sel:[1,1]
	v_pk_mov_b32 v[254:255], v[180:181], v[196:197] op_sel:[1,1]
	v_pk_fma_f32 v[232:233], v[32:33], v[200:201], v[232:233] op_sel_hi:[0,1,1]
	v_pk_fma_f32 v[234:235], v[34:35], v[202:203], v[234:235] op_sel_hi:[0,1,1]
	v_pk_fma_f32 v[244:245], v[36:37], v[204:205], v[244:245] op_sel_hi:[0,1,1]
	v_pk_fma_f32 v[254:255], v[38:39], v[206:207], v[254:255] op_sel_hi:[0,1,1]
	v_pk_fma_f32 v[200:201], v[32:33], v[200:201], v[232:233] op_sel:[1,1,0] op_sel_hi:[1,0,1] neg_lo:[1,0,0]
	v_pk_fma_f32 v[202:203], v[34:35], v[202:203], v[234:235] op_sel:[1,1,0] op_sel_hi:[1,0,1] neg_lo:[1,0,0]
	v_pk_fma_f32 v[204:205], v[36:37], v[204:205], v[244:245] op_sel:[1,1,0] op_sel_hi:[1,0,1] neg_lo:[1,0,0]
	v_pk_fma_f32 v[206:207], v[38:39], v[206:207], v[254:255] op_sel:[1,1,0] op_sel_hi:[1,0,1] neg_lo:[1,0,0]
	v_pk_mov_b32 v[232:233], v[170:171], v[186:187] op_sel:[0,0]
	v_pk_mov_b32 v[234:235], v[174:175], v[190:191] op_sel:[0,0]
	v_pk_mov_b32 v[244:245], v[178:179], v[194:195] op_sel:[0,0]
	v_pk_mov_b32 v[254:255], v[182:183], v[198:199] op_sel:[0,0]
	v_pk_fma_f32 v[232:233], v[32:33], v[200:201], v[232:233] op_sel_hi:[0,1,1]
	v_pk_fma_f32 v[234:235], v[34:35], v[202:203], v[234:235] op_sel_hi:[0,1,1]
	v_pk_fma_f32 v[244:245], v[36:37], v[204:205], v[244:245] op_sel_hi:[0,1,1]
	v_pk_fma_f32 v[254:255], v[38:39], v[206:207], v[254:255] op_sel_hi:[0,1,1]
	v_pk_fma_f32 v[200:201], v[32:33], v[200:201], v[232:233] op_sel:[1,1,0] op_sel_hi:[1,0,1] neg_lo:[1,0,0]
	v_pk_fma_f32 v[202:203], v[34:35], v[202:203], v[234:235] op_sel:[1,1,0] op_sel_hi:[1,0,1] neg_lo:[1,0,0]
	v_pk_fma_f32 v[204:205], v[36:37], v[204:205], v[244:245] op_sel:[1,1,0] op_sel_hi:[1,0,1] neg_lo:[1,0,0]
	v_pk_fma_f32 v[206:207], v[38:39], v[206:207], v[254:255] op_sel:[1,1,0] op_sel_hi:[1,0,1] neg_lo:[1,0,0]
	v_pk_mov_b32 v[232:233], v[170:171], v[186:187] op_sel:[1,1]
	v_pk_mov_b32 v[234:235], v[174:175], v[190:191] op_sel:[1,1]
	v_pk_mov_b32 v[244:245], v[178:179], v[194:195] op_sel:[1,1]
	v_pk_mov_b32 v[254:255], v[182:183], v[198:199] op_sel:[1,1]
	v_pk_fma_f32 v[232:233], v[32:33], v[200:201], v[232:233] op_sel_hi:[0,1,1]
	v_pk_fma_f32 v[234:235], v[34:35], v[202:203], v[234:235] op_sel_hi:[0,1,1]
	v_pk_fma_f32 v[244:245], v[36:37], v[204:205], v[244:245] op_sel_hi:[0,1,1]
	v_pk_fma_f32 v[254:255], v[38:39], v[206:207], v[254:255] op_sel_hi:[0,1,1]
	v_pk_fma_f32 v[200:201], v[32:33], v[200:201], v[232:233] op_sel:[1,1,0] op_sel_hi:[1,0,1] neg_lo:[1,0,0]
	v_pk_fma_f32 v[202:203], v[34:35], v[202:203], v[234:235] op_sel:[1,1,0] op_sel_hi:[1,0,1] neg_lo:[1,0,0]
	v_pk_fma_f32 v[204:205], v[36:37], v[204:205], v[244:245] op_sel:[1,1,0] op_sel_hi:[1,0,1] neg_lo:[1,0,0]
	v_pk_fma_f32 v[206:207], v[38:39], v[206:207], v[254:255] op_sel:[1,1,0] op_sel_hi:[1,0,1] neg_lo:[1,0,0]
	global_load_dwordx4 v[108:111], v238, s[20:21]
	v_add_u32_e32 v238, v238, v243
	s_waitcnt vmcnt(18)
; template <bool FINAL> __device__ __forceinline__ void phase_s5_scan(const Fr& F) {
;     ...
; #pragma unroll
;         for (int sub = 0; sub < 4; ++sub) {
;             const bf16x8 A1 = __builtin_bit_cast(bf16x8, uc[sub]);
; #pragma unroll
;             for (int nt = 0; nt < 8; ++nt) {
;                 f32x4 acc = {0.f, 0.f, 0.f, 0.f};
;                 acc = __builtin_amdgcn_mfma_f32_16x16x32_bf16(A1, B1[nt], acc, 0, 0, 0);
; #pragma unroll
;                 for (int reg = 0; reg < 4; ++reg) BUl[(4 * lq + reg) * 132 + 16 * nt + l15] = acc[reg];
;             }
;             asm volatile("s_waitcnt lgkmcnt(0)" ::: "memory");
; #pragma unroll 4
;             for (int jj = 0; jj < 16; ++jj) {
;                 const float br_ = BUl[jj * 132 + lane], bi_ = BUl[jj * 132 + 64 + lane];
;                 const float nr = ar * xr - ai * xi + br_, ni = ar * xi + ai * xr + bi_; xr = nr; xi = ni;
;                 if (FINAL) { BUl[jj * 132 + lane] = xr; BUl[jj * 132 + 64 + lane] = xi; }
;             }
	v_mfma_f32_16x16x32_bf16 v[168:171], v[116:119], v[0:3], 0
	v_mfma_f32_16x16x32_bf16 v[172:175], v[116:119], v[4:7], 0
	v_mfma_f32_16x16x32_bf16 v[176:179], v[116:119], v[8:11], 0
	v_mfma_f32_16x16x32_bf16 v[180:183], v[116:119], v[12:15], 0
	v_mfma_f32_16x16x32_bf16 v[184:187], v[116:119], v[16:19], 0
	v_mfma_f32_16x16x32_bf16 v[188:191], v[116:119], v[20:23], 0
	v_mfma_f32_16x16x32_bf16 v[192:195], v[116:119], v[24:27], 0
	v_mfma_f32_16x16x32_bf16 v[196:199], v[116:119], v[28:31], 0
	v_pk_mov_b32 v[232:233], v[136:137], v[152:153] op_sel:[0,0]
	v_pk_mov_b32 v[234:235], v[140:141], v[156:157] op_sel:[0,0]
	v_pk_mov_b32 v[244:245], v[144:145], v[160:161] op_sel:[0,0]
	v_pk_mov_b32 v[254:255], v[148:149], v[164:165] op_sel:[0,0]
	v_pk_fma_f32 v[232:233], v[32:33], v[200:201], v[232:233] op_sel_hi:[0,1,1]
	v_pk_fma_f32 v[234:235], v[34:35], v[202:203], v[234:235] op_sel_hi:[0,1,1]
	v_pk_fma_f32 v[244:245], v[36:37], v[204:205], v[244:245] op_sel_hi:[0,1,1]
	v_pk_fma_f32 v[254:255], v[38:39], v[206:207], v[254:255] op_sel_hi:[0,1,1]
	v_pk_fma_f32 v[200:201], v[32:33], v[200:201], v[232:233] op_sel:[1,1,0] op_sel_hi:[1,0,1] neg_lo:[1,0,0]
	v_pk_fma_f32 v[202:203], v[34:35], v[202:203], v[234:235] op_sel:[1,1,0] op_sel_hi:[1,0,1] neg_lo:[1,0,0]
	v_pk_fma_f32 v[204:205], v[36:37], v[204:205], v[244:245] op_sel:[1,1,0] op_sel_hi:[1,0,1] neg_lo:[1,0,0]
	v_pk_fma_f32 v[206:207], v[38:39], v[206:207], v[254:255] op_sel:[1,1,0] op_sel_hi:[1,0,1] neg_lo:[1,0,0]
	v_pk_mov_b32 v[232:233], v[136:137], v[152:153] op_sel:[1,1]
	v_pk_mov_b32 v[234:235], v[140:141], v[156:157] op_sel:[1,1]
	v_pk_mov_b32 v[244:245], v[144:145], v[160:161] op_sel:[1,1]
	v_pk_mov_b32 v[254:255], v[148:149], v[164:165] op_sel:[1,1]
	v_pk_fma_f32 v[232:233], v[32:33], v[200:201], v[232:233] op_sel_hi:[0,1,1]
	v_pk_fma_f32 v[234:235], v[34:35], v[202:203], v[234:235] op_sel_hi:[0,1,1]
	v_pk_fma_f32 v[244:245], v[36:37], v[204:205], v[244:245] op_sel_hi:[0,1,1]
	v_pk_fma_f32 v[254:255], v[38:39], v[206:207], v[254:255] op_sel_hi:[0,1,1]
	v_pk_fma_f32 v[200:201], v[32:33], v[200:201], v[232:233] op_sel:[1,1,0] op_sel_hi:[1,0,1] neg_lo:[1,0,0]
	v_pk_fma_f32 v[202:203], v[34:35], v[202:203], v[234:235] op_sel:[1,1,0] op_sel_hi:[1,0,1] neg_lo:[1,0,0]
	v_pk_fma_f32 v[204:205], v[36:37], v[204:205], v[244:245] op_sel:[1,1,0] op_sel_hi:[1,0,1] neg_lo:[1,0,0]
	v_pk_fma_f32 v[206:207], v[38:39], v[206:207], v[254:255] op_sel:[1,1,0] op_sel_hi:[1,0,1] neg_lo:[1,0,0]
	v_pk_mov_b32 v[232:233], v[138:139], v[154:155] op_sel:[0,0]
	v_pk_mov_b32 v[234:235], v[142:143], v[158:159] op_sel:[0,0]
	v_pk_mov_b32 v[244:245], v[146:147], v[162:163] op_sel:[0,0]
	v_pk_mov_b32 v[254:255], v[150:151], v[166:167] op_sel:[0,0]
	v_pk_fma_f32 v[232:233], v[32:33], v[200:201], v[232:233] op_sel_hi:[0,1,1]
	v_pk_fma_f32 v[234:235], v[34:35], v[202:203], v[234:235] op_sel_hi:[0,1,1]
	v_pk_fma_f32 v[244:245], v[36:37], v[204:205], v[244:245] op_sel_hi:[0,1,1]
	v_pk_fma_f32 v[254:255], v[38:39], v[206:207], v[254:255] op_sel_hi:[0,1,1]
	v_pk_fma_f32 v[200:201], v[32:33], v[200:201], v[232:233] op_sel:[1,1,0] op_sel_hi:[1,0,1] neg_lo:[1,0,0]
	v_pk_fma_f32 v[202:203], v[34:35], v[202:203], v[234:235] op_sel:[1,1,0] op_sel_hi:[1,0,1] neg_lo:[1,0,0]
	v_pk_fma_f32 v[204:205], v[36:37], v[204:205], v[244:245] op_sel:[1,1,0] op_sel_hi:[1,0,1] neg_lo:[1,0,0]
	v_pk_fma_f32 v[206:207], v[38:39], v[206:207], v[254:255] op_sel:[1,1,0] op_sel_hi:[1,0,1] neg_lo:[1,0,0]
	v_pk_mov_b32 v[232:233], v[138:139], v[154:155] op_sel:[1,1]
	v_pk_mov_b32 v[234:235], v[142:143], v[158:159] op_sel:[1,1]
	v_pk_mov_b32 v[244:245], v[146:147], v[162:163] op_sel:[1,1]
	v_pk_mov_b32 v[254:255], v[150:151], v[166:167] op_sel:[1,1]
	v_pk_fma_f32 v[232:233], v[32:33], v[200:201], v[232:233] op_sel_hi:[0,1,1]
	v_pk_fma_f32 v[234:235], v[34:35], v[202:203], v[234:235] op_sel_hi:[0,1,1]
	v_pk_fma_f32 v[244:245], v[36:37], v[204:205], v[244:245] op_sel_hi:[0,1,1]
	v_pk_fma_f32 v[254:255], v[38:39], v[206:207], v[254:255] op_sel_hi:[0,1,1]
	v_pk_fma_f32 v[200:201], v[32:33], v[200:201], v[232:233] op_sel:[1,1,0] op_sel_hi:[1,0,1] neg_lo:[1,0,0]
	v_pk_fma_f32 v[202:203], v[34:35], v[202:203], v[234:235] op_sel:[1,1,0] op_sel_hi:[1,0,1] neg_lo:[1,0,0]
	v_pk_fma_f32 v[204:205], v[36:37], v[204:205], v[244:245] op_sel:[1,1,0] op_sel_hi:[1,0,1] neg_lo:[1,0,0]
	v_pk_fma_f32 v[206:207], v[38:39], v[206:207], v[254:255] op_sel:[1,1,0] op_sel_hi:[1,0,1] neg_lo:[1,0,0]
; __device__ __forceinline__ unsigned f2bf(float f) { unsigned u = __builtin_bit_cast(unsigned, f); return (u + 0x7fffu + ((u >> 16) & 1u)) >> 16; }
; __device__ __forceinline__ bf16x8 pack8(const float (&f)[8]) { u32x4 h; h.x = pk2(f[0], f[1]); h.y = pk2(f[2], f[3]); h.z = pk2(f[4], f[5]); h.w = pk2(f[6], f[7]); return __builtin_bit_cast(bf16x8, h); }
; template <bool FINAL> __device__ __forceinline__ void phase_s5_scan(const Fr& F) {
;     ...
; #pragma unroll 4
;             for (int jj = 0; jj < 16; ++jj) {
;                 const float br_ = BUl[jj * 132 + lane], bi_ = BUl[jj * 132 + 64 + lane];
;                 const float nr = ar * xr - ai * xi + br_, ni = ar * xi + ai * xr + bi_; xr = nr; xi = ni;
;                 if (FINAL) { BUl[jj * 132 + lane] = xr; BUl[jj * 132 + 64 + lane] = xi; }
;             }
;             if (FINAL) {
;                 asm volatile("s_waitcnt lgkmcnt(0)" ::: "memory");
;                 f32x4 acc = {0.f, 0.f, 0.f, 0.f};
; #pragma unroll
;                 for (int ks = 0; ks < 4; ++ks) {
;                     const f32x4 t0 = *(const f32x4*)(BUl + l15 * 132 + 32 * ks + 8 * lq), t1 = *(const f32x4*)(BUl + l15 * 132 + 32 * ks + 8 * lq + 4);
;                     const float xf[8] = {t0.x, t0.y, t0.z, t0.w, t1.x, t1.y, t1.z, t1.w};
;                     acc = __builtin_amdgcn_mfma_f32_16x16x32_bf16(pack8(xf), Chi[ks], acc, 0, 0, 0);
;                 }
; #pragma unroll
;                 for (int reg = 0; reg < 4; ++reg) { const int tok = tokof(s, chunk * 64 + sub * 16 + 4 * lq + reg);
;                     Yb[((size_t)b * TB + tok) * D + g * 16 + l15] = (bf16)f2bf(acc[reg]); }
;                 asm volatile("s_waitcnt lgkmcnt(0)" ::: "memory");
;             }
;         }
;         if (!FINAL) { float* e = E + ((size_t)task * 64 + lane) * 2; e[0] = xr; e[1] = xi; }
	global_load_dwordx4 v[112:115], v238, s[20:21]
	v_add_u32_e32 v238, v238, v243
	v_pk_mov_b32 v[232:233], v[168:169], v[184:185] op_sel:[0,0]
	v_pk_mov_b32 v[234:235], v[172:173], v[188:189] op_sel:[0,0]
	v_pk_mov_b32 v[244:245], v[176:177], v[192:193] op_sel:[0,0]
	v_pk_mov_b32 v[254:255], v[180:181], v[196:197] op_sel:[0,0]
	v_pk_fma_f32 v[232:233], v[32:33], v[200:201], v[232:233] op_sel_hi:[0,1,1]
	v_pk_fma_f32 v[234:235], v[34:35], v[202:203], v[234:235] op_sel_hi:[0,1,1]
	v_pk_fma_f32 v[244:245], v[36:37], v[204:205], v[244:245] op_sel_hi:[0,1,1]
	v_pk_fma_f32 v[254:255], v[38:39], v[206:207], v[254:255] op_sel_hi:[0,1,1]
	v_pk_fma_f32 v[200:201], v[32:33], v[200:201], v[232:233] op_sel:[1,1,0] op_sel_hi:[1,0,1] neg_lo:[1,0,0]
	v_pk_fma_f32 v[202:203], v[34:35], v[202:203], v[234:235] op_sel:[1,1,0] op_sel_hi:[1,0,1] neg_lo:[1,0,0]
	v_pk_fma_f32 v[204:205], v[36:37], v[204:205], v[244:245] op_sel:[1,1,0] op_sel_hi:[1,0,1] neg_lo:[1,0,0]
	v_pk_fma_f32 v[206:207], v[38:39], v[206:207], v[254:255] op_sel:[1,1,0] op_sel_hi:[1,0,1] neg_lo:[1,0,0]
	v_pk_mov_b32 v[232:233], v[168:169], v[184:185] op_sel:[1,1]
	v_pk_mov_b32 v[234:235], v[172:173], v[188:189] op_sel:[1,1]
	v_pk_mov_b32 v[244:245], v[176:177], v[192:193] op_sel:[1,1]
	v_pk_mov_b32 v[254:255], v[180:181], v[196:197] op_sel:[1,1]
	v_pk_fma_f32 v[232:233], v[32:33], v[200:201], v[232:233] op_sel_hi:[0,1,1]
	v_pk_fma_f32 v[234:235], v[34:35], v[202:203], v[234:235] op_sel_hi:[0,1,1]
	v_pk_fma_f32 v[244:245], v[36:37], v[204:205], v[244:245] op_sel_hi:[0,1,1]
	v_pk_fma_f32 v[254:255], v[38:39], v[206:207], v[254:255] op_sel_hi:[0,1,1]
	v_pk_fma_f32 v[200:201], v[32:33], v[200:201], v[232:233] op_sel:[1,1,0] op_sel_hi:[1,0,1] neg_lo:[1,0,0]
	v_pk_fma_f32 v[202:203], v[34:35], v[202:203], v[234:235] op_sel:[1,1,0] op_sel_hi:[1,0,1] neg_lo:[1,0,0]
	v_pk_fma_f32 v[204:205], v[36:37], v[204:205], v[244:245] op_sel:[1,1,0] op_sel_hi:[1,0,1] neg_lo:[1,0,0]
	v_pk_fma_f32 v[206:207], v[38:39], v[206:207], v[254:255] op_sel:[1,1,0] op_sel_hi:[1,0,1] neg_lo:[1,0,0]
	v_pk_mov_b32 v[232:233], v[170:171], v[186:187] op_sel:[0,0]
	v_pk_mov_b32 v[234:235], v[174:175], v[190:191] op_sel:[0,0]
	v_pk_mov_b32 v[244:245], v[178:179], v[194:195] op_sel:[0,0]
	v_pk_mov_b32 v[254:255], v[182:183], v[198:199] op_sel:[0,0]
	v_pk_fma_f32 v[232:233], v[32:33], v[200:201], v[232:233] op_sel_hi:[0,1,1]
	v_pk_fma_f32 v[234:235], v[34:35], v[202:203], v[234:235] op_sel_hi:[0,1,1]
	v_pk_fma_f32 v[244:245], v[36:37], v[204:205], v[244:245] op_sel_hi:[0,1,1]
	v_pk_fma_f32 v[254:255], v[38:39], v[206:207], v[254:255] op_sel_hi:[0,1,1]
	v_pk_fma_f32 v[200:201], v[32:33], v[200:201], v[232:233] op_sel:[1,1,0] op_sel_hi:[1,0,1] neg_lo:[1,0,0]
	v_pk_fma_f32 v[202:203], v[34:35], v[202:203], v[234:235] op_sel:[1,1,0] op_sel_hi:[1,0,1] neg_lo:[1,0,0]
	v_pk_fma_f32 v[204:205], v[36:37], v[204:205], v[244:245] op_sel:[1,1,0] op_sel_hi:[1,0,1] neg_lo:[1,0,0]
	v_pk_fma_f32 v[206:207], v[38:39], v[206:207], v[254:255] op_sel:[1,1,0] op_sel_hi:[1,0,1] neg_lo:[1,0,0]
	v_pk_mov_b32 v[232:233], v[170:171], v[186:187] op_sel:[1,1]
	v_pk_mov_b32 v[234:235], v[174:175], v[190:191] op_sel:[1,1]
	v_pk_mov_b32 v[244:245], v[178:179], v[194:195] op_sel:[1,1]
	v_pk_mov_b32 v[254:255], v[182:183], v[198:199] op_sel:[1,1]
	v_pk_fma_f32 v[232:233], v[32:33], v[200:201], v[232:233] op_sel_hi:[0,1,1]
	v_pk_fma_f32 v[234:235], v[34:35], v[202:203], v[234:235] op_sel_hi:[0,1,1]
	v_pk_fma_f32 v[244:245], v[36:37], v[204:205], v[244:245] op_sel_hi:[0,1,1]
	v_pk_fma_f32 v[254:255], v[38:39], v[206:207], v[254:255] op_sel_hi:[0,1,1]
	v_pk_fma_f32 v[200:201], v[32:33], v[200:201], v[232:233] op_sel:[1,1,0] op_sel_hi:[1,0,1] neg_lo:[1,0,0]
	v_pk_fma_f32 v[202:203], v[34:35], v[202:203], v[234:235] op_sel:[1,1,0] op_sel_hi:[1,0,1] neg_lo:[1,0,0]
	v_pk_fma_f32 v[204:205], v[36:37], v[204:205], v[244:245] op_sel:[1,1,0] op_sel_hi:[1,0,1] neg_lo:[1,0,0]
	v_pk_fma_f32 v[206:207], v[38:39], v[206:207], v[254:255] op_sel:[1,1,0] op_sel_hi:[1,0,1] neg_lo:[1,0,0]
	global_load_dwordx4 v[116:119], v238, s[20:21]
	v_add_u32_e32 v238, v238, v243
	global_store_dwordx2 v240, v[200:201], s[22:23] offset:0
	global_store_dwordx2 v240, v[202:203], s[22:23] offset:128
	global_store_dwordx2 v240, v[204:205], s[22:23] offset:256
	global_store_dwordx2 v240, v[206:207], s[22:23] offset:384
	s_add_i32 s14, s14, 16
	s_add_i32 s19, s19, 1
	s_cmp_lt_u32 s19, s56
	s_cbranch_scc1 .Ls5a_grp
	s_waitcnt vmcnt(0) lgkmcnt(0)

; __device__ __forceinline__ bf16x8 pack8(const float (&f)[8]) { u32x4 h; h.x = pk2(f[0], f[1]); h.y = pk2(f[2], f[3]); h.z = pk2(f[4], f[5]); h.w = pk2(f[6], f[7]); return __builtin_bit_cast(bf16x8, h); }
; template <bool FINAL> __device__ __forceinline__ void phase_s5_scan(const Fr& F) {
;     ...
;     const f32x4 av = *(const f32x4*)((const float*)(F.ws + OFF_S5A) + (sg * 64 + lane) * 4);
;     const float ar = av.x, ai = av.y;
;     bf16x8 B1[8];
; #pragma unroll
;     for (int nt = 0; nt < 8; ++nt) {
;         const int n = 16 * nt + l15; const float* bp = BBf + (size_t)(sg * 64 + (n & 63)) * 32 + 16 * (n >> 6) + 8 * (lq & 1);
;         const f32x4 t0 = *(const f32x4*)bp, t1 = *(const f32x4*)(bp + 4); const float f[8] = {t0.x, t0.y, t0.z, t0.w, t1.x, t1.y, t1.z, t1.w};
;         B1[nt] = lq < 2 ? pack8(f) : (bf16x8){0, 0, 0, 0, 0, 0, 0, 0};
;     }
;     bf16x8 Chi[4];
;     if (FINAL) {
; #pragma unroll
;         for (int ks = 0; ks < 4; ++ks) {
;             const int k = 32 * ks + 8 * lq; const float* cp = (k < 64 ? F.a->in[32] : F.a->in[33]) + (size_t)g * 1024 + l15 * 64 + (k & 63); const float sg_ = k < 64 ? 1.f : -1.f;
;             const f32x4 t0 = *(const f32x4*)cp, t1 = *(const f32x4*)(cp + 4); const float f[8] = {sg_ * t0.x, sg_ * t0.y, sg_ * t0.z, sg_ * t0.w, sg_ * t1.x, sg_ * t1.y, sg_ * t1.z, sg_ * t1.w};
;             Chi[ks] = pack8(f);
;         }
;     }
.LBB0_1716:
	s_or_b64 exec, exec, s[6:7]
	v_cmp_gt_i32_e32 vcc, 18, v2
	v_cmp_lt_i32_e64 s[6:7], 17, v3
	s_and_b64 s[6:7], vcc, s[6:7]
	s_and_saveexec_b64 s[12:13], s[6:7]
	s_cbranch_execz .LBB0_1762
	s_lshr_b32 s3, s36, 4
	s_and_b32 s8, s3, 63
	s_lshr_b32 s9, s3, 6
	s_and_b32 s55, s36, 15
	s_cmp_lt_u32 s55, 4
	s_cselect_b32 s56, 5, 4
	v_and_b32_e32 v236, 15, v130
	v_lshrrev_b32_e32 v237, 4, v130
	s_add_u32 s42, s26, 0x100000
	s_addc_u32 s43, s27, 0
	s_add_u32 s44, s26, 0x40000
	s_addc_u32 s45, s27, 0
	s_add_u32 s20, s26, 0x3400000
	s_addc_u32 s21, s27, 0
	s_add_u32 s22, s26, 0xde00000
	s_addc_u32 s23, s27, 0
	s_mul_i32 s15, s9, 0x2200000
	s_add_u32 s24, s26, s15
	s_addc_u32 s25, s27, 0
	s_add_u32 s24, s24, 0x9a00000
	s_addc_u32 s25, s25, 0
	s_load_dwordx2 s[46:47], s[0:1], 0x100
	s_load_dwordx2 s[48:49], s[0:1], 0x108
	s_lshl_b32 s15, s3, 6
	v_add_u32_e32 v216, s15, v236
	v_and_b32_e32 v217, 1, v237
	v_lshlrev_b32_e32 v217, 5, v217
	v_lshl_add_u32 v218, v216, 7, v217
	v_add_u32_e32 v219, 0x1000, v218
	global_load_dwordx4 v[56:59], v218, s[42:43] offset:0
	global_load_dwordx4 v[60:63], v218, s[42:43] offset:16
	global_load_dwordx4 v[64:67], v218, s[42:43] offset:2048
	global_load_dwordx4 v[68:71], v218, s[42:43] offset:2064
	global_load_dwordx4 v[72:75], v219, s[42:43] offset:0
	global_load_dwordx4 v[76:79], v219, s[42:43] offset:16
	global_load_dwordx4 v[80:83], v219, s[42:43] offset:2048
	global_load_dwordx4 v[84:87], v219, s[42:43] offset:2064
	global_load_dwordx4 v[88:91], v218, s[42:43] offset:64
	global_load_dwordx4 v[92:95], v218, s[42:43] offset:80
	global_load_dwordx4 v[96:99], v218, s[42:43] offset:2112
	global_load_dwordx4 v[100:103], v218, s[42:43] offset:2128
	global_load_dwordx4 v[104:107], v219, s[42:43] offset:64
	global_load_dwordx4 v[108:111], v219, s[42:43] offset:80
	global_load_dwordx4 v[112:115], v219, s[42:43] offset:2112
	global_load_dwordx4 v[116:119], v219, s[42:43] offset:2128
	v_lshlrev_b32_e32 v220, 4, v216
	global_load_dwordx2 v[32:33], v220, s[44:45] offset:0
	global_load_dwordx2 v[34:35], v220, s[44:45] offset:256
	global_load_dwordx2 v[36:37], v220, s[44:45] offset:512
	global_load_dwordx2 v[38:39], v220, s[44:45] offset:768
	s_waitcnt vmcnt(0)
	v_cmp_gt_u32_e32 vcc, 2, v237
	v_cvt_pk_bf16_f32 v0, v56, v57
	v_cvt_pk_bf16_f32 v1, v58, v59
	v_cvt_pk_bf16_f32 v2, v60, v61
	v_cvt_pk_bf16_f32 v3, v62, v63
	v_cvt_pk_bf16_f32 v4, v64, v65
	v_cvt_pk_bf16_f32 v5, v66, v67
	v_cvt_pk_bf16_f32 v6, v68, v69
	v_cvt_pk_bf16_f32 v7, v70, v71
	v_cvt_pk_bf16_f32 v8, v72, v73
	v_cvt_pk_bf16_f32 v9, v74, v75
	v_cvt_pk_bf16_f32 v10, v76, v77
	v_cvt_pk_bf16_f32 v11, v78, v79
	v_cvt_pk_bf16_f32 v12, v80, v81
	v_cvt_pk_bf16_f32 v13, v82, v83
	v_cvt_pk_bf16_f32 v14, v84, v85
	v_cvt_pk_bf16_f32 v15, v86, v87
	v_cvt_pk_bf16_f32 v16, v88, v89
	v_cvt_pk_bf16_f32 v17, v90, v91
	v_cvt_pk_bf16_f32 v18, v92, v93
	v_cvt_pk_bf16_f32 v19, v94, v95
	v_cvt_pk_bf16_f32 v20, v96, v97
	v_cvt_pk_bf16_f32 v21, v98, v99
	v_cvt_pk_bf16_f32 v22, v100, v101
	v_cvt_pk_bf16_f32 v23, v102, v103
	v_cvt_pk_bf16_f32 v24, v104, v105
	v_cvt_pk_bf16_f32 v25, v106, v107
	v_cvt_pk_bf16_f32 v26, v108, v109
	v_cvt_pk_bf16_f32 v27, v110, v111
	v_cvt_pk_bf16_f32 v28, v112, v113
	v_cvt_pk_bf16_f32 v29, v114, v115
	v_cvt_pk_bf16_f32 v30, v116, v117
	v_cvt_pk_bf16_f32 v31, v118, v119
	v_cndmask_b32_e32 v0, 0, v0, vcc
	v_cndmask_b32_e32 v1, 0, v1, vcc
	v_cndmask_b32_e32 v2, 0, v2, vcc
	v_cndmask_b32_e32 v3, 0, v3, vcc
	v_cndmask_b32_e32 v4, 0, v4, vcc
	v_cndmask_b32_e32 v5, 0, v5, vcc
	v_cndmask_b32_e32 v6, 0, v6, vcc
	v_cndmask_b32_e32 v7, 0, v7, vcc
	v_cndmask_b32_e32 v8, 0, v8, vcc
	v_cndmask_b32_e32 v9, 0, v9, vcc
	v_cndmask_b32_e32 v10, 0, v10, vcc
	v_cndmask_b32_e32 v11, 0, v11, vcc
	v_cndmask_b32_e32 v12, 0, v12, vcc
	v_cndmask_b32_e32 v13, 0, v13, vcc
	v_cndmask_b32_e32 v14, 0, v14, vcc
	v_cndmask_b32_e32 v15, 0, v15, vcc
	v_cndmask_b32_e32 v16, 0, v16, vcc
	v_cndmask_b32_e32 v17, 0, v17, vcc
	v_cndmask_b32_e32 v18, 0, v18, vcc
	v_cndmask_b32_e32 v19, 0, v19, vcc
	v_cndmask_b32_e32 v20, 0, v20, vcc
	v_cndmask_b32_e32 v21, 0, v21, vcc
	v_cndmask_b32_e32 v22, 0, v22, vcc
	v_cndmask_b32_e32 v23, 0, v23, vcc
	v_cndmask_b32_e32 v24, 0, v24, vcc
	v_cndmask_b32_e32 v25, 0, v25, vcc
	v_cndmask_b32_e32 v26, 0, v26, vcc
	v_cndmask_b32_e32 v27, 0, v27, vcc
	v_cndmask_b32_e32 v28, 0, v28, vcc
	v_cndmask_b32_e32 v29, 0, v29, vcc
	v_cndmask_b32_e32 v30, 0, v30, vcc
	v_cndmask_b32_e32 v31, 0, v31, vcc
	s_lshl_b32 s15, s8, 4
	v_add_u32_e32 v221, s15, v236
	v_lshl_add_u32 v221, v221, 6, v237
	v_lshlrev_b32_e32 v221, 2, v221
	s_waitcnt lgkmcnt(0)
	global_load_dword v56, v221, s[46:47] offset:0
	global_load_dword v57, v221, s[48:49] offset:0
	global_load_dword v58, v221, s[46:47] offset:64
	global_load_dword v59, v221, s[48:49] offset:64
	global_load_dword v60, v221, s[46:47] offset:128
	global_load_dword v61, v221, s[48:49] offset:128
	global_load_dword v62, v221, s[46:47] offset:192
	global_load_dword v63, v221, s[48:49] offset:192
	global_load_dword v64, v221, s[46:47] offset:16
	global_load_dword v65, v221, s[48:49] offset:16
	global_load_dword v66, v221, s[46:47] offset:80
	global_load_dword v67, v221, s[48:49] offset:80
	global_load_dword v68, v221, s[46:47] offset:144
	global_load_dword v69, v221, s[48:49] offset:144
	global_load_dword v70, v221, s[46:47] offset:208
	global_load_dword v71, v221, s[48:49] offset:208
	global_load_dword v72, v221, s[46:47] offset:32
	global_load_dword v73, v221, s[48:49] offset:32
	global_load_dword v74, v221, s[46:47] offset:96
	global_load_dword v75, v221, s[48:49] offset:96
	global_load_dword v76, v221, s[46:47] offset:160
	global_load_dword v77, v221, s[48:49] offset:160
	global_load_dword v78, v221, s[46:47] offset:224
	global_load_dword v79, v221, s[48:49] offset:224
	global_load_dword v80, v221, s[46:47] offset:48
	global_load_dword v81, v221, s[48:49] offset:48
	global_load_dword v82, v221, s[46:47] offset:112
	global_load_dword v83, v221, s[48:49] offset:112
	global_load_dword v84, v221, s[46:47] offset:176
	global_load_dword v85, v221, s[48:49] offset:176
	global_load_dword v86, v221, s[46:47] offset:240
	global_load_dword v87, v221, s[48:49] offset:240
	s_waitcnt vmcnt(0)
; __device__ __forceinline__ bf16x8 pack8(const float (&f)[8]) { u32x4 h; h.x = pk2(f[0], f[1]); h.y = pk2(f[2], f[3]); h.z = pk2(f[4], f[5]); h.w = pk2(f[6], f[7]); return __builtin_bit_cast(bf16x8, h); }
;     __device__ __forceinline__ bf16* R(int i) const { return (bf16*)(ws + OFF_R0 + (size_t)i * RSZ); }
; template <bool FINAL> __device__ __forceinline__ void phase_s5_scan(const Fr& F) {
;     ...
;             const int k = 32 * ks + 8 * lq; const float* cp = (k < 64 ? F.a->in[32] : F.a->in[33]) + (size_t)g * 1024 + l15 * 64 + (k & 63); const float sg_ = k < 64 ? 1.f : -1.f;
;             const f32x4 t0 = *(const f32x4*)cp, t1 = *(const f32x4*)(cp + 4); const float f[8] = {sg_ * t0.x, sg_ * t0.y, sg_ * t0.z, sg_ * t0.w, sg_ * t1.x, sg_ * t1.y, sg_ * t1.z, sg_ * t1.w};
;             Chi[ks] = pack8(f);
;         }
;     }
;     u32x4 ua[4]; float e0 = 0.f, e1 = 0.f;
;     {   const int ti = F.gw & 15, b = ti / 68, chunk = ti - b * 68;
; #pragma unroll
;         for (int sb = 0; sb < 4; ++sb) ua[sb] = lq < 2 ? *(const u32x4*)(U + ((size_t)b * TB + tokof(s, chunk * 64 + sb * 16 + l15)) * D + g * 16 + 8 * lq) : (u32x4){0u, 0u, 0u, 0u};
;         if (FINAL) { const float* e = E + ((size_t)(((s * 4 + b) * 64 + g) * 68 + chunk) * 64 + lane) * 2; e0 = e[0]; e1 = e[1]; } }
;     for (int ti = (F.gw & 15); ti < NB * 68; ti += 16) {
;         const int b = ti / 68, chunk = ti - b * 68, sbg = (s * 4 + b) * 64 + g, task = sbg * 68 + chunk;
;         float xr = FINAL ? e0 : 0.f, xi = FINAL ? e1 : 0.f;
;         bf16* Yb = F.R(4 + s);
;         u32x4 uc[4];
; #pragma unroll
;         for (int sb = 0; sb < 4; ++sb) uc[sb] = ua[sb];
;         if (ti + 16 < NB * 68) {
;             const int tn = ti + 16, bn = tn / 68, cn = tn - bn * 68;
; #pragma unroll
;             for (int sb = 0; sb < 4; ++sb) ua[sb] = lq < 2 ? *(const u32x4*)(U + ((size_t)bn * TB + tokof(s, cn * 64 + sb * 16 + l15)) * D + g * 16 + 8 * lq) : (u32x4){0u, 0u, 0u, 0u};
;             if (FINAL) { const float* e = E + ((size_t)(((s * 4 + bn) * 64 + g) * 68 + cn) * 64 + lane) * 2; e0 = e[0]; e1 = e[1]; }
	v_cvt_pk_bf16_f32 v40, v56, -v57
	v_cvt_pk_bf16_f32 v41, v58, -v59
	v_cvt_pk_bf16_f32 v42, v60, -v61
	v_cvt_pk_bf16_f32 v43, v62, -v63
	v_cvt_pk_bf16_f32 v44, v64, -v65
	v_cvt_pk_bf16_f32 v45, v66, -v67
	v_cvt_pk_bf16_f32 v46, v68, -v69
	v_cvt_pk_bf16_f32 v47, v70, -v71
	v_cvt_pk_bf16_f32 v48, v72, -v73
	v_cvt_pk_bf16_f32 v49, v74, -v75
	v_cvt_pk_bf16_f32 v50, v76, -v77
	v_cvt_pk_bf16_f32 v51, v78, -v79
	v_cvt_pk_bf16_f32 v52, v80, -v81
	v_cvt_pk_bf16_f32 v53, v82, -v83
	v_cvt_pk_bf16_f32 v54, v84, -v85
	v_cvt_pk_bf16_f32 v55, v86, -v87
	s_lshl_b32 s15, s68, 14
	v_lshlrev_b32_e32 v241, 10, v237
	v_lshl_add_u32 v241, v236, 4, v241
	v_add_u32_e32 v241, s15, v241
	v_lshlrev_b32_e32 v242, 8, v236
	v_lshl_add_u32 v242, v237, 4, v242
	v_add_u32_e32 v242, s15, v242
	s_cmp_eq_u32 s9, 0
	s_mov_b32 s18, 0xffffe000
	s_cselect_b32 s18, 0x2000, s18
	v_mov_b32_e32 v243, s18
	s_mov_b32 s14, s55
	s_lshl_b32 s15, s14, 2
	v_lshrrev_b32_e32 v244, 2, v236
	v_add_u32_e32 v244, s15, v244
	v_mul_u32_u24_e32 v245, 0xf1, v244
	v_lshrrev_b32_e32 v245, 14, v245
	v_mul_u32_u24_e32 v232, 68, v245
	v_sub_u32_e32 v244, v244, v232
	v_and_b32_e32 v232, 3, v236
	v_lshl_add_u32 v232, v244, 6, v232
	v_mov_b32_e32 v233, 0x11ff
	v_mov_b32_e32 v234, 0xff
	v_cmp_gt_u32_e32 vcc, 4, v244
	s_nop 1
	v_cndmask_b32_e32 v233, v233, v234, vcc
	v_sub_u32_e32 v233, v233, v232
	s_cmp_eq_u32 s9, 0
	s_cselect_b64 vcc, -1, 0
	s_nop 1
	v_cndmask_b32_e32 v232, v233, v232, vcc
	v_mul_u32_u24_e32 v245, 0x1100, v245
	v_add_u32_e32 v232, v232, v245
	s_lshl_b32 s16, s8, 5
	v_and_b32_e32 v233, 1, v237
	v_lshl_add_u32 v233, v233, 4, s16
	v_lshl_add_u32 v238, v232, 11, v233
	v_add_u32_e32 v244, s15, v237
	v_mul_u32_u24_e32 v245, 0xf1, v244
	v_lshrrev_b32_e32 v245, 14, v245
	v_mul_u32_u24_e32 v232, 68, v245
	v_sub_u32_e32 v244, v244, v232
	s_lshl_b32 s17, s9, 2
	v_add_u32_e32 v245, s17, v245
	v_lshl_add_u32 v245, v245, 6, s8
	v_mul_u32_u24_e32 v245, 68, v245
	v_add_u32_e32 v245, v245, v244
	v_lshl_add_u32 v245, v245, 6, v236
	v_lshlrev_b32_e32 v240, 3, v245
	global_load_dwordx2 v[246:247], v240, s[22:23] offset:0
	global_load_dwordx2 v[248:249], v240, s[22:23] offset:128
	global_load_dwordx2 v[250:251], v240, s[22:23] offset:256
	global_load_dwordx2 v[252:253], v240, s[22:23] offset:384
	global_load_dwordx4 v[56:59], v238, s[20:21]
	v_add_u32_e32 v238, v238, v243
	global_load_dwordx4 v[60:63], v238, s[20:21]
	v_add_u32_e32 v238, v238, v243
	global_load_dwordx4 v[64:67], v238, s[20:21]
	v_add_u32_e32 v238, v238, v243
	global_load_dwordx4 v[68:71], v238, s[20:21]
	v_add_u32_e32 v238, v238, v243
	global_load_dwordx4 v[72:75], v238, s[20:21]
	v_add_u32_e32 v238, v238, v243
	global_load_dwordx4 v[76:79], v238, s[20:21]
	v_add_u32_e32 v238, v238, v243
	global_load_dwordx4 v[80:83], v238, s[20:21]
	v_add_u32_e32 v238, v238, v243
	global_load_dwordx4 v[84:87], v238, s[20:21]
	v_add_u32_e32 v238, v238, v243
	global_load_dwordx4 v[88:91], v238, s[20:21]
	v_add_u32_e32 v238, v238, v243
	global_load_dwordx4 v[92:95], v238, s[20:21]
	v_add_u32_e32 v238, v238, v243
	global_load_dwordx4 v[96:99], v238, s[20:21]
	v_add_u32_e32 v238, v238, v243
	global_load_dwordx4 v[100:103], v238, s[20:21]
	v_add_u32_e32 v238, v238, v243
	global_load_dwordx4 v[104:107], v238, s[20:21]
	v_add_u32_e32 v238, v238, v243
	global_load_dwordx4 v[108:111], v238, s[20:21]
	v_add_u32_e32 v238, v238, v243
	global_load_dwordx4 v[112:115], v238, s[20:21]
	v_add_u32_e32 v238, v238, v243
	global_load_dwordx4 v[116:119], v238, s[20:21]
	v_add_u32_e32 v238, v238, v243
	s_mov_b32 s19, 0
	s_waitcnt vmcnt(0)
.Ls5b_grp:
	s_lshl_b32 s15, s14, 2
	v_lshrrev_b32_e32 v244, 2, v236
	v_add_u32_e32 v244, s15, v244
	v_mul_u32_u24_e32 v245, 0xf1, v244
	v_lshrrev_b32_e32 v245, 14, v245
	v_mul_u32_u24_e32 v232, 68, v245
	v_sub_u32_e32 v244, v244, v232
	v_and_b32_e32 v232, 3, v236
	v_lshl_add_u32 v232, v244, 6, v232
	v_mov_b32_e32 v233, 0x11ff
	v_mov_b32_e32 v234, 0xff
	v_cmp_gt_u32_e32 vcc, 4, v244
	s_nop 1
	v_cndmask_b32_e32 v233, v233, v234, vcc
	v_sub_u32_e32 v233, v233, v232
	s_cmp_eq_u32 s9, 0
	s_cselect_b64 vcc, -1, 0
	s_nop 1
	v_cndmask_b32_e32 v232, v233, v232, vcc
	v_mul_u32_u24_e32 v245, 0x1100, v245
	v_add_u32_e32 v232, v232, v245
	s_lshl_b32 s16, s8, 5
	v_and_b32_e32 v233, 1, v237
	v_lshl_add_u32 v233, v233, 4, s16
	v_lshl_add_u32 v235, v232, 11, v233
	v_lshl_add_u32 v233, v237, 3, s16
	v_lshl_add_u32 v239, v232, 11, v233
	s_add_i32 s54, s14, 16
	s_lshl_b32 s15, s54, 2
	v_lshrrev_b32_e32 v244, 2, v236
	v_add_u32_e32 v244, s15, v244
	v_mul_u32_u24_e32 v245, 0xf1, v244
	v_lshrrev_b32_e32 v245, 14, v245
	v_mul_u32_u24_e32 v232, 68, v245
	v_sub_u32_e32 v244, v244, v232
	v_and_b32_e32 v232, 3, v236
	v_lshl_add_u32 v232, v244, 6, v232
	v_mov_b32_e32 v233, 0x11ff
	v_mov_b32_e32 v234, 0xff
	v_cmp_gt_u32_e32 vcc, 4, v244
	s_nop 1
	v_cndmask_b32_e32 v233, v233, v234, vcc
	v_sub_u32_e32 v233, v233, v232
	s_cmp_eq_u32 s9, 0
	s_cselect_b64 vcc, -1, 0
	s_nop 1
	v_cndmask_b32_e32 v232, v233, v232, vcc
	v_mul_u32_u24_e32 v245, 0x1100, v245
	v_add_u32_e32 v232, v232, v245
	s_lshl_b32 s16, s8, 5
	v_and_b32_e32 v233, 1, v237
	v_lshl_add_u32 v233, v233, 4, s16
	v_lshl_add_u32 v238, v232, 11, v233
	v_add_u32_e32 v244, s15, v237
	v_mul_u32_u24_e32 v245, 0xf1, v244
	v_lshrrev_b32_e32 v245, 14, v245
	v_mul_u32_u24_e32 v232, 68, v245
	v_sub_u32_e32 v244, v244, v232
	s_lshl_b32 s17, s9, 2
	v_add_u32_e32 v245, s17, v245
	v_lshl_add_u32 v245, v245, 6, s8
	v_mul_u32_u24_e32 v245, 68, v245
	v_add_u32_e32 v245, v245, v244
	v_lshl_add_u32 v245, v245, 6, v236
	v_lshlrev_b32_e32 v240, 3, v245
	s_waitcnt vmcnt(31)
; __device__ __forceinline__ unsigned f2bf(float f) { unsigned u = __builtin_bit_cast(unsigned, f); return (u + 0x7fffu + ((u >> 16) & 1u)) >> 16; }
; __device__ __forceinline__ bf16x8 pack8(const float (&f)[8]) { u32x4 h; h.x = pk2(f[0], f[1]); h.y = pk2(f[2], f[3]); h.z = pk2(f[4], f[5]); h.w = pk2(f[6], f[7]); return __builtin_bit_cast(bf16x8, h); }
; template <bool FINAL> __device__ __forceinline__ void phase_s5_scan(const Fr& F) {
;     ...
;         for (int sub = 0; sub < 4; ++sub) {
;             const bf16x8 A1 = __builtin_bit_cast(bf16x8, uc[sub]);
; #pragma unroll
;             for (int nt = 0; nt < 8; ++nt) {
;                 f32x4 acc = {0.f, 0.f, 0.f, 0.f};
;                 acc = __builtin_amdgcn_mfma_f32_16x16x32_bf16(A1, B1[nt], acc, 0, 0, 0);
; #pragma unroll
;                 for (int reg = 0; reg < 4; ++reg) BUl[(4 * lq + reg) * 132 + 16 * nt + l15] = acc[reg];
;             }
;             asm volatile("s_waitcnt lgkmcnt(0)" ::: "memory");
; #pragma unroll 4
;             for (int jj = 0; jj < 16; ++jj) {
;                 const float br_ = BUl[jj * 132 + lane], bi_ = BUl[jj * 132 + 64 + lane];
;                 const float nr = ar * xr - ai * xi + br_, ni = ar * xi + ai * xr + bi_; xr = nr; xi = ni;
;                 if (FINAL) { BUl[jj * 132 + lane] = xr; BUl[jj * 132 + 64 + lane] = xi; }
;             }
;             if (FINAL) {
;                 asm volatile("s_waitcnt lgkmcnt(0)" ::: "memory");
;                 f32x4 acc = {0.f, 0.f, 0.f, 0.f};
; #pragma unroll
;                 for (int ks = 0; ks < 4; ++ks) {
;                     const f32x4 t0 = *(const f32x4*)(BUl + l15 * 132 + 32 * ks + 8 * lq), t1 = *(const f32x4*)(BUl + l15 * 132 + 32 * ks + 8 * lq + 4);
;                     const float xf[8] = {t0.x, t0.y, t0.z, t0.w, t1.x, t1.y, t1.z, t1.w};
;                     acc = __builtin_amdgcn_mfma_f32_16x16x32_bf16(pack8(xf), Chi[ks], acc, 0, 0, 0);
;                 }
; #pragma unroll
;                 for (int reg = 0; reg < 4; ++reg) { const int tok = tokof(s, chunk * 64 + sub * 16 + 4 * lq + reg);
;                     Yb[((size_t)b * TB + tok) * D + g * 16 + l15] = (bf16)f2bf(acc[reg]); }
;                 asm volatile("s_waitcnt lgkmcnt(0)" ::: "memory");
	v_mov_b32_e32 v200, v246
	v_mov_b32_e32 v201, v247
	v_mov_b32_e32 v202, v248
	v_mov_b32_e32 v203, v249
	v_mov_b32_e32 v204, v250
	v_mov_b32_e32 v205, v251
	v_mov_b32_e32 v206, v252
	v_mov_b32_e32 v207, v253
	s_nop 0
	global_load_dwordx2 v[246:247], v240, s[22:23] offset:0
	global_load_dwordx2 v[248:249], v240, s[22:23] offset:128
	global_load_dwordx2 v[250:251], v240, s[22:23] offset:256
	global_load_dwordx2 v[252:253], v240, s[22:23] offset:384
	v_mfma_f32_16x16x32_bf16 v[136:139], v[56:59], v[0:3], 0
	v_mfma_f32_16x16x32_bf16 v[140:143], v[56:59], v[4:7], 0
	v_mfma_f32_16x16x32_bf16 v[144:147], v[56:59], v[8:11], 0
	v_mfma_f32_16x16x32_bf16 v[148:151], v[56:59], v[12:15], 0
	v_mfma_f32_16x16x32_bf16 v[152:155], v[56:59], v[16:19], 0
	v_mfma_f32_16x16x32_bf16 v[156:159], v[56:59], v[20:23], 0
	v_mfma_f32_16x16x32_bf16 v[160:163], v[56:59], v[24:27], 0
	v_mfma_f32_16x16x32_bf16 v[164:167], v[56:59], v[28:31], 0
	s_waitcnt vmcnt(33)
	v_mfma_f32_16x16x32_bf16 v[168:171], v[60:63], v[0:3], 0
	v_mfma_f32_16x16x32_bf16 v[172:175], v[60:63], v[4:7], 0
	v_mfma_f32_16x16x32_bf16 v[176:179], v[60:63], v[8:11], 0
	v_mfma_f32_16x16x32_bf16 v[180:183], v[60:63], v[12:15], 0
	v_mfma_f32_16x16x32_bf16 v[184:187], v[60:63], v[16:19], 0
	v_mfma_f32_16x16x32_bf16 v[188:191], v[60:63], v[20:23], 0
	v_mfma_f32_16x16x32_bf16 v[192:195], v[60:63], v[24:27], 0
	v_mfma_f32_16x16x32_bf16 v[196:199], v[60:63], v[28:31], 0
	v_pk_mov_b32 v[232:233], v[136:137], v[152:153] op_sel:[0,0]
	v_pk_mov_b32 v[234:235], v[140:141], v[156:157] op_sel:[0,0]
	v_pk_mov_b32 v[244:245], v[144:145], v[160:161] op_sel:[0,0]
	v_pk_mov_b32 v[254:255], v[148:149], v[164:165] op_sel:[0,0]
	v_pk_fma_f32 v[232:233], v[32:33], v[200:201], v[232:233] op_sel_hi:[0,1,1]
	v_pk_fma_f32 v[234:235], v[34:35], v[202:203], v[234:235] op_sel_hi:[0,1,1]
	v_pk_fma_f32 v[244:245], v[36:37], v[204:205], v[244:245] op_sel_hi:[0,1,1]
	v_pk_fma_f32 v[254:255], v[38:39], v[206:207], v[254:255] op_sel_hi:[0,1,1]
	v_pk_fma_f32 v[200:201], v[32:33], v[200:201], v[232:233] op_sel:[1,1,0] op_sel_hi:[1,0,1] neg_lo:[1,0,0]
	v_pk_fma_f32 v[202:203], v[34:35], v[202:203], v[234:235] op_sel:[1,1,0] op_sel_hi:[1,0,1] neg_lo:[1,0,0]
	v_pk_fma_f32 v[204:205], v[36:37], v[204:205], v[244:245] op_sel:[1,1,0] op_sel_hi:[1,0,1] neg_lo:[1,0,0]
	v_pk_fma_f32 v[206:207], v[38:39], v[206:207], v[254:255] op_sel:[1,1,0] op_sel_hi:[1,0,1] neg_lo:[1,0,0]
	v_cvt_pk_bf16_f32 v124, v200, v201
	v_cvt_pk_bf16_f32 v125, v202, v203
	v_cvt_pk_bf16_f32 v126, v204, v205
	v_cvt_pk_bf16_f32 v127, v206, v207
	ds_write_b128 v241, v[124:127] offset:0
	v_pk_mov_b32 v[232:233], v[136:137], v[152:153] op_sel:[1,1]
	v_pk_mov_b32 v[234:235], v[140:141], v[156:157] op_sel:[1,1]
	v_pk_mov_b32 v[244:245], v[144:145], v[160:161] op_sel:[1,1]
	v_pk_mov_b32 v[254:255], v[148:149], v[164:165] op_sel:[1,1]
	v_pk_fma_f32 v[232:233], v[32:33], v[200:201], v[232:233] op_sel_hi:[0,1,1]
	v_pk_fma_f32 v[234:235], v[34:35], v[202:203], v[234:235] op_sel_hi:[0,1,1]
	v_pk_fma_f32 v[244:245], v[36:37], v[204:205], v[244:245] op_sel_hi:[0,1,1]
	v_pk_fma_f32 v[254:255], v[38:39], v[206:207], v[254:255] op_sel_hi:[0,1,1]
	v_pk_fma_f32 v[200:201], v[32:33], v[200:201], v[232:233] op_sel:[1,1,0] op_sel_hi:[1,0,1] neg_lo:[1,0,0]
	v_pk_fma_f32 v[202:203], v[34:35], v[202:203], v[234:235] op_sel:[1,1,0] op_sel_hi:[1,0,1] neg_lo:[1,0,0]
	v_pk_fma_f32 v[204:205], v[36:37], v[204:205], v[244:245] op_sel:[1,1,0] op_sel_hi:[1,0,1] neg_lo:[1,0,0]
	v_pk_fma_f32 v[206:207], v[38:39], v[206:207], v[254:255] op_sel:[1,1,0] op_sel_hi:[1,0,1] neg_lo:[1,0,0]
	v_cvt_pk_bf16_f32 v124, v200, v201
	v_cvt_pk_bf16_f32 v125, v202, v203
	v_cvt_pk_bf16_f32 v126, v204, v205
	v_cvt_pk_bf16_f32 v127, v206, v207
	ds_write_b128 v241, v[124:127] offset:256
	v_pk_mov_b32 v[232:233], v[138:139], v[154:155] op_sel:[0,0]
	v_pk_mov_b32 v[234:235], v[142:143], v[158:159] op_sel:[0,0]
	v_pk_mov_b32 v[244:245], v[146:147], v[162:163] op_sel:[0,0]
	v_pk_mov_b32 v[254:255], v[150:151], v[166:167] op_sel:[0,0]
	v_pk_fma_f32 v[232:233], v[32:33], v[200:201], v[232:233] op_sel_hi:[0,1,1]
	v_pk_fma_f32 v[234:235], v[34:35], v[202:203], v[234:235] op_sel_hi:[0,1,1]
	v_pk_fma_f32 v[244:245], v[36:37], v[204:205], v[244:245] op_sel_hi:[0,1,1]
	v_pk_fma_f32 v[254:255], v[38:39], v[206:207], v[254:255] op_sel_hi:[0,1,1]
	v_pk_fma_f32 v[200:201], v[32:33], v[200:201], v[232:233] op_sel:[1,1,0] op_sel_hi:[1,0,1] neg_lo:[1,0,0]
	v_pk_fma_f32 v[202:203], v[34:35], v[202:203], v[234:235] op_sel:[1,1,0] op_sel_hi:[1,0,1] neg_lo:[1,0,0]
	v_pk_fma_f32 v[204:205], v[36:37], v[204:205], v[244:245] op_sel:[1,1,0] op_sel_hi:[1,0,1] neg_lo:[1,0,0]
	v_pk_fma_f32 v[206:207], v[38:39], v[206:207], v[254:255] op_sel:[1,1,0] op_sel_hi:[1,0,1] neg_lo:[1,0,0]
	v_cvt_pk_bf16_f32 v124, v200, v201
	v_cvt_pk_bf16_f32 v125, v202, v203
	v_cvt_pk_bf16_f32 v126, v204, v205
	v_cvt_pk_bf16_f32 v127, v206, v207
	ds_write_b128 v241, v[124:127] offset:512
	v_pk_mov_b32 v[232:233], v[138:139], v[154:155] op_sel:[1,1]
	v_pk_mov_b32 v[234:235], v[142:143], v[158:159] op_sel:[1,1]
	v_pk_mov_b32 v[244:245], v[146:147], v[162:163] op_sel:[1,1]
	v_pk_mov_b32 v[254:255], v[150:151], v[166:167] op_sel:[1,1]
	v_pk_fma_f32 v[232:233], v[32:33], v[200:201], v[232:233] op_sel_hi:[0,1,1]
	v_pk_fma_f32 v[234:235], v[34:35], v[202:203], v[234:235] op_sel_hi:[0,1,1]
	v_pk_fma_f32 v[244:245], v[36:37], v[204:205], v[244:245] op_sel_hi:[0,1,1]
	v_pk_fma_f32 v[254:255], v[38:39], v[206:207], v[254:255] op_sel_hi:[0,1,1]
	v_pk_fma_f32 v[200:201], v[32:33], v[200:201], v[232:233] op_sel:[1,1,0] op_sel_hi:[1,0,1] neg_lo:[1,0,0]
	v_pk_fma_f32 v[202:203], v[34:35], v[202:203], v[234:235] op_sel:[1,1,0] op_sel_hi:[1,0,1] neg_lo:[1,0,0]
	v_pk_fma_f32 v[204:205], v[36:37], v[204:205], v[244:245] op_sel:[1,1,0] op_sel_hi:[1,0,1] neg_lo:[1,0,0]
	v_pk_fma_f32 v[206:207], v[38:39], v[206:207], v[254:255] op_sel:[1,1,0] op_sel_hi:[1,0,1] neg_lo:[1,0,0]
	v_cvt_pk_bf16_f32 v124, v200, v201
	v_cvt_pk_bf16_f32 v125, v202, v203
	v_cvt_pk_bf16_f32 v126, v204, v205
	v_cvt_pk_bf16_f32 v127, v206, v207
	ds_write_b128 v241, v[124:127] offset:768
	global_load_dwordx4 v[56:59], v238, s[20:21]
	v_add_u32_e32 v238, v238, v243
	s_waitcnt vmcnt(33)
; __device__ __forceinline__ unsigned f2bf(float f) { unsigned u = __builtin_bit_cast(unsigned, f); return (u + 0x7fffu + ((u >> 16) & 1u)) >> 16; }
; __device__ __forceinline__ bf16x8 pack8(const float (&f)[8]) { u32x4 h; h.x = pk2(f[0], f[1]); h.y = pk2(f[2], f[3]); h.z = pk2(f[4], f[5]); h.w = pk2(f[6], f[7]); return __builtin_bit_cast(bf16x8, h); }
; template <bool FINAL> __device__ __forceinline__ void phase_s5_scan(const Fr& F) {
;     ...
;         for (int sub = 0; sub < 4; ++sub) {
;             const bf16x8 A1 = __builtin_bit_cast(bf16x8, uc[sub]);
; #pragma unroll
;             for (int nt = 0; nt < 8; ++nt) {
;                 f32x4 acc = {0.f, 0.f, 0.f, 0.f};
;                 acc = __builtin_amdgcn_mfma_f32_16x16x32_bf16(A1, B1[nt], acc, 0, 0, 0);
; #pragma unroll
;                 for (int reg = 0; reg < 4; ++reg) BUl[(4 * lq + reg) * 132 + 16 * nt + l15] = acc[reg];
;             }
;             asm volatile("s_waitcnt lgkmcnt(0)" ::: "memory");
; #pragma unroll 4
;             for (int jj = 0; jj < 16; ++jj) {
;                 const float br_ = BUl[jj * 132 + lane], bi_ = BUl[jj * 132 + 64 + lane];
;                 const float nr = ar * xr - ai * xi + br_, ni = ar * xi + ai * xr + bi_; xr = nr; xi = ni;
;                 if (FINAL) { BUl[jj * 132 + lane] = xr; BUl[jj * 132 + 64 + lane] = xi; }
;             }
;             if (FINAL) {
;                 asm volatile("s_waitcnt lgkmcnt(0)" ::: "memory");
;                 f32x4 acc = {0.f, 0.f, 0.f, 0.f};
; #pragma unroll
;                 for (int ks = 0; ks < 4; ++ks) {
;                     const f32x4 t0 = *(const f32x4*)(BUl + l15 * 132 + 32 * ks + 8 * lq), t1 = *(const f32x4*)(BUl + l15 * 132 + 32 * ks + 8 * lq + 4);
;                     const float xf[8] = {t0.x, t0.y, t0.z, t0.w, t1.x, t1.y, t1.z, t1.w};
;                     acc = __builtin_amdgcn_mfma_f32_16x16x32_bf16(pack8(xf), Chi[ks], acc, 0, 0, 0);
;                 }
; #pragma unroll
;                 for (int reg = 0; reg < 4; ++reg) { const int tok = tokof(s, chunk * 64 + sub * 16 + 4 * lq + reg);
;                     Yb[((size_t)b * TB + tok) * D + g * 16 + l15] = (bf16)f2bf(acc[reg]); }
;                 asm volatile("s_waitcnt lgkmcnt(0)" ::: "memory");
	v_mfma_f32_16x16x32_bf16 v[136:139], v[64:67], v[0:3], 0
	v_mfma_f32_16x16x32_bf16 v[140:143], v[64:67], v[4:7], 0
	v_mfma_f32_16x16x32_bf16 v[144:147], v[64:67], v[8:11], 0
	v_mfma_f32_16x16x32_bf16 v[148:151], v[64:67], v[12:15], 0
	v_mfma_f32_16x16x32_bf16 v[152:155], v[64:67], v[16:19], 0
	v_mfma_f32_16x16x32_bf16 v[156:159], v[64:67], v[20:23], 0
	v_mfma_f32_16x16x32_bf16 v[160:163], v[64:67], v[24:27], 0
	v_mfma_f32_16x16x32_bf16 v[164:167], v[64:67], v[28:31], 0
	ds_read_b128 v[216:219], v242 offset:0
	ds_read_b128 v[220:223], v242 offset:64
	ds_read_b128 v[224:227], v242 offset:128
	ds_read_b128 v[228:231], v242 offset:192
	v_pk_mov_b32 v[232:233], v[168:169], v[184:185] op_sel:[0,0]
	v_pk_mov_b32 v[234:235], v[172:173], v[188:189] op_sel:[0,0]
	v_pk_mov_b32 v[244:245], v[176:177], v[192:193] op_sel:[0,0]
	v_pk_mov_b32 v[254:255], v[180:181], v[196:197] op_sel:[0,0]
	v_pk_fma_f32 v[232:233], v[32:33], v[200:201], v[232:233] op_sel_hi:[0,1,1]
	v_pk_fma_f32 v[234:235], v[34:35], v[202:203], v[234:235] op_sel_hi:[0,1,1]
	v_pk_fma_f32 v[244:245], v[36:37], v[204:205], v[244:245] op_sel_hi:[0,1,1]
	v_pk_fma_f32 v[254:255], v[38:39], v[206:207], v[254:255] op_sel_hi:[0,1,1]
	v_pk_fma_f32 v[200:201], v[32:33], v[200:201], v[232:233] op_sel:[1,1,0] op_sel_hi:[1,0,1] neg_lo:[1,0,0]
	v_pk_fma_f32 v[202:203], v[34:35], v[202:203], v[234:235] op_sel:[1,1,0] op_sel_hi:[1,0,1] neg_lo:[1,0,0]
	v_pk_fma_f32 v[204:205], v[36:37], v[204:205], v[244:245] op_sel:[1,1,0] op_sel_hi:[1,0,1] neg_lo:[1,0,0]
	v_pk_fma_f32 v[206:207], v[38:39], v[206:207], v[254:255] op_sel:[1,1,0] op_sel_hi:[1,0,1] neg_lo:[1,0,0]
	v_cvt_pk_bf16_f32 v124, v200, v201
	v_cvt_pk_bf16_f32 v125, v202, v203
	v_cvt_pk_bf16_f32 v126, v204, v205
	v_cvt_pk_bf16_f32 v127, v206, v207
	ds_write_b128 v241, v[124:127] offset:4096
	v_pk_mov_b32 v[232:233], v[168:169], v[184:185] op_sel:[1,1]
	v_pk_mov_b32 v[234:235], v[172:173], v[188:189] op_sel:[1,1]
	v_pk_mov_b32 v[244:245], v[176:177], v[192:193] op_sel:[1,1]
	v_pk_mov_b32 v[254:255], v[180:181], v[196:197] op_sel:[1,1]
	v_pk_fma_f32 v[232:233], v[32:33], v[200:201], v[232:233] op_sel_hi:[0,1,1]
	v_pk_fma_f32 v[234:235], v[34:35], v[202:203], v[234:235] op_sel_hi:[0,1,1]
	v_pk_fma_f32 v[244:245], v[36:37], v[204:205], v[244:245] op_sel_hi:[0,1,1]
	v_pk_fma_f32 v[254:255], v[38:39], v[206:207], v[254:255] op_sel_hi:[0,1,1]
	v_pk_fma_f32 v[200:201], v[32:33], v[200:201], v[232:233] op_sel:[1,1,0] op_sel_hi:[1,0,1] neg_lo:[1,0,0]
	v_pk_fma_f32 v[202:203], v[34:35], v[202:203], v[234:235] op_sel:[1,1,0] op_sel_hi:[1,0,1] neg_lo:[1,0,0]
	v_pk_fma_f32 v[204:205], v[36:37], v[204:205], v[244:245] op_sel:[1,1,0] op_sel_hi:[1,0,1] neg_lo:[1,0,0]
	v_pk_fma_f32 v[206:207], v[38:39], v[206:207], v[254:255] op_sel:[1,1,0] op_sel_hi:[1,0,1] neg_lo:[1,0,0]
	v_cvt_pk_bf16_f32 v124, v200, v201
	v_cvt_pk_bf16_f32 v125, v202, v203
	v_cvt_pk_bf16_f32 v126, v204, v205
	v_cvt_pk_bf16_f32 v127, v206, v207
	ds_write_b128 v241, v[124:127] offset:4352
	s_waitcnt lgkmcnt(2)
	v_mfma_f32_16x16x32_bf16 v[120:123], v[40:43], v[216:219], 0
	v_mfma_f32_16x16x32_bf16 v[120:123], v[44:47], v[220:223], v[120:123]
	v_mfma_f32_16x16x32_bf16 v[120:123], v[48:51], v[224:227], v[120:123]
	v_mfma_f32_16x16x32_bf16 v[120:123], v[52:55], v[228:231], v[120:123]
	v_pk_mov_b32 v[232:233], v[170:171], v[186:187] op_sel:[0,0]
	v_pk_mov_b32 v[234:235], v[174:175], v[190:191] op_sel:[0,0]
	v_pk_mov_b32 v[244:245], v[178:179], v[194:195] op_sel:[0,0]
	v_pk_mov_b32 v[254:255], v[182:183], v[198:199] op_sel:[0,0]
	v_pk_fma_f32 v[232:233], v[32:33], v[200:201], v[232:233] op_sel_hi:[0,1,1]
	v_pk_fma_f32 v[234:235], v[34:35], v[202:203], v[234:235] op_sel_hi:[0,1,1]
	v_pk_fma_f32 v[244:245], v[36:37], v[204:205], v[244:245] op_sel_hi:[0,1,1]
	v_pk_fma_f32 v[254:255], v[38:39], v[206:207], v[254:255] op_sel_hi:[0,1,1]
	v_pk_fma_f32 v[200:201], v[32:33], v[200:201], v[232:233] op_sel:[1,1,0] op_sel_hi:[1,0,1] neg_lo:[1,0,0]
	v_pk_fma_f32 v[202:203], v[34:35], v[202:203], v[234:235] op_sel:[1,1,0] op_sel_hi:[1,0,1] neg_lo:[1,0,0]
	v_pk_fma_f32 v[204:205], v[36:37], v[204:205], v[244:245] op_sel:[1,1,0] op_sel_hi:[1,0,1] neg_lo:[1,0,0]
	v_pk_fma_f32 v[206:207], v[38:39], v[206:207], v[254:255] op_sel:[1,1,0] op_sel_hi:[1,0,1] neg_lo:[1,0,0]
	v_cvt_pk_bf16_f32 v124, v200, v201
	v_cvt_pk_bf16_f32 v125, v202, v203
	v_cvt_pk_bf16_f32 v126, v204, v205
	v_cvt_pk_bf16_f32 v127, v206, v207
	ds_write_b128 v241, v[124:127] offset:4608
	v_pk_mov_b32 v[232:233], v[170:171], v[186:187] op_sel:[1,1]
	v_pk_mov_b32 v[234:235], v[174:175], v[190:191] op_sel:[1,1]
	v_pk_mov_b32 v[244:245], v[178:179], v[194:195] op_sel:[1,1]
	v_pk_mov_b32 v[254:255], v[182:183], v[198:199] op_sel:[1,1]
	v_pk_fma_f32 v[232:233], v[32:33], v[200:201], v[232:233] op_sel_hi:[0,1,1]
	v_pk_fma_f32 v[234:235], v[34:35], v[202:203], v[234:235] op_sel_hi:[0,1,1]
	v_pk_fma_f32 v[244:245], v[36:37], v[204:205], v[244:245] op_sel_hi:[0,1,1]
	v_pk_fma_f32 v[254:255], v[38:39], v[206:207], v[254:255] op_sel_hi:[0,1,1]
	v_pk_fma_f32 v[200:201], v[32:33], v[200:201], v[232:233] op_sel:[1,1,0] op_sel_hi:[1,0,1] neg_lo:[1,0,0]
	v_pk_fma_f32 v[202:203], v[34:35], v[202:203], v[234:235] op_sel:[1,1,0] op_sel_hi:[1,0,1] neg_lo:[1,0,0]
	v_pk_fma_f32 v[204:205], v[36:37], v[204:205], v[244:245] op_sel:[1,1,0] op_sel_hi:[1,0,1] neg_lo:[1,0,0]
	v_pk_fma_f32 v[206:207], v[38:39], v[206:207], v[254:255] op_sel:[1,1,0] op_sel_hi:[1,0,1] neg_lo:[1,0,0]
	v_cvt_pk_bf16_f32 v124, v200, v201
	v_cvt_pk_bf16_f32 v125, v202, v203
	v_cvt_pk_bf16_f32 v126, v204, v205
	v_cvt_pk_bf16_f32 v127, v206, v207
	ds_write_b128 v241, v[124:127] offset:4864
	global_load_dwordx4 v[60:63], v238, s[20:21]
	v_add_u32_e32 v238, v238, v243
	v_cvt_pk_bf16_f32 v124, v120, v121
	v_cvt_pk_bf16_f32 v125, v122, v123
	s_nop 0
	global_store_dwordx2 v239, v[124:125], s[24:25]
	v_add_u32_e32 v239, v239, v243
	s_waitcnt vmcnt(33)
; __device__ __forceinline__ unsigned f2bf(float f) { unsigned u = __builtin_bit_cast(unsigned, f); return (u + 0x7fffu + ((u >> 16) & 1u)) >> 16; }
; __device__ __forceinline__ bf16x8 pack8(const float (&f)[8]) { u32x4 h; h.x = pk2(f[0], f[1]); h.y = pk2(f[2], f[3]); h.z = pk2(f[4], f[5]); h.w = pk2(f[6], f[7]); return __builtin_bit_cast(bf16x8, h); }
; template <bool FINAL> __device__ __forceinline__ void phase_s5_scan(const Fr& F) {
;     ...
;         for (int sub = 0; sub < 4; ++sub) {
;             const bf16x8 A1 = __builtin_bit_cast(bf16x8, uc[sub]);
; #pragma unroll
;             for (int nt = 0; nt < 8; ++nt) {
;                 f32x4 acc = {0.f, 0.f, 0.f, 0.f};
;                 acc = __builtin_amdgcn_mfma_f32_16x16x32_bf16(A1, B1[nt], acc, 0, 0, 0);
; #pragma unroll
;                 for (int reg = 0; reg < 4; ++reg) BUl[(4 * lq + reg) * 132 + 16 * nt + l15] = acc[reg];
;             }
;             asm volatile("s_waitcnt lgkmcnt(0)" ::: "memory");
; #pragma unroll 4
;             for (int jj = 0; jj < 16; ++jj) {
;                 const float br_ = BUl[jj * 132 + lane], bi_ = BUl[jj * 132 + 64 + lane];
;                 const float nr = ar * xr - ai * xi + br_, ni = ar * xi + ai * xr + bi_; xr = nr; xi = ni;
;                 if (FINAL) { BUl[jj * 132 + lane] = xr; BUl[jj * 132 + 64 + lane] = xi; }
;             }
;             if (FINAL) {
;                 asm volatile("s_waitcnt lgkmcnt(0)" ::: "memory");
;                 f32x4 acc = {0.f, 0.f, 0.f, 0.f};
; #pragma unroll
;                 for (int ks = 0; ks < 4; ++ks) {
;                     const f32x4 t0 = *(const f32x4*)(BUl + l15 * 132 + 32 * ks + 8 * lq), t1 = *(const f32x4*)(BUl + l15 * 132 + 32 * ks + 8 * lq + 4);
;                     const float xf[8] = {t0.x, t0.y, t0.z, t0.w, t1.x, t1.y, t1.z, t1.w};
;                     acc = __builtin_amdgcn_mfma_f32_16x16x32_bf16(pack8(xf), Chi[ks], acc, 0, 0, 0);
;                 }
; #pragma unroll
;                 for (int reg = 0; reg < 4; ++reg) { const int tok = tokof(s, chunk * 64 + sub * 16 + 4 * lq + reg);
;                     Yb[((size_t)b * TB + tok) * D + g * 16 + l15] = (bf16)f2bf(acc[reg]); }
;                 asm volatile("s_waitcnt lgkmcnt(0)" ::: "memory");
	v_mfma_f32_16x16x32_bf16 v[168:171], v[68:71], v[0:3], 0
	v_mfma_f32_16x16x32_bf16 v[172:175], v[68:71], v[4:7], 0
	v_mfma_f32_16x16x32_bf16 v[176:179], v[68:71], v[8:11], 0
	v_mfma_f32_16x16x32_bf16 v[180:183], v[68:71], v[12:15], 0
	v_mfma_f32_16x16x32_bf16 v[184:187], v[68:71], v[16:19], 0
	v_mfma_f32_16x16x32_bf16 v[188:191], v[68:71], v[20:23], 0
	v_mfma_f32_16x16x32_bf16 v[192:195], v[68:71], v[24:27], 0
	v_mfma_f32_16x16x32_bf16 v[196:199], v[68:71], v[28:31], 0
	ds_read_b128 v[216:219], v242 offset:4096
	ds_read_b128 v[220:223], v242 offset:4160
	ds_read_b128 v[224:227], v242 offset:4224
	ds_read_b128 v[228:231], v242 offset:4288
	v_pk_mov_b32 v[232:233], v[136:137], v[152:153] op_sel:[0,0]
	v_pk_mov_b32 v[234:235], v[140:141], v[156:157] op_sel:[0,0]
	v_pk_mov_b32 v[244:245], v[144:145], v[160:161] op_sel:[0,0]
	v_pk_mov_b32 v[254:255], v[148:149], v[164:165] op_sel:[0,0]
	v_pk_fma_f32 v[232:233], v[32:33], v[200:201], v[232:233] op_sel_hi:[0,1,1]
	v_pk_fma_f32 v[234:235], v[34:35], v[202:203], v[234:235] op_sel_hi:[0,1,1]
	v_pk_fma_f32 v[244:245], v[36:37], v[204:205], v[244:245] op_sel_hi:[0,1,1]
	v_pk_fma_f32 v[254:255], v[38:39], v[206:207], v[254:255] op_sel_hi:[0,1,1]
	v_pk_fma_f32 v[200:201], v[32:33], v[200:201], v[232:233] op_sel:[1,1,0] op_sel_hi:[1,0,1] neg_lo:[1,0,0]
	v_pk_fma_f32 v[202:203], v[34:35], v[202:203], v[234:235] op_sel:[1,1,0] op_sel_hi:[1,0,1] neg_lo:[1,0,0]
	v_pk_fma_f32 v[204:205], v[36:37], v[204:205], v[244:245] op_sel:[1,1,0] op_sel_hi:[1,0,1] neg_lo:[1,0,0]
	v_pk_fma_f32 v[206:207], v[38:39], v[206:207], v[254:255] op_sel:[1,1,0] op_sel_hi:[1,0,1] neg_lo:[1,0,0]
	v_cvt_pk_bf16_f32 v124, v200, v201
	v_cvt_pk_bf16_f32 v125, v202, v203
	v_cvt_pk_bf16_f32 v126, v204, v205
	v_cvt_pk_bf16_f32 v127, v206, v207
	ds_write_b128 v241, v[124:127] offset:0
	v_pk_mov_b32 v[232:233], v[136:137], v[152:153] op_sel:[1,1]
	v_pk_mov_b32 v[234:235], v[140:141], v[156:157] op_sel:[1,1]
	v_pk_mov_b32 v[244:245], v[144:145], v[160:161] op_sel:[1,1]
	v_pk_mov_b32 v[254:255], v[148:149], v[164:165] op_sel:[1,1]
	v_pk_fma_f32 v[232:233], v[32:33], v[200:201], v[232:233] op_sel_hi:[0,1,1]
	v_pk_fma_f32 v[234:235], v[34:35], v[202:203], v[234:235] op_sel_hi:[0,1,1]
	v_pk_fma_f32 v[244:245], v[36:37], v[204:205], v[244:245] op_sel_hi:[0,1,1]
	v_pk_fma_f32 v[254:255], v[38:39], v[206:207], v[254:255] op_sel_hi:[0,1,1]
	v_pk_fma_f32 v[200:201], v[32:33], v[200:201], v[232:233] op_sel:[1,1,0] op_sel_hi:[1,0,1] neg_lo:[1,0,0]
	v_pk_fma_f32 v[202:203], v[34:35], v[202:203], v[234:235] op_sel:[1,1,0] op_sel_hi:[1,0,1] neg_lo:[1,0,0]
	v_pk_fma_f32 v[204:205], v[36:37], v[204:205], v[244:245] op_sel:[1,1,0] op_sel_hi:[1,0,1] neg_lo:[1,0,0]
	v_pk_fma_f32 v[206:207], v[38:39], v[206:207], v[254:255] op_sel:[1,1,0] op_sel_hi:[1,0,1] neg_lo:[1,0,0]
	v_cvt_pk_bf16_f32 v124, v200, v201
	v_cvt_pk_bf16_f32 v125, v202, v203
	v_cvt_pk_bf16_f32 v126, v204, v205
	v_cvt_pk_bf16_f32 v127, v206, v207
	ds_write_b128 v241, v[124:127] offset:256
	s_waitcnt lgkmcnt(2)
	v_mfma_f32_16x16x32_bf16 v[120:123], v[40:43], v[216:219], 0
	v_mfma_f32_16x16x32_bf16 v[120:123], v[44:47], v[220:223], v[120:123]
	v_mfma_f32_16x16x32_bf16 v[120:123], v[48:51], v[224:227], v[120:123]
	v_mfma_f32_16x16x32_bf16 v[120:123], v[52:55], v[228:231], v[120:123]
	v_pk_mov_b32 v[232:233], v[138:139], v[154:155] op_sel:[0,0]
	v_pk_mov_b32 v[234:235], v[142:143], v[158:159] op_sel:[0,0]
	v_pk_mov_b32 v[244:245], v[146:147], v[162:163] op_sel:[0,0]
	v_pk_mov_b32 v[254:255], v[150:151], v[166:167] op_sel:[0,0]
	v_pk_fma_f32 v[232:233], v[32:33], v[200:201], v[232:233] op_sel_hi:[0,1,1]
	v_pk_fma_f32 v[234:235], v[34:35], v[202:203], v[234:235] op_sel_hi:[0,1,1]
	v_pk_fma_f32 v[244:245], v[36:37], v[204:205], v[244:245] op_sel_hi:[0,1,1]
	v_pk_fma_f32 v[254:255], v[38:39], v[206:207], v[254:255] op_sel_hi:[0,1,1]
	v_pk_fma_f32 v[200:201], v[32:33], v[200:201], v[232:233] op_sel:[1,1,0] op_sel_hi:[1,0,1] neg_lo:[1,0,0]
	v_pk_fma_f32 v[202:203], v[34:35], v[202:203], v[234:235] op_sel:[1,1,0] op_sel_hi:[1,0,1] neg_lo:[1,0,0]
	v_pk_fma_f32 v[204:205], v[36:37], v[204:205], v[244:245] op_sel:[1,1,0] op_sel_hi:[1,0,1] neg_lo:[1,0,0]
	v_pk_fma_f32 v[206:207], v[38:39], v[206:207], v[254:255] op_sel:[1,1,0] op_sel_hi:[1,0,1] neg_lo:[1,0,0]
	v_cvt_pk_bf16_f32 v124, v200, v201
	v_cvt_pk_bf16_f32 v125, v202, v203
	v_cvt_pk_bf16_f32 v126, v204, v205
	v_cvt_pk_bf16_f32 v127, v206, v207
	ds_write_b128 v241, v[124:127] offset:512
	v_pk_mov_b32 v[232:233], v[138:139], v[154:155] op_sel:[1,1]
	v_pk_mov_b32 v[234:235], v[142:143], v[158:159] op_sel:[1,1]
	v_pk_mov_b32 v[244:245], v[146:147], v[162:163] op_sel:[1,1]
	v_pk_mov_b32 v[254:255], v[150:151], v[166:167] op_sel:[1,1]
	v_pk_fma_f32 v[232:233], v[32:33], v[200:201], v[232:233] op_sel_hi:[0,1,1]
	v_pk_fma_f32 v[234:235], v[34:35], v[202:203], v[234:235] op_sel_hi:[0,1,1]
	v_pk_fma_f32 v[244:245], v[36:37], v[204:205], v[244:245] op_sel_hi:[0,1,1]
	v_pk_fma_f32 v[254:255], v[38:39], v[206:207], v[254:255] op_sel_hi:[0,1,1]
	v_pk_fma_f32 v[200:201], v[32:33], v[200:201], v[232:233] op_sel:[1,1,0] op_sel_hi:[1,0,1] neg_lo:[1,0,0]
	v_pk_fma_f32 v[202:203], v[34:35], v[202:203], v[234:235] op_sel:[1,1,0] op_sel_hi:[1,0,1] neg_lo:[1,0,0]
	v_pk_fma_f32 v[204:205], v[36:37], v[204:205], v[244:245] op_sel:[1,1,0] op_sel_hi:[1,0,1] neg_lo:[1,0,0]
	v_pk_fma_f32 v[206:207], v[38:39], v[206:207], v[254:255] op_sel:[1,1,0] op_sel_hi:[1,0,1] neg_lo:[1,0,0]
	v_cvt_pk_bf16_f32 v124, v200, v201
	v_cvt_pk_bf16_f32 v125, v202, v203
	v_cvt_pk_bf16_f32 v126, v204, v205
	v_cvt_pk_bf16_f32 v127, v206, v207
	ds_write_b128 v241, v[124:127] offset:768
	global_load_dwordx4 v[64:67], v238, s[20:21]
	v_add_u32_e32 v238, v238, v243
	v_cvt_pk_bf16_f32 v124, v120, v121
	v_cvt_pk_bf16_f32 v125, v122, v123
	s_nop 0
	global_store_dwordx2 v239, v[124:125], s[24:25]
	v_add_u32_e32 v239, v239, v243
	s_waitcnt vmcnt(33)
; __device__ __forceinline__ unsigned f2bf(float f) { unsigned u = __builtin_bit_cast(unsigned, f); return (u + 0x7fffu + ((u >> 16) & 1u)) >> 16; }
; __device__ __forceinline__ bf16x8 pack8(const float (&f)[8]) { u32x4 h; h.x = pk2(f[0], f[1]); h.y = pk2(f[2], f[3]); h.z = pk2(f[4], f[5]); h.w = pk2(f[6], f[7]); return __builtin_bit_cast(bf16x8, h); }
; template <bool FINAL> __device__ __forceinline__ void phase_s5_scan(const Fr& F) {
;     ...
;         for (int sub = 0; sub < 4; ++sub) {
;             const bf16x8 A1 = __builtin_bit_cast(bf16x8, uc[sub]);
; #pragma unroll
;             for (int nt = 0; nt < 8; ++nt) {
;                 f32x4 acc = {0.f, 0.f, 0.f, 0.f};
;                 acc = __builtin_amdgcn_mfma_f32_16x16x32_bf16(A1, B1[nt], acc, 0, 0, 0);
; #pragma unroll
;                 for (int reg = 0; reg < 4; ++reg) BUl[(4 * lq + reg) * 132 + 16 * nt + l15] = acc[reg];
;             }
;             asm volatile("s_waitcnt lgkmcnt(0)" ::: "memory");
; #pragma unroll 4
;             for (int jj = 0; jj < 16; ++jj) {
;                 const float br_ = BUl[jj * 132 + lane], bi_ = BUl[jj * 132 + 64 + lane];
;                 const float nr = ar * xr - ai * xi + br_, ni = ar * xi + ai * xr + bi_; xr = nr; xi = ni;
;                 if (FINAL) { BUl[jj * 132 + lane] = xr; BUl[jj * 132 + 64 + lane] = xi; }
;             }
;             if (FINAL) {
;                 asm volatile("s_waitcnt lgkmcnt(0)" ::: "memory");
;                 f32x4 acc = {0.f, 0.f, 0.f, 0.f};
; #pragma unroll
;                 for (int ks = 0; ks < 4; ++ks) {
;                     const f32x4 t0 = *(const f32x4*)(BUl + l15 * 132 + 32 * ks + 8 * lq), t1 = *(const f32x4*)(BUl + l15 * 132 + 32 * ks + 8 * lq + 4);
;                     const float xf[8] = {t0.x, t0.y, t0.z, t0.w, t1.x, t1.y, t1.z, t1.w};
;                     acc = __builtin_amdgcn_mfma_f32_16x16x32_bf16(pack8(xf), Chi[ks], acc, 0, 0, 0);
;                 }
; #pragma unroll
;                 for (int reg = 0; reg < 4; ++reg) { const int tok = tokof(s, chunk * 64 + sub * 16 + 4 * lq + reg);
;                     Yb[((size_t)b * TB + tok) * D + g * 16 + l15] = (bf16)f2bf(acc[reg]); }
;                 asm volatile("s_waitcnt lgkmcnt(0)" ::: "memory");
	v_mfma_f32_16x16x32_bf16 v[136:139], v[72:75], v[0:3], 0
	v_mfma_f32_16x16x32_bf16 v[140:143], v[72:75], v[4:7], 0
	v_mfma_f32_16x16x32_bf16 v[144:147], v[72:75], v[8:11], 0
	v_mfma_f32_16x16x32_bf16 v[148:151], v[72:75], v[12:15], 0
	v_mfma_f32_16x16x32_bf16 v[152:155], v[72:75], v[16:19], 0
	v_mfma_f32_16x16x32_bf16 v[156:159], v[72:75], v[20:23], 0
	v_mfma_f32_16x16x32_bf16 v[160:163], v[72:75], v[24:27], 0
	v_mfma_f32_16x16x32_bf16 v[164:167], v[72:75], v[28:31], 0
	ds_read_b128 v[216:219], v242 offset:0
	ds_read_b128 v[220:223], v242 offset:64
	ds_read_b128 v[224:227], v242 offset:128
	ds_read_b128 v[228:231], v242 offset:192
	v_pk_mov_b32 v[232:233], v[168:169], v[184:185] op_sel:[0,0]
	v_pk_mov_b32 v[234:235], v[172:173], v[188:189] op_sel:[0,0]
	v_pk_mov_b32 v[244:245], v[176:177], v[192:193] op_sel:[0,0]
	v_pk_mov_b32 v[254:255], v[180:181], v[196:197] op_sel:[0,0]
	v_pk_fma_f32 v[232:233], v[32:33], v[200:201], v[232:233] op_sel_hi:[0,1,1]
	v_pk_fma_f32 v[234:235], v[34:35], v[202:203], v[234:235] op_sel_hi:[0,1,1]
	v_pk_fma_f32 v[244:245], v[36:37], v[204:205], v[244:245] op_sel_hi:[0,1,1]
	v_pk_fma_f32 v[254:255], v[38:39], v[206:207], v[254:255] op_sel_hi:[0,1,1]
	v_pk_fma_f32 v[200:201], v[32:33], v[200:201], v[232:233] op_sel:[1,1,0] op_sel_hi:[1,0,1] neg_lo:[1,0,0]
	v_pk_fma_f32 v[202:203], v[34:35], v[202:203], v[234:235] op_sel:[1,1,0] op_sel_hi:[1,0,1] neg_lo:[1,0,0]
	v_pk_fma_f32 v[204:205], v[36:37], v[204:205], v[244:245] op_sel:[1,1,0] op_sel_hi:[1,0,1] neg_lo:[1,0,0]
	v_pk_fma_f32 v[206:207], v[38:39], v[206:207], v[254:255] op_sel:[1,1,0] op_sel_hi:[1,0,1] neg_lo:[1,0,0]
	v_cvt_pk_bf16_f32 v124, v200, v201
	v_cvt_pk_bf16_f32 v125, v202, v203
	v_cvt_pk_bf16_f32 v126, v204, v205
	v_cvt_pk_bf16_f32 v127, v206, v207
	ds_write_b128 v241, v[124:127] offset:4096
	v_pk_mov_b32 v[232:233], v[168:169], v[184:185] op_sel:[1,1]
	v_pk_mov_b32 v[234:235], v[172:173], v[188:189] op_sel:[1,1]
	v_pk_mov_b32 v[244:245], v[176:177], v[192:193] op_sel:[1,1]
	v_pk_mov_b32 v[254:255], v[180:181], v[196:197] op_sel:[1,1]
	v_pk_fma_f32 v[232:233], v[32:33], v[200:201], v[232:233] op_sel_hi:[0,1,1]
	v_pk_fma_f32 v[234:235], v[34:35], v[202:203], v[234:235] op_sel_hi:[0,1,1]
	v_pk_fma_f32 v[244:245], v[36:37], v[204:205], v[244:245] op_sel_hi:[0,1,1]
	v_pk_fma_f32 v[254:255], v[38:39], v[206:207], v[254:255] op_sel_hi:[0,1,1]
	v_pk_fma_f32 v[200:201], v[32:33], v[200:201], v[232:233] op_sel:[1,1,0] op_sel_hi:[1,0,1] neg_lo:[1,0,0]
	v_pk_fma_f32 v[202:203], v[34:35], v[202:203], v[234:235] op_sel:[1,1,0] op_sel_hi:[1,0,1] neg_lo:[1,0,0]
	v_pk_fma_f32 v[204:205], v[36:37], v[204:205], v[244:245] op_sel:[1,1,0] op_sel_hi:[1,0,1] neg_lo:[1,0,0]
	v_pk_fma_f32 v[206:207], v[38:39], v[206:207], v[254:255] op_sel:[1,1,0] op_sel_hi:[1,0,1] neg_lo:[1,0,0]
	v_cvt_pk_bf16_f32 v124, v200, v201
	v_cvt_pk_bf16_f32 v125, v202, v203
	v_cvt_pk_bf16_f32 v126, v204, v205
	v_cvt_pk_bf16_f32 v127, v206, v207
	ds_write_b128 v241, v[124:127] offset:4352
	s_waitcnt lgkmcnt(2)
	v_mfma_f32_16x16x32_bf16 v[120:123], v[40:43], v[216:219], 0
	v_mfma_f32_16x16x32_bf16 v[120:123], v[44:47], v[220:223], v[120:123]
	v_mfma_f32_16x16x32_bf16 v[120:123], v[48:51], v[224:227], v[120:123]
	v_mfma_f32_16x16x32_bf16 v[120:123], v[52:55], v[228:231], v[120:123]
	v_pk_mov_b32 v[232:233], v[170:171], v[186:187] op_sel:[0,0]
	v_pk_mov_b32 v[234:235], v[174:175], v[190:191] op_sel:[0,0]
	v_pk_mov_b32 v[244:245], v[178:179], v[194:195] op_sel:[0,0]
	v_pk_mov_b32 v[254:255], v[182:183], v[198:199] op_sel:[0,0]
	v_pk_fma_f32 v[232:233], v[32:33], v[200:201], v[232:233] op_sel_hi:[0,1,1]
	v_pk_fma_f32 v[234:235], v[34:35], v[202:203], v[234:235] op_sel_hi:[0,1,1]
	v_pk_fma_f32 v[244:245], v[36:37], v[204:205], v[244:245] op_sel_hi:[0,1,1]
	v_pk_fma_f32 v[254:255], v[38:39], v[206:207], v[254:255] op_sel_hi:[0,1,1]
	v_pk_fma_f32 v[200:201], v[32:33], v[200:201], v[232:233] op_sel:[1,1,0] op_sel_hi:[1,0,1] neg_lo:[1,0,0]
	v_pk_fma_f32 v[202:203], v[34:35], v[202:203], v[234:235] op_sel:[1,1,0] op_sel_hi:[1,0,1] neg_lo:[1,0,0]
	v_pk_fma_f32 v[204:205], v[36:37], v[204:205], v[244:245] op_sel:[1,1,0] op_sel_hi:[1,0,1] neg_lo:[1,0,0]
	v_pk_fma_f32 v[206:207], v[38:39], v[206:207], v[254:255] op_sel:[1,1,0] op_sel_hi:[1,0,1] neg_lo:[1,0,0]
	v_cvt_pk_bf16_f32 v124, v200, v201
	v_cvt_pk_bf16_f32 v125, v202, v203
	v_cvt_pk_bf16_f32 v126, v204, v205
	v_cvt_pk_bf16_f32 v127, v206, v207
	ds_write_b128 v241, v[124:127] offset:4608
	v_pk_mov_b32 v[232:233], v[170:171], v[186:187] op_sel:[1,1]
	v_pk_mov_b32 v[234:235], v[174:175], v[190:191] op_sel:[1,1]
	v_pk_mov_b32 v[244:245], v[178:179], v[194:195] op_sel:[1,1]
	v_pk_mov_b32 v[254:255], v[182:183], v[198:199] op_sel:[1,1]
	v_pk_fma_f32 v[232:233], v[32:33], v[200:201], v[232:233] op_sel_hi:[0,1,1]
	v_pk_fma_f32 v[234:235], v[34:35], v[202:203], v[234:235] op_sel_hi:[0,1,1]
	v_pk_fma_f32 v[244:245], v[36:37], v[204:205], v[244:245] op_sel_hi:[0,1,1]
	v_pk_fma_f32 v[254:255], v[38:39], v[206:207], v[254:255] op_sel_hi:[0,1,1]
	v_pk_fma_f32 v[200:201], v[32:33], v[200:201], v[232:233] op_sel:[1,1,0] op_sel_hi:[1,0,1] neg_lo:[1,0,0]
	v_pk_fma_f32 v[202:203], v[34:35], v[202:203], v[234:235] op_sel:[1,1,0] op_sel_hi:[1,0,1] neg_lo:[1,0,0]
	v_pk_fma_f32 v[204:205], v[36:37], v[204:205], v[244:245] op_sel:[1,1,0] op_sel_hi:[1,0,1] neg_lo:[1,0,0]
	v_pk_fma_f32 v[206:207], v[38:39], v[206:207], v[254:255] op_sel:[1,1,0] op_sel_hi:[1,0,1] neg_lo:[1,0,0]
	v_cvt_pk_bf16_f32 v124, v200, v201
	v_cvt_pk_bf16_f32 v125, v202, v203
	v_cvt_pk_bf16_f32 v126, v204, v205
	v_cvt_pk_bf16_f32 v127, v206, v207
	ds_write_b128 v241, v[124:127] offset:4864
	global_load_dwordx4 v[68:71], v238, s[20:21]
	v_add_u32_e32 v238, v238, v243
	v_cvt_pk_bf16_f32 v124, v120, v121
	v_cvt_pk_bf16_f32 v125, v122, v123
	s_nop 0
	global_store_dwordx2 v239, v[124:125], s[24:25]
	v_add_u32_e32 v239, v239, v243
	s_waitcnt vmcnt(33)
; __device__ __forceinline__ unsigned f2bf(float f) { unsigned u = __builtin_bit_cast(unsigned, f); return (u + 0x7fffu + ((u >> 16) & 1u)) >> 16; }
; __device__ __forceinline__ bf16x8 pack8(const float (&f)[8]) { u32x4 h; h.x = pk2(f[0], f[1]); h.y = pk2(f[2], f[3]); h.z = pk2(f[4], f[5]); h.w = pk2(f[6], f[7]); return __builtin_bit_cast(bf16x8, h); }
; template <bool FINAL> __device__ __forceinline__ void phase_s5_scan(const Fr& F) {
;     ...
;         for (int sub = 0; sub < 4; ++sub) {
;             const bf16x8 A1 = __builtin_bit_cast(bf16x8, uc[sub]);
; #pragma unroll
;             for (int nt = 0; nt < 8; ++nt) {
;                 f32x4 acc = {0.f, 0.f, 0.f, 0.f};
;                 acc = __builtin_amdgcn_mfma_f32_16x16x32_bf16(A1, B1[nt], acc, 0, 0, 0);
; #pragma unroll
;                 for (int reg = 0; reg < 4; ++reg) BUl[(4 * lq + reg) * 132 + 16 * nt + l15] = acc[reg];
;             }
;             asm volatile("s_waitcnt lgkmcnt(0)" ::: "memory");
; #pragma unroll 4
;             for (int jj = 0; jj < 16; ++jj) {
;                 const float br_ = BUl[jj * 132 + lane], bi_ = BUl[jj * 132 + 64 + lane];
;                 const float nr = ar * xr - ai * xi + br_, ni = ar * xi + ai * xr + bi_; xr = nr; xi = ni;
;                 if (FINAL) { BUl[jj * 132 + lane] = xr; BUl[jj * 132 + 64 + lane] = xi; }
;             }
;             if (FINAL) {
;                 asm volatile("s_waitcnt lgkmcnt(0)" ::: "memory");
;                 f32x4 acc = {0.f, 0.f, 0.f, 0.f};
; #pragma unroll
;                 for (int ks = 0; ks < 4; ++ks) {
;                     const f32x4 t0 = *(const f32x4*)(BUl + l15 * 132 + 32 * ks + 8 * lq), t1 = *(const f32x4*)(BUl + l15 * 132 + 32 * ks + 8 * lq + 4);
;                     const float xf[8] = {t0.x, t0.y, t0.z, t0.w, t1.x, t1.y, t1.z, t1.w};
;                     acc = __builtin_amdgcn_mfma_f32_16x16x32_bf16(pack8(xf), Chi[ks], acc, 0, 0, 0);
;                 }
; #pragma unroll
;                 for (int reg = 0; reg < 4; ++reg) { const int tok = tokof(s, chunk * 64 + sub * 16 + 4 * lq + reg);
;                     Yb[((size_t)b * TB + tok) * D + g * 16 + l15] = (bf16)f2bf(acc[reg]); }
;                 asm volatile("s_waitcnt lgkmcnt(0)" ::: "memory");
	v_mfma_f32_16x16x32_bf16 v[168:171], v[76:79], v[0:3], 0
	v_mfma_f32_16x16x32_bf16 v[172:175], v[76:79], v[4:7], 0
	v_mfma_f32_16x16x32_bf16 v[176:179], v[76:79], v[8:11], 0
	v_mfma_f32_16x16x32_bf16 v[180:183], v[76:79], v[12:15], 0
	v_mfma_f32_16x16x32_bf16 v[184:187], v[76:79], v[16:19], 0
	v_mfma_f32_16x16x32_bf16 v[188:191], v[76:79], v[20:23], 0
	v_mfma_f32_16x16x32_bf16 v[192:195], v[76:79], v[24:27], 0
	v_mfma_f32_16x16x32_bf16 v[196:199], v[76:79], v[28:31], 0
	ds_read_b128 v[216:219], v242 offset:4096
	ds_read_b128 v[220:223], v242 offset:4160
	ds_read_b128 v[224:227], v242 offset:4224
	ds_read_b128 v[228:231], v242 offset:4288
	v_pk_mov_b32 v[232:233], v[136:137], v[152:153] op_sel:[0,0]
	v_pk_mov_b32 v[234:235], v[140:141], v[156:157] op_sel:[0,0]
	v_pk_mov_b32 v[244:245], v[144:145], v[160:161] op_sel:[0,0]
	v_pk_mov_b32 v[254:255], v[148:149], v[164:165] op_sel:[0,0]
	v_pk_fma_f32 v[232:233], v[32:33], v[200:201], v[232:233] op_sel_hi:[0,1,1]
	v_pk_fma_f32 v[234:235], v[34:35], v[202:203], v[234:235] op_sel_hi:[0,1,1]
	v_pk_fma_f32 v[244:245], v[36:37], v[204:205], v[244:245] op_sel_hi:[0,1,1]
	v_pk_fma_f32 v[254:255], v[38:39], v[206:207], v[254:255] op_sel_hi:[0,1,1]
	v_pk_fma_f32 v[200:201], v[32:33], v[200:201], v[232:233] op_sel:[1,1,0] op_sel_hi:[1,0,1] neg_lo:[1,0,0]
	v_pk_fma_f32 v[202:203], v[34:35], v[202:203], v[234:235] op_sel:[1,1,0] op_sel_hi:[1,0,1] neg_lo:[1,0,0]
	v_pk_fma_f32 v[204:205], v[36:37], v[204:205], v[244:245] op_sel:[1,1,0] op_sel_hi:[1,0,1] neg_lo:[1,0,0]
	v_pk_fma_f32 v[206:207], v[38:39], v[206:207], v[254:255] op_sel:[1,1,0] op_sel_hi:[1,0,1] neg_lo:[1,0,0]
	v_cvt_pk_bf16_f32 v124, v200, v201
	v_cvt_pk_bf16_f32 v125, v202, v203
	v_cvt_pk_bf16_f32 v126, v204, v205
	v_cvt_pk_bf16_f32 v127, v206, v207
	ds_write_b128 v241, v[124:127] offset:0
	v_pk_mov_b32 v[232:233], v[136:137], v[152:153] op_sel:[1,1]
	v_pk_mov_b32 v[234:235], v[140:141], v[156:157] op_sel:[1,1]
	v_pk_mov_b32 v[244:245], v[144:145], v[160:161] op_sel:[1,1]
	v_pk_mov_b32 v[254:255], v[148:149], v[164:165] op_sel:[1,1]
	v_pk_fma_f32 v[232:233], v[32:33], v[200:201], v[232:233] op_sel_hi:[0,1,1]
	v_pk_fma_f32 v[234:235], v[34:35], v[202:203], v[234:235] op_sel_hi:[0,1,1]
	v_pk_fma_f32 v[244:245], v[36:37], v[204:205], v[244:245] op_sel_hi:[0,1,1]
	v_pk_fma_f32 v[254:255], v[38:39], v[206:207], v[254:255] op_sel_hi:[0,1,1]
	v_pk_fma_f32 v[200:201], v[32:33], v[200:201], v[232:233] op_sel:[1,1,0] op_sel_hi:[1,0,1] neg_lo:[1,0,0]
	v_pk_fma_f32 v[202:203], v[34:35], v[202:203], v[234:235] op_sel:[1,1,0] op_sel_hi:[1,0,1] neg_lo:[1,0,0]
	v_pk_fma_f32 v[204:205], v[36:37], v[204:205], v[244:245] op_sel:[1,1,0] op_sel_hi:[1,0,1] neg_lo:[1,0,0]
	v_pk_fma_f32 v[206:207], v[38:39], v[206:207], v[254:255] op_sel:[1,1,0] op_sel_hi:[1,0,1] neg_lo:[1,0,0]
	v_cvt_pk_bf16_f32 v124, v200, v201
	v_cvt_pk_bf16_f32 v125, v202, v203
	v_cvt_pk_bf16_f32 v126, v204, v205
	v_cvt_pk_bf16_f32 v127, v206, v207
	ds_write_b128 v241, v[124:127] offset:256
	s_waitcnt lgkmcnt(2)
	v_mfma_f32_16x16x32_bf16 v[120:123], v[40:43], v[216:219], 0
	v_mfma_f32_16x16x32_bf16 v[120:123], v[44:47], v[220:223], v[120:123]
	v_mfma_f32_16x16x32_bf16 v[120:123], v[48:51], v[224:227], v[120:123]
	v_mfma_f32_16x16x32_bf16 v[120:123], v[52:55], v[228:231], v[120:123]
	v_pk_mov_b32 v[232:233], v[138:139], v[154:155] op_sel:[0,0]
	v_pk_mov_b32 v[234:235], v[142:143], v[158:159] op_sel:[0,0]
	v_pk_mov_b32 v[244:245], v[146:147], v[162:163] op_sel:[0,0]
	v_pk_mov_b32 v[254:255], v[150:151], v[166:167] op_sel:[0,0]
	v_pk_fma_f32 v[232:233], v[32:33], v[200:201], v[232:233] op_sel_hi:[0,1,1]
	v_pk_fma_f32 v[234:235], v[34:35], v[202:203], v[234:235] op_sel_hi:[0,1,1]
	v_pk_fma_f32 v[244:245], v[36:37], v[204:205], v[244:245] op_sel_hi:[0,1,1]
	v_pk_fma_f32 v[254:255], v[38:39], v[206:207], v[254:255] op_sel_hi:[0,1,1]
	v_pk_fma_f32 v[200:201], v[32:33], v[200:201], v[232:233] op_sel:[1,1,0] op_sel_hi:[1,0,1] neg_lo:[1,0,0]
	v_pk_fma_f32 v[202:203], v[34:35], v[202:203], v[234:235] op_sel:[1,1,0] op_sel_hi:[1,0,1] neg_lo:[1,0,0]
	v_pk_fma_f32 v[204:205], v[36:37], v[204:205], v[244:245] op_sel:[1,1,0] op_sel_hi:[1,0,1] neg_lo:[1,0,0]
	v_pk_fma_f32 v[206:207], v[38:39], v[206:207], v[254:255] op_sel:[1,1,0] op_sel_hi:[1,0,1] neg_lo:[1,0,0]
	v_cvt_pk_bf16_f32 v124, v200, v201
	v_cvt_pk_bf16_f32 v125, v202, v203
	v_cvt_pk_bf16_f32 v126, v204, v205
	v_cvt_pk_bf16_f32 v127, v206, v207
	ds_write_b128 v241, v[124:127] offset:512
	v_pk_mov_b32 v[232:233], v[138:139], v[154:155] op_sel:[1,1]
	v_pk_mov_b32 v[234:235], v[142:143], v[158:159] op_sel:[1,1]
	v_pk_mov_b32 v[244:245], v[146:147], v[162:163] op_sel:[1,1]
	v_pk_mov_b32 v[254:255], v[150:151], v[166:167] op_sel:[1,1]
	v_pk_fma_f32 v[232:233], v[32:33], v[200:201], v[232:233] op_sel_hi:[0,1,1]
	v_pk_fma_f32 v[234:235], v[34:35], v[202:203], v[234:235] op_sel_hi:[0,1,1]
	v_pk_fma_f32 v[244:245], v[36:37], v[204:205], v[244:245] op_sel_hi:[0,1,1]
	v_pk_fma_f32 v[254:255], v[38:39], v[206:207], v[254:255] op_sel_hi:[0,1,1]
	v_pk_fma_f32 v[200:201], v[32:33], v[200:201], v[232:233] op_sel:[1,1,0] op_sel_hi:[1,0,1] neg_lo:[1,0,0]
	v_pk_fma_f32 v[202:203], v[34:35], v[202:203], v[234:235] op_sel:[1,1,0] op_sel_hi:[1,0,1] neg_lo:[1,0,0]
	v_pk_fma_f32 v[204:205], v[36:37], v[204:205], v[244:245] op_sel:[1,1,0] op_sel_hi:[1,0,1] neg_lo:[1,0,0]
	v_pk_fma_f32 v[206:207], v[38:39], v[206:207], v[254:255] op_sel:[1,1,0] op_sel_hi:[1,0,1] neg_lo:[1,0,0]
	v_cvt_pk_bf16_f32 v124, v200, v201
	v_cvt_pk_bf16_f32 v125, v202, v203
	v_cvt_pk_bf16_f32 v126, v204, v205
	v_cvt_pk_bf16_f32 v127, v206, v207
	ds_write_b128 v241, v[124:127] offset:768
	global_load_dwordx4 v[72:75], v238, s[20:21]
	v_add_u32_e32 v238, v238, v243
	v_cvt_pk_bf16_f32 v124, v120, v121
	v_cvt_pk_bf16_f32 v125, v122, v123
	s_nop 0
	global_store_dwordx2 v239, v[124:125], s[24:25]
	v_add_u32_e32 v239, v239, v243
	s_waitcnt vmcnt(33)
; __device__ __forceinline__ unsigned f2bf(float f) { unsigned u = __builtin_bit_cast(unsigned, f); return (u + 0x7fffu + ((u >> 16) & 1u)) >> 16; }
; __device__ __forceinline__ bf16x8 pack8(const float (&f)[8]) { u32x4 h; h.x = pk2(f[0], f[1]); h.y = pk2(f[2], f[3]); h.z = pk2(f[4], f[5]); h.w = pk2(f[6], f[7]); return __builtin_bit_cast(bf16x8, h); }
; template <bool FINAL> __device__ __forceinline__ void phase_s5_scan(const Fr& F) {
;     ...
;         for (int sub = 0; sub < 4; ++sub) {
;             const bf16x8 A1 = __builtin_bit_cast(bf16x8, uc[sub]);
; #pragma unroll
;             for (int nt = 0; nt < 8; ++nt) {
;                 f32x4 acc = {0.f, 0.f, 0.f, 0.f};
;                 acc = __builtin_amdgcn_mfma_f32_16x16x32_bf16(A1, B1[nt], acc, 0, 0, 0);
; #pragma unroll
;                 for (int reg = 0; reg < 4; ++reg) BUl[(4 * lq + reg) * 132 + 16 * nt + l15] = acc[reg];
;             }
;             asm volatile("s_waitcnt lgkmcnt(0)" ::: "memory");
; #pragma unroll 4
;             for (int jj = 0; jj < 16; ++jj) {
;                 const float br_ = BUl[jj * 132 + lane], bi_ = BUl[jj * 132 + 64 + lane];
;                 const float nr = ar * xr - ai * xi + br_, ni = ar * xi + ai * xr + bi_; xr = nr; xi = ni;
;                 if (FINAL) { BUl[jj * 132 + lane] = xr; BUl[jj * 132 + 64 + lane] = xi; }
;             }
;             if (FINAL) {
;                 asm volatile("s_waitcnt lgkmcnt(0)" ::: "memory");
;                 f32x4 acc = {0.f, 0.f, 0.f, 0.f};
; #pragma unroll
;                 for (int ks = 0; ks < 4; ++ks) {
;                     const f32x4 t0 = *(const f32x4*)(BUl + l15 * 132 + 32 * ks + 8 * lq), t1 = *(const f32x4*)(BUl + l15 * 132 + 32 * ks + 8 * lq + 4);
;                     const float xf[8] = {t0.x, t0.y, t0.z, t0.w, t1.x, t1.y, t1.z, t1.w};
;                     acc = __builtin_amdgcn_mfma_f32_16x16x32_bf16(pack8(xf), Chi[ks], acc, 0, 0, 0);
;                 }
; #pragma unroll
;                 for (int reg = 0; reg < 4; ++reg) { const int tok = tokof(s, chunk * 64 + sub * 16 + 4 * lq + reg);
;                     Yb[((size_t)b * TB + tok) * D + g * 16 + l15] = (bf16)f2bf(acc[reg]); }
;                 asm volatile("s_waitcnt lgkmcnt(0)" ::: "memory");
	v_mfma_f32_16x16x32_bf16 v[136:139], v[80:83], v[0:3], 0
	v_mfma_f32_16x16x32_bf16 v[140:143], v[80:83], v[4:7], 0
	v_mfma_f32_16x16x32_bf16 v[144:147], v[80:83], v[8:11], 0
	v_mfma_f32_16x16x32_bf16 v[148:151], v[80:83], v[12:15], 0
	v_mfma_f32_16x16x32_bf16 v[152:155], v[80:83], v[16:19], 0
	v_mfma_f32_16x16x32_bf16 v[156:159], v[80:83], v[20:23], 0
	v_mfma_f32_16x16x32_bf16 v[160:163], v[80:83], v[24:27], 0
	v_mfma_f32_16x16x32_bf16 v[164:167], v[80:83], v[28:31], 0
	ds_read_b128 v[216:219], v242 offset:0
	ds_read_b128 v[220:223], v242 offset:64
	ds_read_b128 v[224:227], v242 offset:128
	ds_read_b128 v[228:231], v242 offset:192
	v_pk_mov_b32 v[232:233], v[168:169], v[184:185] op_sel:[0,0]
	v_pk_mov_b32 v[234:235], v[172:173], v[188:189] op_sel:[0,0]
	v_pk_mov_b32 v[244:245], v[176:177], v[192:193] op_sel:[0,0]
	v_pk_mov_b32 v[254:255], v[180:181], v[196:197] op_sel:[0,0]
	v_pk_fma_f32 v[232:233], v[32:33], v[200:201], v[232:233] op_sel_hi:[0,1,1]
	v_pk_fma_f32 v[234:235], v[34:35], v[202:203], v[234:235] op_sel_hi:[0,1,1]
	v_pk_fma_f32 v[244:245], v[36:37], v[204:205], v[244:245] op_sel_hi:[0,1,1]
	v_pk_fma_f32 v[254:255], v[38:39], v[206:207], v[254:255] op_sel_hi:[0,1,1]
	v_pk_fma_f32 v[200:201], v[32:33], v[200:201], v[232:233] op_sel:[1,1,0] op_sel_hi:[1,0,1] neg_lo:[1,0,0]
	v_pk_fma_f32 v[202:203], v[34:35], v[202:203], v[234:235] op_sel:[1,1,0] op_sel_hi:[1,0,1] neg_lo:[1,0,0]
	v_pk_fma_f32 v[204:205], v[36:37], v[204:205], v[244:245] op_sel:[1,1,0] op_sel_hi:[1,0,1] neg_lo:[1,0,0]
	v_pk_fma_f32 v[206:207], v[38:39], v[206:207], v[254:255] op_sel:[1,1,0] op_sel_hi:[1,0,1] neg_lo:[1,0,0]
	v_cvt_pk_bf16_f32 v124, v200, v201
	v_cvt_pk_bf16_f32 v125, v202, v203
	v_cvt_pk_bf16_f32 v126, v204, v205
	v_cvt_pk_bf16_f32 v127, v206, v207
	ds_write_b128 v241, v[124:127] offset:4096
	v_pk_mov_b32 v[232:233], v[168:169], v[184:185] op_sel:[1,1]
	v_pk_mov_b32 v[234:235], v[172:173], v[188:189] op_sel:[1,1]
	v_pk_mov_b32 v[244:245], v[176:177], v[192:193] op_sel:[1,1]
	v_pk_mov_b32 v[254:255], v[180:181], v[196:197] op_sel:[1,1]
	v_pk_fma_f32 v[232:233], v[32:33], v[200:201], v[232:233] op_sel_hi:[0,1,1]
	v_pk_fma_f32 v[234:235], v[34:35], v[202:203], v[234:235] op_sel_hi:[0,1,1]
	v_pk_fma_f32 v[244:245], v[36:37], v[204:205], v[244:245] op_sel_hi:[0,1,1]
	v_pk_fma_f32 v[254:255], v[38:39], v[206:207], v[254:255] op_sel_hi:[0,1,1]
	v_pk_fma_f32 v[200:201], v[32:33], v[200:201], v[232:233] op_sel:[1,1,0] op_sel_hi:[1,0,1] neg_lo:[1,0,0]
	v_pk_fma_f32 v[202:203], v[34:35], v[202:203], v[234:235] op_sel:[1,1,0] op_sel_hi:[1,0,1] neg_lo:[1,0,0]
	v_pk_fma_f32 v[204:205], v[36:37], v[204:205], v[244:245] op_sel:[1,1,0] op_sel_hi:[1,0,1] neg_lo:[1,0,0]
	v_pk_fma_f32 v[206:207], v[38:39], v[206:207], v[254:255] op_sel:[1,1,0] op_sel_hi:[1,0,1] neg_lo:[1,0,0]
	v_cvt_pk_bf16_f32 v124, v200, v201
	v_cvt_pk_bf16_f32 v125, v202, v203
	v_cvt_pk_bf16_f32 v126, v204, v205
	v_cvt_pk_bf16_f32 v127, v206, v207
	ds_write_b128 v241, v[124:127] offset:4352
	s_waitcnt lgkmcnt(2)
	v_mfma_f32_16x16x32_bf16 v[120:123], v[40:43], v[216:219], 0
	v_mfma_f32_16x16x32_bf16 v[120:123], v[44:47], v[220:223], v[120:123]
	v_mfma_f32_16x16x32_bf16 v[120:123], v[48:51], v[224:227], v[120:123]
	v_mfma_f32_16x16x32_bf16 v[120:123], v[52:55], v[228:231], v[120:123]
	v_pk_mov_b32 v[232:233], v[170:171], v[186:187] op_sel:[0,0]
	v_pk_mov_b32 v[234:235], v[174:175], v[190:191] op_sel:[0,0]
	v_pk_mov_b32 v[244:245], v[178:179], v[194:195] op_sel:[0,0]
	v_pk_mov_b32 v[254:255], v[182:183], v[198:199] op_sel:[0,0]
	v_pk_fma_f32 v[232:233], v[32:33], v[200:201], v[232:233] op_sel_hi:[0,1,1]
	v_pk_fma_f32 v[234:235], v[34:35], v[202:203], v[234:235] op_sel_hi:[0,1,1]
	v_pk_fma_f32 v[244:245], v[36:37], v[204:205], v[244:245] op_sel_hi:[0,1,1]
	v_pk_fma_f32 v[254:255], v[38:39], v[206:207], v[254:255] op_sel_hi:[0,1,1]
	v_pk_fma_f32 v[200:201], v[32:33], v[200:201], v[232:233] op_sel:[1,1,0] op_sel_hi:[1,0,1] neg_lo:[1,0,0]
	v_pk_fma_f32 v[202:203], v[34:35], v[202:203], v[234:235] op_sel:[1,1,0] op_sel_hi:[1,0,1] neg_lo:[1,0,0]
	v_pk_fma_f32 v[204:205], v[36:37], v[204:205], v[244:245] op_sel:[1,1,0] op_sel_hi:[1,0,1] neg_lo:[1,0,0]
	v_pk_fma_f32 v[206:207], v[38:39], v[206:207], v[254:255] op_sel:[1,1,0] op_sel_hi:[1,0,1] neg_lo:[1,0,0]
	v_cvt_pk_bf16_f32 v124, v200, v201
	v_cvt_pk_bf16_f32 v125, v202, v203
	v_cvt_pk_bf16_f32 v126, v204, v205
	v_cvt_pk_bf16_f32 v127, v206, v207
	ds_write_b128 v241, v[124:127] offset:4608
	v_pk_mov_b32 v[232:233], v[170:171], v[186:187] op_sel:[1,1]
	v_pk_mov_b32 v[234:235], v[174:175], v[190:191] op_sel:[1,1]
	v_pk_mov_b32 v[244:245], v[178:179], v[194:195] op_sel:[1,1]
	v_pk_mov_b32 v[254:255], v[182:183], v[198:199] op_sel:[1,1]
	v_pk_fma_f32 v[232:233], v[32:33], v[200:201], v[232:233] op_sel_hi:[0,1,1]
	v_pk_fma_f32 v[234:235], v[34:35], v[202:203], v[234:235] op_sel_hi:[0,1,1]
	v_pk_fma_f32 v[244:245], v[36:37], v[204:205], v[244:245] op_sel_hi:[0,1,1]
	v_pk_fma_f32 v[254:255], v[38:39], v[206:207], v[254:255] op_sel_hi:[0,1,1]
	v_pk_fma_f32 v[200:201], v[32:33], v[200:201], v[232:233] op_sel:[1,1,0] op_sel_hi:[1,0,1] neg_lo:[1,0,0]
	v_pk_fma_f32 v[202:203], v[34:35], v[202:203], v[234:235] op_sel:[1,1,0] op_sel_hi:[1,0,1] neg_lo:[1,0,0]
	v_pk_fma_f32 v[204:205], v[36:37], v[204:205], v[244:245] op_sel:[1,1,0] op_sel_hi:[1,0,1] neg_lo:[1,0,0]
	v_pk_fma_f32 v[206:207], v[38:39], v[206:207], v[254:255] op_sel:[1,1,0] op_sel_hi:[1,0,1] neg_lo:[1,0,0]
	v_cvt_pk_bf16_f32 v124, v200, v201
	v_cvt_pk_bf16_f32 v125, v202, v203
	v_cvt_pk_bf16_f32 v126, v204, v205
	v_cvt_pk_bf16_f32 v127, v206, v207
	ds_write_b128 v241, v[124:127] offset:4864
	global_load_dwordx4 v[76:79], v238, s[20:21]
	v_add_u32_e32 v238, v238, v243
	v_cvt_pk_bf16_f32 v124, v120, v121
	v_cvt_pk_bf16_f32 v125, v122, v123
	s_nop 0
	global_store_dwordx2 v239, v[124:125], s[24:25]
	v_add_u32_e32 v239, v239, v243
	s_waitcnt vmcnt(33)
; __device__ __forceinline__ unsigned f2bf(float f) { unsigned u = __builtin_bit_cast(unsigned, f); return (u + 0x7fffu + ((u >> 16) & 1u)) >> 16; }
; __device__ __forceinline__ bf16x8 pack8(const float (&f)[8]) { u32x4 h; h.x = pk2(f[0], f[1]); h.y = pk2(f[2], f[3]); h.z = pk2(f[4], f[5]); h.w = pk2(f[6], f[7]); return __builtin_bit_cast(bf16x8, h); }
; template <bool FINAL> __device__ __forceinline__ void phase_s5_scan(const Fr& F) {
;     ...
;         for (int sub = 0; sub < 4; ++sub) {
;             const bf16x8 A1 = __builtin_bit_cast(bf16x8, uc[sub]);
; #pragma unroll
;             for (int nt = 0; nt < 8; ++nt) {
;                 f32x4 acc = {0.f, 0.f, 0.f, 0.f};
;                 acc = __builtin_amdgcn_mfma_f32_16x16x32_bf16(A1, B1[nt], acc, 0, 0, 0);
; #pragma unroll
;                 for (int reg = 0; reg < 4; ++reg) BUl[(4 * lq + reg) * 132 + 16 * nt + l15] = acc[reg];
;             }
;             asm volatile("s_waitcnt lgkmcnt(0)" ::: "memory");
; #pragma unroll 4
;             for (int jj = 0; jj < 16; ++jj) {
;                 const float br_ = BUl[jj * 132 + lane], bi_ = BUl[jj * 132 + 64 + lane];
;                 const float nr = ar * xr - ai * xi + br_, ni = ar * xi + ai * xr + bi_; xr = nr; xi = ni;
;                 if (FINAL) { BUl[jj * 132 + lane] = xr; BUl[jj * 132 + 64 + lane] = xi; }
;             }
;             if (FINAL) {
;                 asm volatile("s_waitcnt lgkmcnt(0)" ::: "memory");
;                 f32x4 acc = {0.f, 0.f, 0.f, 0.f};
; #pragma unroll
;                 for (int ks = 0; ks < 4; ++ks) {
;                     const f32x4 t0 = *(const f32x4*)(BUl + l15 * 132 + 32 * ks + 8 * lq), t1 = *(const f32x4*)(BUl + l15 * 132 + 32 * ks + 8 * lq + 4);
;                     const float xf[8] = {t0.x, t0.y, t0.z, t0.w, t1.x, t1.y, t1.z, t1.w};
;                     acc = __builtin_amdgcn_mfma_f32_16x16x32_bf16(pack8(xf), Chi[ks], acc, 0, 0, 0);
;                 }
; #pragma unroll
;                 for (int reg = 0; reg < 4; ++reg) { const int tok = tokof(s, chunk * 64 + sub * 16 + 4 * lq + reg);
;                     Yb[((size_t)b * TB + tok) * D + g * 16 + l15] = (bf16)f2bf(acc[reg]); }
;                 asm volatile("s_waitcnt lgkmcnt(0)" ::: "memory");
	v_mfma_f32_16x16x32_bf16 v[168:171], v[84:87], v[0:3], 0
	v_mfma_f32_16x16x32_bf16 v[172:175], v[84:87], v[4:7], 0
	v_mfma_f32_16x16x32_bf16 v[176:179], v[84:87], v[8:11], 0
	v_mfma_f32_16x16x32_bf16 v[180:183], v[84:87], v[12:15], 0
	v_mfma_f32_16x16x32_bf16 v[184:187], v[84:87], v[16:19], 0
	v_mfma_f32_16x16x32_bf16 v[188:191], v[84:87], v[20:23], 0
	v_mfma_f32_16x16x32_bf16 v[192:195], v[84:87], v[24:27], 0
	v_mfma_f32_16x16x32_bf16 v[196:199], v[84:87], v[28:31], 0
	ds_read_b128 v[216:219], v242 offset:4096
	ds_read_b128 v[220:223], v242 offset:4160
	ds_read_b128 v[224:227], v242 offset:4224
	ds_read_b128 v[228:231], v242 offset:4288
	v_pk_mov_b32 v[232:233], v[136:137], v[152:153] op_sel:[0,0]
	v_pk_mov_b32 v[234:235], v[140:141], v[156:157] op_sel:[0,0]
	v_pk_mov_b32 v[244:245], v[144:145], v[160:161] op_sel:[0,0]
	v_pk_mov_b32 v[254:255], v[148:149], v[164:165] op_sel:[0,0]
	v_pk_fma_f32 v[232:233], v[32:33], v[200:201], v[232:233] op_sel_hi:[0,1,1]
	v_pk_fma_f32 v[234:235], v[34:35], v[202:203], v[234:235] op_sel_hi:[0,1,1]
	v_pk_fma_f32 v[244:245], v[36:37], v[204:205], v[244:245] op_sel_hi:[0,1,1]
	v_pk_fma_f32 v[254:255], v[38:39], v[206:207], v[254:255] op_sel_hi:[0,1,1]
	v_pk_fma_f32 v[200:201], v[32:33], v[200:201], v[232:233] op_sel:[1,1,0] op_sel_hi:[1,0,1] neg_lo:[1,0,0]
	v_pk_fma_f32 v[202:203], v[34:35], v[202:203], v[234:235] op_sel:[1,1,0] op_sel_hi:[1,0,1] neg_lo:[1,0,0]
	v_pk_fma_f32 v[204:205], v[36:37], v[204:205], v[244:245] op_sel:[1,1,0] op_sel_hi:[1,0,1] neg_lo:[1,0,0]
	v_pk_fma_f32 v[206:207], v[38:39], v[206:207], v[254:255] op_sel:[1,1,0] op_sel_hi:[1,0,1] neg_lo:[1,0,0]
	v_cvt_pk_bf16_f32 v124, v200, v201
	v_cvt_pk_bf16_f32 v125, v202, v203
	v_cvt_pk_bf16_f32 v126, v204, v205
	v_cvt_pk_bf16_f32 v127, v206, v207
	ds_write_b128 v241, v[124:127] offset:0
	v_pk_mov_b32 v[232:233], v[136:137], v[152:153] op_sel:[1,1]
	v_pk_mov_b32 v[234:235], v[140:141], v[156:157] op_sel:[1,1]
	v_pk_mov_b32 v[244:245], v[144:145], v[160:161] op_sel:[1,1]
	v_pk_mov_b32 v[254:255], v[148:149], v[164:165] op_sel:[1,1]
	v_pk_fma_f32 v[232:233], v[32:33], v[200:201], v[232:233] op_sel_hi:[0,1,1]
	v_pk_fma_f32 v[234:235], v[34:35], v[202:203], v[234:235] op_sel_hi:[0,1,1]
	v_pk_fma_f32 v[244:245], v[36:37], v[204:205], v[244:245] op_sel_hi:[0,1,1]
	v_pk_fma_f32 v[254:255], v[38:39], v[206:207], v[254:255] op_sel_hi:[0,1,1]
	v_pk_fma_f32 v[200:201], v[32:33], v[200:201], v[232:233] op_sel:[1,1,0] op_sel_hi:[1,0,1] neg_lo:[1,0,0]
	v_pk_fma_f32 v[202:203], v[34:35], v[202:203], v[234:235] op_sel:[1,1,0] op_sel_hi:[1,0,1] neg_lo:[1,0,0]
	v_pk_fma_f32 v[204:205], v[36:37], v[204:205], v[244:245] op_sel:[1,1,0] op_sel_hi:[1,0,1] neg_lo:[1,0,0]
	v_pk_fma_f32 v[206:207], v[38:39], v[206:207], v[254:255] op_sel:[1,1,0] op_sel_hi:[1,0,1] neg_lo:[1,0,0]
	v_cvt_pk_bf16_f32 v124, v200, v201
	v_cvt_pk_bf16_f32 v125, v202, v203
	v_cvt_pk_bf16_f32 v126, v204, v205
	v_cvt_pk_bf16_f32 v127, v206, v207
	ds_write_b128 v241, v[124:127] offset:256
	s_waitcnt lgkmcnt(2)
	v_mfma_f32_16x16x32_bf16 v[120:123], v[40:43], v[216:219], 0
	v_mfma_f32_16x16x32_bf16 v[120:123], v[44:47], v[220:223], v[120:123]
	v_mfma_f32_16x16x32_bf16 v[120:123], v[48:51], v[224:227], v[120:123]
	v_mfma_f32_16x16x32_bf16 v[120:123], v[52:55], v[228:231], v[120:123]
	v_pk_mov_b32 v[232:233], v[138:139], v[154:155] op_sel:[0,0]
	v_pk_mov_b32 v[234:235], v[142:143], v[158:159] op_sel:[0,0]
	v_pk_mov_b32 v[244:245], v[146:147], v[162:163] op_sel:[0,0]
	v_pk_mov_b32 v[254:255], v[150:151], v[166:167] op_sel:[0,0]
	v_pk_fma_f32 v[232:233], v[32:33], v[200:201], v[232:233] op_sel_hi:[0,1,1]
	v_pk_fma_f32 v[234:235], v[34:35], v[202:203], v[234:235] op_sel_hi:[0,1,1]
	v_pk_fma_f32 v[244:245], v[36:37], v[204:205], v[244:245] op_sel_hi:[0,1,1]
	v_pk_fma_f32 v[254:255], v[38:39], v[206:207], v[254:255] op_sel_hi:[0,1,1]
	v_pk_fma_f32 v[200:201], v[32:33], v[200:201], v[232:233] op_sel:[1,1,0] op_sel_hi:[1,0,1] neg_lo:[1,0,0]
	v_pk_fma_f32 v[202:203], v[34:35], v[202:203], v[234:235] op_sel:[1,1,0] op_sel_hi:[1,0,1] neg_lo:[1,0,0]
	v_pk_fma_f32 v[204:205], v[36:37], v[204:205], v[244:245] op_sel:[1,1,0] op_sel_hi:[1,0,1] neg_lo:[1,0,0]
	v_pk_fma_f32 v[206:207], v[38:39], v[206:207], v[254:255] op_sel:[1,1,0] op_sel_hi:[1,0,1] neg_lo:[1,0,0]
	v_cvt_pk_bf16_f32 v124, v200, v201
	v_cvt_pk_bf16_f32 v125, v202, v203
	v_cvt_pk_bf16_f32 v126, v204, v205
	v_cvt_pk_bf16_f32 v127, v206, v207
	ds_write_b128 v241, v[124:127] offset:512
	v_pk_mov_b32 v[232:233], v[138:139], v[154:155] op_sel:[1,1]
	v_pk_mov_b32 v[234:235], v[142:143], v[158:159] op_sel:[1,1]
	v_pk_mov_b32 v[244:245], v[146:147], v[162:163] op_sel:[1,1]
	v_pk_mov_b32 v[254:255], v[150:151], v[166:167] op_sel:[1,1]
	v_pk_fma_f32 v[232:233], v[32:33], v[200:201], v[232:233] op_sel_hi:[0,1,1]
	v_pk_fma_f32 v[234:235], v[34:35], v[202:203], v[234:235] op_sel_hi:[0,1,1]
	v_pk_fma_f32 v[244:245], v[36:37], v[204:205], v[244:245] op_sel_hi:[0,1,1]
	v_pk_fma_f32 v[254:255], v[38:39], v[206:207], v[254:255] op_sel_hi:[0,1,1]
	v_pk_fma_f32 v[200:201], v[32:33], v[200:201], v[232:233] op_sel:[1,1,0] op_sel_hi:[1,0,1] neg_lo:[1,0,0]
	v_pk_fma_f32 v[202:203], v[34:35], v[202:203], v[234:235] op_sel:[1,1,0] op_sel_hi:[1,0,1] neg_lo:[1,0,0]
	v_pk_fma_f32 v[204:205], v[36:37], v[204:205], v[244:245] op_sel:[1,1,0] op_sel_hi:[1,0,1] neg_lo:[1,0,0]
	v_pk_fma_f32 v[206:207], v[38:39], v[206:207], v[254:255] op_sel:[1,1,0] op_sel_hi:[1,0,1] neg_lo:[1,0,0]
	v_cvt_pk_bf16_f32 v124, v200, v201
	v_cvt_pk_bf16_f32 v125, v202, v203
	v_cvt_pk_bf16_f32 v126, v204, v205
	v_cvt_pk_bf16_f32 v127, v206, v207
	ds_write_b128 v241, v[124:127] offset:768
	global_load_dwordx4 v[80:83], v238, s[20:21]
	v_add_u32_e32 v238, v238, v243
	v_cvt_pk_bf16_f32 v124, v120, v121
	v_cvt_pk_bf16_f32 v125, v122, v123
	s_nop 0
	global_store_dwordx2 v239, v[124:125], s[24:25]
	v_add_u32_e32 v239, v239, v243
	s_waitcnt vmcnt(33)
; __device__ __forceinline__ unsigned f2bf(float f) { unsigned u = __builtin_bit_cast(unsigned, f); return (u + 0x7fffu + ((u >> 16) & 1u)) >> 16; }
; __device__ __forceinline__ bf16x8 pack8(const float (&f)[8]) { u32x4 h; h.x = pk2(f[0], f[1]); h.y = pk2(f[2], f[3]); h.z = pk2(f[4], f[5]); h.w = pk2(f[6], f[7]); return __builtin_bit_cast(bf16x8, h); }
; template <bool FINAL> __device__ __forceinline__ void phase_s5_scan(const Fr& F) {
;     ...
;         for (int sub = 0; sub < 4; ++sub) {
;             const bf16x8 A1 = __builtin_bit_cast(bf16x8, uc[sub]);
; #pragma unroll
;             for (int nt = 0; nt < 8; ++nt) {
;                 f32x4 acc = {0.f, 0.f, 0.f, 0.f};
;                 acc = __builtin_amdgcn_mfma_f32_16x16x32_bf16(A1, B1[nt], acc, 0, 0, 0);
; #pragma unroll
;                 for (int reg = 0; reg < 4; ++reg) BUl[(4 * lq + reg) * 132 + 16 * nt + l15] = acc[reg];
;             }
;             asm volatile("s_waitcnt lgkmcnt(0)" ::: "memory");
; #pragma unroll 4
;             for (int jj = 0; jj < 16; ++jj) {
;                 const float br_ = BUl[jj * 132 + lane], bi_ = BUl[jj * 132 + 64 + lane];
;                 const float nr = ar * xr - ai * xi + br_, ni = ar * xi + ai * xr + bi_; xr = nr; xi = ni;
;                 if (FINAL) { BUl[jj * 132 + lane] = xr; BUl[jj * 132 + 64 + lane] = xi; }
;             }
;             if (FINAL) {
;                 asm volatile("s_waitcnt lgkmcnt(0)" ::: "memory");
;                 f32x4 acc = {0.f, 0.f, 0.f, 0.f};
; #pragma unroll
;                 for (int ks = 0; ks < 4; ++ks) {
;                     const f32x4 t0 = *(const f32x4*)(BUl + l15 * 132 + 32 * ks + 8 * lq), t1 = *(const f32x4*)(BUl + l15 * 132 + 32 * ks + 8 * lq + 4);
;                     const float xf[8] = {t0.x, t0.y, t0.z, t0.w, t1.x, t1.y, t1.z, t1.w};
;                     acc = __builtin_amdgcn_mfma_f32_16x16x32_bf16(pack8(xf), Chi[ks], acc, 0, 0, 0);
;                 }
; #pragma unroll
;                 for (int reg = 0; reg < 4; ++reg) { const int tok = tokof(s, chunk * 64 + sub * 16 + 4 * lq + reg);
;                     Yb[((size_t)b * TB + tok) * D + g * 16 + l15] = (bf16)f2bf(acc[reg]); }
;                 asm volatile("s_waitcnt lgkmcnt(0)" ::: "memory");
	v_mfma_f32_16x16x32_bf16 v[136:139], v[88:91], v[0:3], 0
	v_mfma_f32_16x16x32_bf16 v[140:143], v[88:91], v[4:7], 0
	v_mfma_f32_16x16x32_bf16 v[144:147], v[88:91], v[8:11], 0
	v_mfma_f32_16x16x32_bf16 v[148:151], v[88:91], v[12:15], 0
	v_mfma_f32_16x16x32_bf16 v[152:155], v[88:91], v[16:19], 0
	v_mfma_f32_16x16x32_bf16 v[156:159], v[88:91], v[20:23], 0
	v_mfma_f32_16x16x32_bf16 v[160:163], v[88:91], v[24:27], 0
	v_mfma_f32_16x16x32_bf16 v[164:167], v[88:91], v[28:31], 0
	ds_read_b128 v[216:219], v242 offset:0
	ds_read_b128 v[220:223], v242 offset:64
	ds_read_b128 v[224:227], v242 offset:128
	ds_read_b128 v[228:231], v242 offset:192
	v_pk_mov_b32 v[232:233], v[168:169], v[184:185] op_sel:[0,0]
	v_pk_mov_b32 v[234:235], v[172:173], v[188:189] op_sel:[0,0]
	v_pk_mov_b32 v[244:245], v[176:177], v[192:193] op_sel:[0,0]
	v_pk_mov_b32 v[254:255], v[180:181], v[196:197] op_sel:[0,0]
	v_pk_fma_f32 v[232:233], v[32:33], v[200:201], v[232:233] op_sel_hi:[0,1,1]
	v_pk_fma_f32 v[234:235], v[34:35], v[202:203], v[234:235] op_sel_hi:[0,1,1]
	v_pk_fma_f32 v[244:245], v[36:37], v[204:205], v[244:245] op_sel_hi:[0,1,1]
	v_pk_fma_f32 v[254:255], v[38:39], v[206:207], v[254:255] op_sel_hi:[0,1,1]
	v_pk_fma_f32 v[200:201], v[32:33], v[200:201], v[232:233] op_sel:[1,1,0] op_sel_hi:[1,0,1] neg_lo:[1,0,0]
	v_pk_fma_f32 v[202:203], v[34:35], v[202:203], v[234:235] op_sel:[1,1,0] op_sel_hi:[1,0,1] neg_lo:[1,0,0]
	v_pk_fma_f32 v[204:205], v[36:37], v[204:205], v[244:245] op_sel:[1,1,0] op_sel_hi:[1,0,1] neg_lo:[1,0,0]
	v_pk_fma_f32 v[206:207], v[38:39], v[206:207], v[254:255] op_sel:[1,1,0] op_sel_hi:[1,0,1] neg_lo:[1,0,0]
	v_cvt_pk_bf16_f32 v124, v200, v201
	v_cvt_pk_bf16_f32 v125, v202, v203
	v_cvt_pk_bf16_f32 v126, v204, v205
	v_cvt_pk_bf16_f32 v127, v206, v207
	ds_write_b128 v241, v[124:127] offset:4096
	v_pk_mov_b32 v[232:233], v[168:169], v[184:185] op_sel:[1,1]
	v_pk_mov_b32 v[234:235], v[172:173], v[188:189] op_sel:[1,1]
	v_pk_mov_b32 v[244:245], v[176:177], v[192:193] op_sel:[1,1]
	v_pk_mov_b32 v[254:255], v[180:181], v[196:197] op_sel:[1,1]
	v_pk_fma_f32 v[232:233], v[32:33], v[200:201], v[232:233] op_sel_hi:[0,1,1]
	v_pk_fma_f32 v[234:235], v[34:35], v[202:203], v[234:235] op_sel_hi:[0,1,1]
	v_pk_fma_f32 v[244:245], v[36:37], v[204:205], v[244:245] op_sel_hi:[0,1,1]
	v_pk_fma_f32 v[254:255], v[38:39], v[206:207], v[254:255] op_sel_hi:[0,1,1]
	v_pk_fma_f32 v[200:201], v[32:33], v[200:201], v[232:233] op_sel:[1,1,0] op_sel_hi:[1,0,1] neg_lo:[1,0,0]
	v_pk_fma_f32 v[202:203], v[34:35], v[202:203], v[234:235] op_sel:[1,1,0] op_sel_hi:[1,0,1] neg_lo:[1,0,0]
	v_pk_fma_f32 v[204:205], v[36:37], v[204:205], v[244:245] op_sel:[1,1,0] op_sel_hi:[1,0,1] neg_lo:[1,0,0]
	v_pk_fma_f32 v[206:207], v[38:39], v[206:207], v[254:255] op_sel:[1,1,0] op_sel_hi:[1,0,1] neg_lo:[1,0,0]
	v_cvt_pk_bf16_f32 v124, v200, v201
	v_cvt_pk_bf16_f32 v125, v202, v203
	v_cvt_pk_bf16_f32 v126, v204, v205
	v_cvt_pk_bf16_f32 v127, v206, v207
	ds_write_b128 v241, v[124:127] offset:4352
	s_waitcnt lgkmcnt(2)
	v_mfma_f32_16x16x32_bf16 v[120:123], v[40:43], v[216:219], 0
	v_mfma_f32_16x16x32_bf16 v[120:123], v[44:47], v[220:223], v[120:123]
	v_mfma_f32_16x16x32_bf16 v[120:123], v[48:51], v[224:227], v[120:123]
	v_mfma_f32_16x16x32_bf16 v[120:123], v[52:55], v[228:231], v[120:123]
	v_pk_mov_b32 v[232:233], v[170:171], v[186:187] op_sel:[0,0]
	v_pk_mov_b32 v[234:235], v[174:175], v[190:191] op_sel:[0,0]
	v_pk_mov_b32 v[244:245], v[178:179], v[194:195] op_sel:[0,0]
	v_pk_mov_b32 v[254:255], v[182:183], v[198:199] op_sel:[0,0]
	v_pk_fma_f32 v[232:233], v[32:33], v[200:201], v[232:233] op_sel_hi:[0,1,1]
	v_pk_fma_f32 v[234:235], v[34:35], v[202:203], v[234:235] op_sel_hi:[0,1,1]
	v_pk_fma_f32 v[244:245], v[36:37], v[204:205], v[244:245] op_sel_hi:[0,1,1]
	v_pk_fma_f32 v[254:255], v[38:39], v[206:207], v[254:255] op_sel_hi:[0,1,1]
	v_pk_fma_f32 v[200:201], v[32:33], v[200:201], v[232:233] op_sel:[1,1,0] op_sel_hi:[1,0,1] neg_lo:[1,0,0]
	v_pk_fma_f32 v[202:203], v[34:35], v[202:203], v[234:235] op_sel:[1,1,0] op_sel_hi:[1,0,1] neg_lo:[1,0,0]
	v_pk_fma_f32 v[204:205], v[36:37], v[204:205], v[244:245] op_sel:[1,1,0] op_sel_hi:[1,0,1] neg_lo:[1,0,0]
	v_pk_fma_f32 v[206:207], v[38:39], v[206:207], v[254:255] op_sel:[1,1,0] op_sel_hi:[1,0,1] neg_lo:[1,0,0]
	v_cvt_pk_bf16_f32 v124, v200, v201
	v_cvt_pk_bf16_f32 v125, v202, v203
	v_cvt_pk_bf16_f32 v126, v204, v205
	v_cvt_pk_bf16_f32 v127, v206, v207
	ds_write_b128 v241, v[124:127] offset:4608
	v_pk_mov_b32 v[232:233], v[170:171], v[186:187] op_sel:[1,1]
	v_pk_mov_b32 v[234:235], v[174:175], v[190:191] op_sel:[1,1]
	v_pk_mov_b32 v[244:245], v[178:179], v[194:195] op_sel:[1,1]
	v_pk_mov_b32 v[254:255], v[182:183], v[198:199] op_sel:[1,1]
	v_pk_fma_f32 v[232:233], v[32:33], v[200:201], v[232:233] op_sel_hi:[0,1,1]
	v_pk_fma_f32 v[234:235], v[34:35], v[202:203], v[234:235] op_sel_hi:[0,1,1]
	v_pk_fma_f32 v[244:245], v[36:37], v[204:205], v[244:245] op_sel_hi:[0,1,1]
	v_pk_fma_f32 v[254:255], v[38:39], v[206:207], v[254:255] op_sel_hi:[0,1,1]
	v_pk_fma_f32 v[200:201], v[32:33], v[200:201], v[232:233] op_sel:[1,1,0] op_sel_hi:[1,0,1] neg_lo:[1,0,0]
	v_pk_fma_f32 v[202:203], v[34:35], v[202:203], v[234:235] op_sel:[1,1,0] op_sel_hi:[1,0,1] neg_lo:[1,0,0]
	v_pk_fma_f32 v[204:205], v[36:37], v[204:205], v[244:245] op_sel:[1,1,0] op_sel_hi:[1,0,1] neg_lo:[1,0,0]
	v_pk_fma_f32 v[206:207], v[38:39], v[206:207], v[254:255] op_sel:[1,1,0] op_sel_hi:[1,0,1] neg_lo:[1,0,0]
	v_cvt_pk_bf16_f32 v124, v200, v201
	v_cvt_pk_bf16_f32 v125, v202, v203
	v_cvt_pk_bf16_f32 v126, v204, v205
	v_cvt_pk_bf16_f32 v127, v206, v207
	ds_write_b128 v241, v[124:127] offset:4864
	global_load_dwordx4 v[84:87], v238, s[20:21]
	v_add_u32_e32 v238, v238, v243
	v_cvt_pk_bf16_f32 v124, v120, v121
	v_cvt_pk_bf16_f32 v125, v122, v123
	s_nop 0
	global_store_dwordx2 v239, v[124:125], s[24:25]
	v_add_u32_e32 v239, v239, v243
	s_waitcnt vmcnt(33)
; __device__ __forceinline__ unsigned f2bf(float f) { unsigned u = __builtin_bit_cast(unsigned, f); return (u + 0x7fffu + ((u >> 16) & 1u)) >> 16; }
; __device__ __forceinline__ bf16x8 pack8(const float (&f)[8]) { u32x4 h; h.x = pk2(f[0], f[1]); h.y = pk2(f[2], f[3]); h.z = pk2(f[4], f[5]); h.w = pk2(f[6], f[7]); return __builtin_bit_cast(bf16x8, h); }
; template <bool FINAL> __device__ __forceinline__ void phase_s5_scan(const Fr& F) {
;     ...
;         for (int sub = 0; sub < 4; ++sub) {
;             const bf16x8 A1 = __builtin_bit_cast(bf16x8, uc[sub]);
; #pragma unroll
;             for (int nt = 0; nt < 8; ++nt) {
;                 f32x4 acc = {0.f, 0.f, 0.f, 0.f};
;                 acc = __builtin_amdgcn_mfma_f32_16x16x32_bf16(A1, B1[nt], acc, 0, 0, 0);
; #pragma unroll
;                 for (int reg = 0; reg < 4; ++reg) BUl[(4 * lq + reg) * 132 + 16 * nt + l15] = acc[reg];
;             }
;             asm volatile("s_waitcnt lgkmcnt(0)" ::: "memory");
; #pragma unroll 4
;             for (int jj = 0; jj < 16; ++jj) {
;                 const float br_ = BUl[jj * 132 + lane], bi_ = BUl[jj * 132 + 64 + lane];
;                 const float nr = ar * xr - ai * xi + br_, ni = ar * xi + ai * xr + bi_; xr = nr; xi = ni;
;                 if (FINAL) { BUl[jj * 132 + lane] = xr; BUl[jj * 132 + 64 + lane] = xi; }
;             }
;             if (FINAL) {
;                 asm volatile("s_waitcnt lgkmcnt(0)" ::: "memory");
;                 f32x4 acc = {0.f, 0.f, 0.f, 0.f};
; #pragma unroll
;                 for (int ks = 0; ks < 4; ++ks) {
;                     const f32x4 t0 = *(const f32x4*)(BUl + l15 * 132 + 32 * ks + 8 * lq), t1 = *(const f32x4*)(BUl + l15 * 132 + 32 * ks + 8 * lq + 4);
;                     const float xf[8] = {t0.x, t0.y, t0.z, t0.w, t1.x, t1.y, t1.z, t1.w};
;                     acc = __builtin_amdgcn_mfma_f32_16x16x32_bf16(pack8(xf), Chi[ks], acc, 0, 0, 0);
;                 }
; #pragma unroll
;                 for (int reg = 0; reg < 4; ++reg) { const int tok = tokof(s, chunk * 64 + sub * 16 + 4 * lq + reg);
;                     Yb[((size_t)b * TB + tok) * D + g * 16 + l15] = (bf16)f2bf(acc[reg]); }
;                 asm volatile("s_waitcnt lgkmcnt(0)" ::: "memory");
	v_mfma_f32_16x16x32_bf16 v[168:171], v[92:95], v[0:3], 0
	v_mfma_f32_16x16x32_bf16 v[172:175], v[92:95], v[4:7], 0
	v_mfma_f32_16x16x32_bf16 v[176:179], v[92:95], v[8:11], 0
	v_mfma_f32_16x16x32_bf16 v[180:183], v[92:95], v[12:15], 0
	v_mfma_f32_16x16x32_bf16 v[184:187], v[92:95], v[16:19], 0
	v_mfma_f32_16x16x32_bf16 v[188:191], v[92:95], v[20:23], 0
	v_mfma_f32_16x16x32_bf16 v[192:195], v[92:95], v[24:27], 0
	v_mfma_f32_16x16x32_bf16 v[196:199], v[92:95], v[28:31], 0
	ds_read_b128 v[216:219], v242 offset:4096
	ds_read_b128 v[220:223], v242 offset:4160
	ds_read_b128 v[224:227], v242 offset:4224
	ds_read_b128 v[228:231], v242 offset:4288
	v_pk_mov_b32 v[232:233], v[136:137], v[152:153] op_sel:[0,0]
	v_pk_mov_b32 v[234:235], v[140:141], v[156:157] op_sel:[0,0]
	v_pk_mov_b32 v[244:245], v[144:145], v[160:161] op_sel:[0,0]
	v_pk_mov_b32 v[254:255], v[148:149], v[164:165] op_sel:[0,0]
	v_pk_fma_f32 v[232:233], v[32:33], v[200:201], v[232:233] op_sel_hi:[0,1,1]
	v_pk_fma_f32 v[234:235], v[34:35], v[202:203], v[234:235] op_sel_hi:[0,1,1]
	v_pk_fma_f32 v[244:245], v[36:37], v[204:205], v[244:245] op_sel_hi:[0,1,1]
	v_pk_fma_f32 v[254:255], v[38:39], v[206:207], v[254:255] op_sel_hi:[0,1,1]
	v_pk_fma_f32 v[200:201], v[32:33], v[200:201], v[232:233] op_sel:[1,1,0] op_sel_hi:[1,0,1] neg_lo:[1,0,0]
	v_pk_fma_f32 v[202:203], v[34:35], v[202:203], v[234:235] op_sel:[1,1,0] op_sel_hi:[1,0,1] neg_lo:[1,0,0]
	v_pk_fma_f32 v[204:205], v[36:37], v[204:205], v[244:245] op_sel:[1,1,0] op_sel_hi:[1,0,1] neg_lo:[1,0,0]
	v_pk_fma_f32 v[206:207], v[38:39], v[206:207], v[254:255] op_sel:[1,1,0] op_sel_hi:[1,0,1] neg_lo:[1,0,0]
	v_cvt_pk_bf16_f32 v124, v200, v201
	v_cvt_pk_bf16_f32 v125, v202, v203
	v_cvt_pk_bf16_f32 v126, v204, v205
	v_cvt_pk_bf16_f32 v127, v206, v207
	ds_write_b128 v241, v[124:127] offset:0
	v_pk_mov_b32 v[232:233], v[136:137], v[152:153] op_sel:[1,1]
	v_pk_mov_b32 v[234:235], v[140:141], v[156:157] op_sel:[1,1]
	v_pk_mov_b32 v[244:245], v[144:145], v[160:161] op_sel:[1,1]
	v_pk_mov_b32 v[254:255], v[148:149], v[164:165] op_sel:[1,1]
	v_pk_fma_f32 v[232:233], v[32:33], v[200:201], v[232:233] op_sel_hi:[0,1,1]
	v_pk_fma_f32 v[234:235], v[34:35], v[202:203], v[234:235] op_sel_hi:[0,1,1]
	v_pk_fma_f32 v[244:245], v[36:37], v[204:205], v[244:245] op_sel_hi:[0,1,1]
	v_pk_fma_f32 v[254:255], v[38:39], v[206:207], v[254:255] op_sel_hi:[0,1,1]
	v_pk_fma_f32 v[200:201], v[32:33], v[200:201], v[232:233] op_sel:[1,1,0] op_sel_hi:[1,0,1] neg_lo:[1,0,0]
	v_pk_fma_f32 v[202:203], v[34:35], v[202:203], v[234:235] op_sel:[1,1,0] op_sel_hi:[1,0,1] neg_lo:[1,0,0]
	v_pk_fma_f32 v[204:205], v[36:37], v[204:205], v[244:245] op_sel:[1,1,0] op_sel_hi:[1,0,1] neg_lo:[1,0,0]
	v_pk_fma_f32 v[206:207], v[38:39], v[206:207], v[254:255] op_sel:[1,1,0] op_sel_hi:[1,0,1] neg_lo:[1,0,0]
	v_cvt_pk_bf16_f32 v124, v200, v201
	v_cvt_pk_bf16_f32 v125, v202, v203
	v_cvt_pk_bf16_f32 v126, v204, v205
	v_cvt_pk_bf16_f32 v127, v206, v207
	ds_write_b128 v241, v[124:127] offset:256
	s_waitcnt lgkmcnt(2)
	v_mfma_f32_16x16x32_bf16 v[120:123], v[40:43], v[216:219], 0
	v_mfma_f32_16x16x32_bf16 v[120:123], v[44:47], v[220:223], v[120:123]
	v_mfma_f32_16x16x32_bf16 v[120:123], v[48:51], v[224:227], v[120:123]
	v_mfma_f32_16x16x32_bf16 v[120:123], v[52:55], v[228:231], v[120:123]
	v_pk_mov_b32 v[232:233], v[138:139], v[154:155] op_sel:[0,0]
	v_pk_mov_b32 v[234:235], v[142:143], v[158:159] op_sel:[0,0]
	v_pk_mov_b32 v[244:245], v[146:147], v[162:163] op_sel:[0,0]
	v_pk_mov_b32 v[254:255], v[150:151], v[166:167] op_sel:[0,0]
	v_pk_fma_f32 v[232:233], v[32:33], v[200:201], v[232:233] op_sel_hi:[0,1,1]
	v_pk_fma_f32 v[234:235], v[34:35], v[202:203], v[234:235] op_sel_hi:[0,1,1]
	v_pk_fma_f32 v[244:245], v[36:37], v[204:205], v[244:245] op_sel_hi:[0,1,1]
	v_pk_fma_f32 v[254:255], v[38:39], v[206:207], v[254:255] op_sel_hi:[0,1,1]
	v_pk_fma_f32 v[200:201], v[32:33], v[200:201], v[232:233] op_sel:[1,1,0] op_sel_hi:[1,0,1] neg_lo:[1,0,0]
	v_pk_fma_f32 v[202:203], v[34:35], v[202:203], v[234:235] op_sel:[1,1,0] op_sel_hi:[1,0,1] neg_lo:[1,0,0]
	v_pk_fma_f32 v[204:205], v[36:37], v[204:205], v[244:245] op_sel:[1,1,0] op_sel_hi:[1,0,1] neg_lo:[1,0,0]
	v_pk_fma_f32 v[206:207], v[38:39], v[206:207], v[254:255] op_sel:[1,1,0] op_sel_hi:[1,0,1] neg_lo:[1,0,0]
	v_cvt_pk_bf16_f32 v124, v200, v201
	v_cvt_pk_bf16_f32 v125, v202, v203
	v_cvt_pk_bf16_f32 v126, v204, v205
	v_cvt_pk_bf16_f32 v127, v206, v207
	ds_write_b128 v241, v[124:127] offset:512
	v_pk_mov_b32 v[232:233], v[138:139], v[154:155] op_sel:[1,1]
	v_pk_mov_b32 v[234:235], v[142:143], v[158:159] op_sel:[1,1]
	v_pk_mov_b32 v[244:245], v[146:147], v[162:163] op_sel:[1,1]
	v_pk_mov_b32 v[254:255], v[150:151], v[166:167] op_sel:[1,1]
	v_pk_fma_f32 v[232:233], v[32:33], v[200:201], v[232:233] op_sel_hi:[0,1,1]
	v_pk_fma_f32 v[234:235], v[34:35], v[202:203], v[234:235] op_sel_hi:[0,1,1]
	v_pk_fma_f32 v[244:245], v[36:37], v[204:205], v[244:245] op_sel_hi:[0,1,1]
	v_pk_fma_f32 v[254:255], v[38:39], v[206:207], v[254:255] op_sel_hi:[0,1,1]
	v_pk_fma_f32 v[200:201], v[32:33], v[200:201], v[232:233] op_sel:[1,1,0] op_sel_hi:[1,0,1] neg_lo:[1,0,0]
	v_pk_fma_f32 v[202:203], v[34:35], v[202:203], v[234:235] op_sel:[1,1,0] op_sel_hi:[1,0,1] neg_lo:[1,0,0]
	v_pk_fma_f32 v[204:205], v[36:37], v[204:205], v[244:245] op_sel:[1,1,0] op_sel_hi:[1,0,1] neg_lo:[1,0,0]
	v_pk_fma_f32 v[206:207], v[38:39], v[206:207], v[254:255] op_sel:[1,1,0] op_sel_hi:[1,0,1] neg_lo:[1,0,0]
	v_cvt_pk_bf16_f32 v124, v200, v201
	v_cvt_pk_bf16_f32 v125, v202, v203
	v_cvt_pk_bf16_f32 v126, v204, v205
	v_cvt_pk_bf16_f32 v127, v206, v207
	ds_write_b128 v241, v[124:127] offset:768
	global_load_dwordx4 v[88:91], v238, s[20:21]
	v_add_u32_e32 v238, v238, v243
	v_cvt_pk_bf16_f32 v124, v120, v121
	v_cvt_pk_bf16_f32 v125, v122, v123
	s_nop 0
	global_store_dwordx2 v239, v[124:125], s[24:25]
	v_add_u32_e32 v239, v239, v243
	s_waitcnt vmcnt(33)
; __device__ __forceinline__ unsigned f2bf(float f) { unsigned u = __builtin_bit_cast(unsigned, f); return (u + 0x7fffu + ((u >> 16) & 1u)) >> 16; }
; __device__ __forceinline__ bf16x8 pack8(const float (&f)[8]) { u32x4 h; h.x = pk2(f[0], f[1]); h.y = pk2(f[2], f[3]); h.z = pk2(f[4], f[5]); h.w = pk2(f[6], f[7]); return __builtin_bit_cast(bf16x8, h); }
; template <bool FINAL> __device__ __forceinline__ void phase_s5_scan(const Fr& F) {
;     ...
;         for (int sub = 0; sub < 4; ++sub) {
;             const bf16x8 A1 = __builtin_bit_cast(bf16x8, uc[sub]);
; #pragma unroll
;             for (int nt = 0; nt < 8; ++nt) {
;                 f32x4 acc = {0.f, 0.f, 0.f, 0.f};
;                 acc = __builtin_amdgcn_mfma_f32_16x16x32_bf16(A1, B1[nt], acc, 0, 0, 0);
; #pragma unroll
;                 for (int reg = 0; reg < 4; ++reg) BUl[(4 * lq + reg) * 132 + 16 * nt + l15] = acc[reg];
;             }
;             asm volatile("s_waitcnt lgkmcnt(0)" ::: "memory");
; #pragma unroll 4
;             for (int jj = 0; jj < 16; ++jj) {
;                 const float br_ = BUl[jj * 132 + lane], bi_ = BUl[jj * 132 + 64 + lane];
;                 const float nr = ar * xr - ai * xi + br_, ni = ar * xi + ai * xr + bi_; xr = nr; xi = ni;
;                 if (FINAL) { BUl[jj * 132 + lane] = xr; BUl[jj * 132 + 64 + lane] = xi; }
;             }
;             if (FINAL) {
;                 asm volatile("s_waitcnt lgkmcnt(0)" ::: "memory");
;                 f32x4 acc = {0.f, 0.f, 0.f, 0.f};
; #pragma unroll
;                 for (int ks = 0; ks < 4; ++ks) {
;                     const f32x4 t0 = *(const f32x4*)(BUl + l15 * 132 + 32 * ks + 8 * lq), t1 = *(const f32x4*)(BUl + l15 * 132 + 32 * ks + 8 * lq + 4);
;                     const float xf[8] = {t0.x, t0.y, t0.z, t0.w, t1.x, t1.y, t1.z, t1.w};
;                     acc = __builtin_amdgcn_mfma_f32_16x16x32_bf16(pack8(xf), Chi[ks], acc, 0, 0, 0);
;                 }
; #pragma unroll
;                 for (int reg = 0; reg < 4; ++reg) { const int tok = tokof(s, chunk * 64 + sub * 16 + 4 * lq + reg);
;                     Yb[((size_t)b * TB + tok) * D + g * 16 + l15] = (bf16)f2bf(acc[reg]); }
;                 asm volatile("s_waitcnt lgkmcnt(0)" ::: "memory");
	v_mfma_f32_16x16x32_bf16 v[136:139], v[96:99], v[0:3], 0
	v_mfma_f32_16x16x32_bf16 v[140:143], v[96:99], v[4:7], 0
	v_mfma_f32_16x16x32_bf16 v[144:147], v[96:99], v[8:11], 0
	v_mfma_f32_16x16x32_bf16 v[148:151], v[96:99], v[12:15], 0
	v_mfma_f32_16x16x32_bf16 v[152:155], v[96:99], v[16:19], 0
	v_mfma_f32_16x16x32_bf16 v[156:159], v[96:99], v[20:23], 0
	v_mfma_f32_16x16x32_bf16 v[160:163], v[96:99], v[24:27], 0
	v_mfma_f32_16x16x32_bf16 v[164:167], v[96:99], v[28:31], 0
	ds_read_b128 v[216:219], v242 offset:0
	ds_read_b128 v[220:223], v242 offset:64
	ds_read_b128 v[224:227], v242 offset:128
	ds_read_b128 v[228:231], v242 offset:192
	v_pk_mov_b32 v[232:233], v[168:169], v[184:185] op_sel:[0,0]
	v_pk_mov_b32 v[234:235], v[172:173], v[188:189] op_sel:[0,0]
	v_pk_mov_b32 v[244:245], v[176:177], v[192:193] op_sel:[0,0]
	v_pk_mov_b32 v[254:255], v[180:181], v[196:197] op_sel:[0,0]
	v_pk_fma_f32 v[232:233], v[32:33], v[200:201], v[232:233] op_sel_hi:[0,1,1]
	v_pk_fma_f32 v[234:235], v[34:35], v[202:203], v[234:235] op_sel_hi:[0,1,1]
	v_pk_fma_f32 v[244:245], v[36:37], v[204:205], v[244:245] op_sel_hi:[0,1,1]
	v_pk_fma_f32 v[254:255], v[38:39], v[206:207], v[254:255] op_sel_hi:[0,1,1]
	v_pk_fma_f32 v[200:201], v[32:33], v[200:201], v[232:233] op_sel:[1,1,0] op_sel_hi:[1,0,1] neg_lo:[1,0,0]
	v_pk_fma_f32 v[202:203], v[34:35], v[202:203], v[234:235] op_sel:[1,1,0] op_sel_hi:[1,0,1] neg_lo:[1,0,0]
	v_pk_fma_f32 v[204:205], v[36:37], v[204:205], v[244:245] op_sel:[1,1,0] op_sel_hi:[1,0,1] neg_lo:[1,0,0]
	v_pk_fma_f32 v[206:207], v[38:39], v[206:207], v[254:255] op_sel:[1,1,0] op_sel_hi:[1,0,1] neg_lo:[1,0,0]
	v_cvt_pk_bf16_f32 v124, v200, v201
	v_cvt_pk_bf16_f32 v125, v202, v203
	v_cvt_pk_bf16_f32 v126, v204, v205
	v_cvt_pk_bf16_f32 v127, v206, v207
	ds_write_b128 v241, v[124:127] offset:4096
	v_pk_mov_b32 v[232:233], v[168:169], v[184:185] op_sel:[1,1]
	v_pk_mov_b32 v[234:235], v[172:173], v[188:189] op_sel:[1,1]
	v_pk_mov_b32 v[244:245], v[176:177], v[192:193] op_sel:[1,1]
	v_pk_mov_b32 v[254:255], v[180:181], v[196:197] op_sel:[1,1]
	v_pk_fma_f32 v[232:233], v[32:33], v[200:201], v[232:233] op_sel_hi:[0,1,1]
	v_pk_fma_f32 v[234:235], v[34:35], v[202:203], v[234:235] op_sel_hi:[0,1,1]
	v_pk_fma_f32 v[244:245], v[36:37], v[204:205], v[244:245] op_sel_hi:[0,1,1]
	v_pk_fma_f32 v[254:255], v[38:39], v[206:207], v[254:255] op_sel_hi:[0,1,1]
	v_pk_fma_f32 v[200:201], v[32:33], v[200:201], v[232:233] op_sel:[1,1,0] op_sel_hi:[1,0,1] neg_lo:[1,0,0]
	v_pk_fma_f32 v[202:203], v[34:35], v[202:203], v[234:235] op_sel:[1,1,0] op_sel_hi:[1,0,1] neg_lo:[1,0,0]
	v_pk_fma_f32 v[204:205], v[36:37], v[204:205], v[244:245] op_sel:[1,1,0] op_sel_hi:[1,0,1] neg_lo:[1,0,0]
	v_pk_fma_f32 v[206:207], v[38:39], v[206:207], v[254:255] op_sel:[1,1,0] op_sel_hi:[1,0,1] neg_lo:[1,0,0]
	v_cvt_pk_bf16_f32 v124, v200, v201
	v_cvt_pk_bf16_f32 v125, v202, v203
	v_cvt_pk_bf16_f32 v126, v204, v205
	v_cvt_pk_bf16_f32 v127, v206, v207
	ds_write_b128 v241, v[124:127] offset:4352
	s_waitcnt lgkmcnt(2)
	v_mfma_f32_16x16x32_bf16 v[120:123], v[40:43], v[216:219], 0
	v_mfma_f32_16x16x32_bf16 v[120:123], v[44:47], v[220:223], v[120:123]
	v_mfma_f32_16x16x32_bf16 v[120:123], v[48:51], v[224:227], v[120:123]
	v_mfma_f32_16x16x32_bf16 v[120:123], v[52:55], v[228:231], v[120:123]
	v_pk_mov_b32 v[232:233], v[170:171], v[186:187] op_sel:[0,0]
	v_pk_mov_b32 v[234:235], v[174:175], v[190:191] op_sel:[0,0]
	v_pk_mov_b32 v[244:245], v[178:179], v[194:195] op_sel:[0,0]
	v_pk_mov_b32 v[254:255], v[182:183], v[198:199] op_sel:[0,0]
	v_pk_fma_f32 v[232:233], v[32:33], v[200:201], v[232:233] op_sel_hi:[0,1,1]
	v_pk_fma_f32 v[234:235], v[34:35], v[202:203], v[234:235] op_sel_hi:[0,1,1]
	v_pk_fma_f32 v[244:245], v[36:37], v[204:205], v[244:245] op_sel_hi:[0,1,1]
	v_pk_fma_f32 v[254:255], v[38:39], v[206:207], v[254:255] op_sel_hi:[0,1,1]
	v_pk_fma_f32 v[200:201], v[32:33], v[200:201], v[232:233] op_sel:[1,1,0] op_sel_hi:[1,0,1] neg_lo:[1,0,0]
	v_pk_fma_f32 v[202:203], v[34:35], v[202:203], v[234:235] op_sel:[1,1,0] op_sel_hi:[1,0,1] neg_lo:[1,0,0]
	v_pk_fma_f32 v[204:205], v[36:37], v[204:205], v[244:245] op_sel:[1,1,0] op_sel_hi:[1,0,1] neg_lo:[1,0,0]
	v_pk_fma_f32 v[206:207], v[38:39], v[206:207], v[254:255] op_sel:[1,1,0] op_sel_hi:[1,0,1] neg_lo:[1,0,0]
	v_cvt_pk_bf16_f32 v124, v200, v201
	v_cvt_pk_bf16_f32 v125, v202, v203
	v_cvt_pk_bf16_f32 v126, v204, v205
	v_cvt_pk_bf16_f32 v127, v206, v207
	ds_write_b128 v241, v[124:127] offset:4608
	v_pk_mov_b32 v[232:233], v[170:171], v[186:187] op_sel:[1,1]
	v_pk_mov_b32 v[234:235], v[174:175], v[190:191] op_sel:[1,1]
	v_pk_mov_b32 v[244:245], v[178:179], v[194:195] op_sel:[1,1]
	v_pk_mov_b32 v[254:255], v[182:183], v[198:199] op_sel:[1,1]
	v_pk_fma_f32 v[232:233], v[32:33], v[200:201], v[232:233] op_sel_hi:[0,1,1]
	v_pk_fma_f32 v[234:235], v[34:35], v[202:203], v[234:235] op_sel_hi:[0,1,1]
	v_pk_fma_f32 v[244:245], v[36:37], v[204:205], v[244:245] op_sel_hi:[0,1,1]
	v_pk_fma_f32 v[254:255], v[38:39], v[206:207], v[254:255] op_sel_hi:[0,1,1]
	v_pk_fma_f32 v[200:201], v[32:33], v[200:201], v[232:233] op_sel:[1,1,0] op_sel_hi:[1,0,1] neg_lo:[1,0,0]
	v_pk_fma_f32 v[202:203], v[34:35], v[202:203], v[234:235] op_sel:[1,1,0] op_sel_hi:[1,0,1] neg_lo:[1,0,0]
	v_pk_fma_f32 v[204:205], v[36:37], v[204:205], v[244:245] op_sel:[1,1,0] op_sel_hi:[1,0,1] neg_lo:[1,0,0]
	v_pk_fma_f32 v[206:207], v[38:39], v[206:207], v[254:255] op_sel:[1,1,0] op_sel_hi:[1,0,1] neg_lo:[1,0,0]
	v_cvt_pk_bf16_f32 v124, v200, v201
	v_cvt_pk_bf16_f32 v125, v202, v203
	v_cvt_pk_bf16_f32 v126, v204, v205
	v_cvt_pk_bf16_f32 v127, v206, v207
	ds_write_b128 v241, v[124:127] offset:4864
	global_load_dwordx4 v[92:95], v238, s[20:21]
	v_add_u32_e32 v238, v238, v243
	v_cvt_pk_bf16_f32 v124, v120, v121
	v_cvt_pk_bf16_f32 v125, v122, v123
	s_nop 0
	global_store_dwordx2 v239, v[124:125], s[24:25]
	v_add_u32_e32 v239, v239, v243
	s_waitcnt vmcnt(33)
; __device__ __forceinline__ unsigned f2bf(float f) { unsigned u = __builtin_bit_cast(unsigned, f); return (u + 0x7fffu + ((u >> 16) & 1u)) >> 16; }
; __device__ __forceinline__ bf16x8 pack8(const float (&f)[8]) { u32x4 h; h.x = pk2(f[0], f[1]); h.y = pk2(f[2], f[3]); h.z = pk2(f[4], f[5]); h.w = pk2(f[6], f[7]); return __builtin_bit_cast(bf16x8, h); }
; template <bool FINAL> __device__ __forceinline__ void phase_s5_scan(const Fr& F) {
;     ...
;         for (int sub = 0; sub < 4; ++sub) {
;             const bf16x8 A1 = __builtin_bit_cast(bf16x8, uc[sub]);
; #pragma unroll
;             for (int nt = 0; nt < 8; ++nt) {
;                 f32x4 acc = {0.f, 0.f, 0.f, 0.f};
;                 acc = __builtin_amdgcn_mfma_f32_16x16x32_bf16(A1, B1[nt], acc, 0, 0, 0);
; #pragma unroll
;                 for (int reg = 0; reg < 4; ++reg) BUl[(4 * lq + reg) * 132 + 16 * nt + l15] = acc[reg];
;             }
;             asm volatile("s_waitcnt lgkmcnt(0)" ::: "memory");
; #pragma unroll 4
;             for (int jj = 0; jj < 16; ++jj) {
;                 const float br_ = BUl[jj * 132 + lane], bi_ = BUl[jj * 132 + 64 + lane];
;                 const float nr = ar * xr - ai * xi + br_, ni = ar * xi + ai * xr + bi_; xr = nr; xi = ni;
;                 if (FINAL) { BUl[jj * 132 + lane] = xr; BUl[jj * 132 + 64 + lane] = xi; }
;             }
;             if (FINAL) {
;                 asm volatile("s_waitcnt lgkmcnt(0)" ::: "memory");
;                 f32x4 acc = {0.f, 0.f, 0.f, 0.f};
; #pragma unroll
;                 for (int ks = 0; ks < 4; ++ks) {
;                     const f32x4 t0 = *(const f32x4*)(BUl + l15 * 132 + 32 * ks + 8 * lq), t1 = *(const f32x4*)(BUl + l15 * 132 + 32 * ks + 8 * lq + 4);
;                     const float xf[8] = {t0.x, t0.y, t0.z, t0.w, t1.x, t1.y, t1.z, t1.w};
;                     acc = __builtin_amdgcn_mfma_f32_16x16x32_bf16(pack8(xf), Chi[ks], acc, 0, 0, 0);
;                 }
; #pragma unroll
;                 for (int reg = 0; reg < 4; ++reg) { const int tok = tokof(s, chunk * 64 + sub * 16 + 4 * lq + reg);
;                     Yb[((size_t)b * TB + tok) * D + g * 16 + l15] = (bf16)f2bf(acc[reg]); }
;                 asm volatile("s_waitcnt lgkmcnt(0)" ::: "memory");
	v_mfma_f32_16x16x32_bf16 v[168:171], v[100:103], v[0:3], 0
	v_mfma_f32_16x16x32_bf16 v[172:175], v[100:103], v[4:7], 0
	v_mfma_f32_16x16x32_bf16 v[176:179], v[100:103], v[8:11], 0
	v_mfma_f32_16x16x32_bf16 v[180:183], v[100:103], v[12:15], 0
	v_mfma_f32_16x16x32_bf16 v[184:187], v[100:103], v[16:19], 0
	v_mfma_f32_16x16x32_bf16 v[188:191], v[100:103], v[20:23], 0
	v_mfma_f32_16x16x32_bf16 v[192:195], v[100:103], v[24:27], 0
	v_mfma_f32_16x16x32_bf16 v[196:199], v[100:103], v[28:31], 0
	ds_read_b128 v[216:219], v242 offset:4096
	ds_read_b128 v[220:223], v242 offset:4160
	ds_read_b128 v[224:227], v242 offset:4224
	ds_read_b128 v[228:231], v242 offset:4288
	v_pk_mov_b32 v[232:233], v[136:137], v[152:153] op_sel:[0,0]
	v_pk_mov_b32 v[234:235], v[140:141], v[156:157] op_sel:[0,0]
	v_pk_mov_b32 v[244:245], v[144:145], v[160:161] op_sel:[0,0]
	v_pk_mov_b32 v[254:255], v[148:149], v[164:165] op_sel:[0,0]
	v_pk_fma_f32 v[232:233], v[32:33], v[200:201], v[232:233] op_sel_hi:[0,1,1]
	v_pk_fma_f32 v[234:235], v[34:35], v[202:203], v[234:235] op_sel_hi:[0,1,1]
	v_pk_fma_f32 v[244:245], v[36:37], v[204:205], v[244:245] op_sel_hi:[0,1,1]
	v_pk_fma_f32 v[254:255], v[38:39], v[206:207], v[254:255] op_sel_hi:[0,1,1]
	v_pk_fma_f32 v[200:201], v[32:33], v[200:201], v[232:233] op_sel:[1,1,0] op_sel_hi:[1,0,1] neg_lo:[1,0,0]
	v_pk_fma_f32 v[202:203], v[34:35], v[202:203], v[234:235] op_sel:[1,1,0] op_sel_hi:[1,0,1] neg_lo:[1,0,0]
	v_pk_fma_f32 v[204:205], v[36:37], v[204:205], v[244:245] op_sel:[1,1,0] op_sel_hi:[1,0,1] neg_lo:[1,0,0]
	v_pk_fma_f32 v[206:207], v[38:39], v[206:207], v[254:255] op_sel:[1,1,0] op_sel_hi:[1,0,1] neg_lo:[1,0,0]
	v_cvt_pk_bf16_f32 v124, v200, v201
	v_cvt_pk_bf16_f32 v125, v202, v203
	v_cvt_pk_bf16_f32 v126, v204, v205
	v_cvt_pk_bf16_f32 v127, v206, v207
	ds_write_b128 v241, v[124:127] offset:0
	v_pk_mov_b32 v[232:233], v[136:137], v[152:153] op_sel:[1,1]
	v_pk_mov_b32 v[234:235], v[140:141], v[156:157] op_sel:[1,1]
	v_pk_mov_b32 v[244:245], v[144:145], v[160:161] op_sel:[1,1]
	v_pk_mov_b32 v[254:255], v[148:149], v[164:165] op_sel:[1,1]
	v_pk_fma_f32 v[232:233], v[32:33], v[200:201], v[232:233] op_sel_hi:[0,1,1]
	v_pk_fma_f32 v[234:235], v[34:35], v[202:203], v[234:235] op_sel_hi:[0,1,1]
	v_pk_fma_f32 v[244:245], v[36:37], v[204:205], v[244:245] op_sel_hi:[0,1,1]
	v_pk_fma_f32 v[254:255], v[38:39], v[206:207], v[254:255] op_sel_hi:[0,1,1]
	v_pk_fma_f32 v[200:201], v[32:33], v[200:201], v[232:233] op_sel:[1,1,0] op_sel_hi:[1,0,1] neg_lo:[1,0,0]
	v_pk_fma_f32 v[202:203], v[34:35], v[202:203], v[234:235] op_sel:[1,1,0] op_sel_hi:[1,0,1] neg_lo:[1,0,0]
	v_pk_fma_f32 v[204:205], v[36:37], v[204:205], v[244:245] op_sel:[1,1,0] op_sel_hi:[1,0,1] neg_lo:[1,0,0]
	v_pk_fma_f32 v[206:207], v[38:39], v[206:207], v[254:255] op_sel:[1,1,0] op_sel_hi:[1,0,1] neg_lo:[1,0,0]
	v_cvt_pk_bf16_f32 v124, v200, v201
	v_cvt_pk_bf16_f32 v125, v202, v203
	v_cvt_pk_bf16_f32 v126, v204, v205
	v_cvt_pk_bf16_f32 v127, v206, v207
	ds_write_b128 v241, v[124:127] offset:256
	s_waitcnt lgkmcnt(2)
	v_mfma_f32_16x16x32_bf16 v[120:123], v[40:43], v[216:219], 0
	v_mfma_f32_16x16x32_bf16 v[120:123], v[44:47], v[220:223], v[120:123]
	v_mfma_f32_16x16x32_bf16 v[120:123], v[48:51], v[224:227], v[120:123]
	v_mfma_f32_16x16x32_bf16 v[120:123], v[52:55], v[228:231], v[120:123]
	v_pk_mov_b32 v[232:233], v[138:139], v[154:155] op_sel:[0,0]
	v_pk_mov_b32 v[234:235], v[142:143], v[158:159] op_sel:[0,0]
	v_pk_mov_b32 v[244:245], v[146:147], v[162:163] op_sel:[0,0]
	v_pk_mov_b32 v[254:255], v[150:151], v[166:167] op_sel:[0,0]
	v_pk_fma_f32 v[232:233], v[32:33], v[200:201], v[232:233] op_sel_hi:[0,1,1]
	v_pk_fma_f32 v[234:235], v[34:35], v[202:203], v[234:235] op_sel_hi:[0,1,1]
	v_pk_fma_f32 v[244:245], v[36:37], v[204:205], v[244:245] op_sel_hi:[0,1,1]
	v_pk_fma_f32 v[254:255], v[38:39], v[206:207], v[254:255] op_sel_hi:[0,1,1]
	v_pk_fma_f32 v[200:201], v[32:33], v[200:201], v[232:233] op_sel:[1,1,0] op_sel_hi:[1,0,1] neg_lo:[1,0,0]
	v_pk_fma_f32 v[202:203], v[34:35], v[202:203], v[234:235] op_sel:[1,1,0] op_sel_hi:[1,0,1] neg_lo:[1,0,0]
	v_pk_fma_f32 v[204:205], v[36:37], v[204:205], v[244:245] op_sel:[1,1,0] op_sel_hi:[1,0,1] neg_lo:[1,0,0]
	v_pk_fma_f32 v[206:207], v[38:39], v[206:207], v[254:255] op_sel:[1,1,0] op_sel_hi:[1,0,1] neg_lo:[1,0,0]
	v_cvt_pk_bf16_f32 v124, v200, v201
	v_cvt_pk_bf16_f32 v125, v202, v203
	v_cvt_pk_bf16_f32 v126, v204, v205
	v_cvt_pk_bf16_f32 v127, v206, v207
	ds_write_b128 v241, v[124:127] offset:512
	v_pk_mov_b32 v[232:233], v[138:139], v[154:155] op_sel:[1,1]
	v_pk_mov_b32 v[234:235], v[142:143], v[158:159] op_sel:[1,1]
	v_pk_mov_b32 v[244:245], v[146:147], v[162:163] op_sel:[1,1]
	v_pk_mov_b32 v[254:255], v[150:151], v[166:167] op_sel:[1,1]
	v_pk_fma_f32 v[232:233], v[32:33], v[200:201], v[232:233] op_sel_hi:[0,1,1]
	v_pk_fma_f32 v[234:235], v[34:35], v[202:203], v[234:235] op_sel_hi:[0,1,1]
	v_pk_fma_f32 v[244:245], v[36:37], v[204:205], v[244:245] op_sel_hi:[0,1,1]
	v_pk_fma_f32 v[254:255], v[38:39], v[206:207], v[254:255] op_sel_hi:[0,1,1]
	v_pk_fma_f32 v[200:201], v[32:33], v[200:201], v[232:233] op_sel:[1,1,0] op_sel_hi:[1,0,1] neg_lo:[1,0,0]
	v_pk_fma_f32 v[202:203], v[34:35], v[202:203], v[234:235] op_sel:[1,1,0] op_sel_hi:[1,0,1] neg_lo:[1,0,0]
	v_pk_fma_f32 v[204:205], v[36:37], v[204:205], v[244:245] op_sel:[1,1,0] op_sel_hi:[1,0,1] neg_lo:[1,0,0]
	v_pk_fma_f32 v[206:207], v[38:39], v[206:207], v[254:255] op_sel:[1,1,0] op_sel_hi:[1,0,1] neg_lo:[1,0,0]
	v_cvt_pk_bf16_f32 v124, v200, v201
	v_cvt_pk_bf16_f32 v125, v202, v203
	v_cvt_pk_bf16_f32 v126, v204, v205
	v_cvt_pk_bf16_f32 v127, v206, v207
	ds_write_b128 v241, v[124:127] offset:768
	global_load_dwordx4 v[96:99], v238, s[20:21]
	v_add_u32_e32 v238, v238, v243
	v_cvt_pk_bf16_f32 v124, v120, v121
	v_cvt_pk_bf16_f32 v125, v122, v123
	s_nop 0
	global_store_dwordx2 v239, v[124:125], s[24:25]
	v_add_u32_e32 v239, v239, v243
	s_waitcnt vmcnt(33)
; __device__ __forceinline__ unsigned f2bf(float f) { unsigned u = __builtin_bit_cast(unsigned, f); return (u + 0x7fffu + ((u >> 16) & 1u)) >> 16; }
; __device__ __forceinline__ bf16x8 pack8(const float (&f)[8]) { u32x4 h; h.x = pk2(f[0], f[1]); h.y = pk2(f[2], f[3]); h.z = pk2(f[4], f[5]); h.w = pk2(f[6], f[7]); return __builtin_bit_cast(bf16x8, h); }
; template <bool FINAL> __device__ __forceinline__ void phase_s5_scan(const Fr& F) {
;     ...
;         for (int sub = 0; sub < 4; ++sub) {
;             const bf16x8 A1 = __builtin_bit_cast(bf16x8, uc[sub]);
; #pragma unroll
;             for (int nt = 0; nt < 8; ++nt) {
;                 f32x4 acc = {0.f, 0.f, 0.f, 0.f};
;                 acc = __builtin_amdgcn_mfma_f32_16x16x32_bf16(A1, B1[nt], acc, 0, 0, 0);
; #pragma unroll
;                 for (int reg = 0; reg < 4; ++reg) BUl[(4 * lq + reg) * 132 + 16 * nt + l15] = acc[reg];
;             }
;             asm volatile("s_waitcnt lgkmcnt(0)" ::: "memory");
; #pragma unroll 4
;             for (int jj = 0; jj < 16; ++jj) {
;                 const float br_ = BUl[jj * 132 + lane], bi_ = BUl[jj * 132 + 64 + lane];
;                 const float nr = ar * xr - ai * xi + br_, ni = ar * xi + ai * xr + bi_; xr = nr; xi = ni;
;                 if (FINAL) { BUl[jj * 132 + lane] = xr; BUl[jj * 132 + 64 + lane] = xi; }
;             }
;             if (FINAL) {
;                 asm volatile("s_waitcnt lgkmcnt(0)" ::: "memory");
;                 f32x4 acc = {0.f, 0.f, 0.f, 0.f};
; #pragma unroll
;                 for (int ks = 0; ks < 4; ++ks) {
;                     const f32x4 t0 = *(const f32x4*)(BUl + l15 * 132 + 32 * ks + 8 * lq), t1 = *(const f32x4*)(BUl + l15 * 132 + 32 * ks + 8 * lq + 4);
;                     const float xf[8] = {t0.x, t0.y, t0.z, t0.w, t1.x, t1.y, t1.z, t1.w};
;                     acc = __builtin_amdgcn_mfma_f32_16x16x32_bf16(pack8(xf), Chi[ks], acc, 0, 0, 0);
;                 }
; #pragma unroll
;                 for (int reg = 0; reg < 4; ++reg) { const int tok = tokof(s, chunk * 64 + sub * 16 + 4 * lq + reg);
;                     Yb[((size_t)b * TB + tok) * D + g * 16 + l15] = (bf16)f2bf(acc[reg]); }
;                 asm volatile("s_waitcnt lgkmcnt(0)" ::: "memory");
	v_mfma_f32_16x16x32_bf16 v[136:139], v[104:107], v[0:3], 0
	v_mfma_f32_16x16x32_bf16 v[140:143], v[104:107], v[4:7], 0
	v_mfma_f32_16x16x32_bf16 v[144:147], v[104:107], v[8:11], 0
	v_mfma_f32_16x16x32_bf16 v[148:151], v[104:107], v[12:15], 0
	v_mfma_f32_16x16x32_bf16 v[152:155], v[104:107], v[16:19], 0
	v_mfma_f32_16x16x32_bf16 v[156:159], v[104:107], v[20:23], 0
	v_mfma_f32_16x16x32_bf16 v[160:163], v[104:107], v[24:27], 0
	v_mfma_f32_16x16x32_bf16 v[164:167], v[104:107], v[28:31], 0
	ds_read_b128 v[216:219], v242 offset:0
	ds_read_b128 v[220:223], v242 offset:64
	ds_read_b128 v[224:227], v242 offset:128
	ds_read_b128 v[228:231], v242 offset:192
	v_pk_mov_b32 v[232:233], v[168:169], v[184:185] op_sel:[0,0]
	v_pk_mov_b32 v[234:235], v[172:173], v[188:189] op_sel:[0,0]
	v_pk_mov_b32 v[244:245], v[176:177], v[192:193] op_sel:[0,0]
	v_pk_mov_b32 v[254:255], v[180:181], v[196:197] op_sel:[0,0]
	v_pk_fma_f32 v[232:233], v[32:33], v[200:201], v[232:233] op_sel_hi:[0,1,1]
	v_pk_fma_f32 v[234:235], v[34:35], v[202:203], v[234:235] op_sel_hi:[0,1,1]
	v_pk_fma_f32 v[244:245], v[36:37], v[204:205], v[244:245] op_sel_hi:[0,1,1]
	v_pk_fma_f32 v[254:255], v[38:39], v[206:207], v[254:255] op_sel_hi:[0,1,1]
	v_pk_fma_f32 v[200:201], v[32:33], v[200:201], v[232:233] op_sel:[1,1,0] op_sel_hi:[1,0,1] neg_lo:[1,0,0]
	v_pk_fma_f32 v[202:203], v[34:35], v[202:203], v[234:235] op_sel:[1,1,0] op_sel_hi:[1,0,1] neg_lo:[1,0,0]
	v_pk_fma_f32 v[204:205], v[36:37], v[204:205], v[244:245] op_sel:[1,1,0] op_sel_hi:[1,0,1] neg_lo:[1,0,0]
	v_pk_fma_f32 v[206:207], v[38:39], v[206:207], v[254:255] op_sel:[1,1,0] op_sel_hi:[1,0,1] neg_lo:[1,0,0]
	v_cvt_pk_bf16_f32 v124, v200, v201
	v_cvt_pk_bf16_f32 v125, v202, v203
	v_cvt_pk_bf16_f32 v126, v204, v205
	v_cvt_pk_bf16_f32 v127, v206, v207
	ds_write_b128 v241, v[124:127] offset:4096
	v_pk_mov_b32 v[232:233], v[168:169], v[184:185] op_sel:[1,1]
	v_pk_mov_b32 v[234:235], v[172:173], v[188:189] op_sel:[1,1]
	v_pk_mov_b32 v[244:245], v[176:177], v[192:193] op_sel:[1,1]
	v_pk_mov_b32 v[254:255], v[180:181], v[196:197] op_sel:[1,1]
	v_pk_fma_f32 v[232:233], v[32:33], v[200:201], v[232:233] op_sel_hi:[0,1,1]
	v_pk_fma_f32 v[234:235], v[34:35], v[202:203], v[234:235] op_sel_hi:[0,1,1]
	v_pk_fma_f32 v[244:245], v[36:37], v[204:205], v[244:245] op_sel_hi:[0,1,1]
	v_pk_fma_f32 v[254:255], v[38:39], v[206:207], v[254:255] op_sel_hi:[0,1,1]
	v_pk_fma_f32 v[200:201], v[32:33], v[200:201], v[232:233] op_sel:[1,1,0] op_sel_hi:[1,0,1] neg_lo:[1,0,0]
	v_pk_fma_f32 v[202:203], v[34:35], v[202:203], v[234:235] op_sel:[1,1,0] op_sel_hi:[1,0,1] neg_lo:[1,0,0]
	v_pk_fma_f32 v[204:205], v[36:37], v[204:205], v[244:245] op_sel:[1,1,0] op_sel_hi:[1,0,1] neg_lo:[1,0,0]
	v_pk_fma_f32 v[206:207], v[38:39], v[206:207], v[254:255] op_sel:[1,1,0] op_sel_hi:[1,0,1] neg_lo:[1,0,0]
	v_cvt_pk_bf16_f32 v124, v200, v201
	v_cvt_pk_bf16_f32 v125, v202, v203
	v_cvt_pk_bf16_f32 v126, v204, v205
	v_cvt_pk_bf16_f32 v127, v206, v207
	ds_write_b128 v241, v[124:127] offset:4352
	s_waitcnt lgkmcnt(2)
	v_mfma_f32_16x16x32_bf16 v[120:123], v[40:43], v[216:219], 0
	v_mfma_f32_16x16x32_bf16 v[120:123], v[44:47], v[220:223], v[120:123]
	v_mfma_f32_16x16x32_bf16 v[120:123], v[48:51], v[224:227], v[120:123]
	v_mfma_f32_16x16x32_bf16 v[120:123], v[52:55], v[228:231], v[120:123]
	v_pk_mov_b32 v[232:233], v[170:171], v[186:187] op_sel:[0,0]
	v_pk_mov_b32 v[234:235], v[174:175], v[190:191] op_sel:[0,0]
	v_pk_mov_b32 v[244:245], v[178:179], v[194:195] op_sel:[0,0]
	v_pk_mov_b32 v[254:255], v[182:183], v[198:199] op_sel:[0,0]
	v_pk_fma_f32 v[232:233], v[32:33], v[200:201], v[232:233] op_sel_hi:[0,1,1]
	v_pk_fma_f32 v[234:235], v[34:35], v[202:203], v[234:235] op_sel_hi:[0,1,1]
	v_pk_fma_f32 v[244:245], v[36:37], v[204:205], v[244:245] op_sel_hi:[0,1,1]
	v_pk_fma_f32 v[254:255], v[38:39], v[206:207], v[254:255] op_sel_hi:[0,1,1]
	v_pk_fma_f32 v[200:201], v[32:33], v[200:201], v[232:233] op_sel:[1,1,0] op_sel_hi:[1,0,1] neg_lo:[1,0,0]
	v_pk_fma_f32 v[202:203], v[34:35], v[202:203], v[234:235] op_sel:[1,1,0] op_sel_hi:[1,0,1] neg_lo:[1,0,0]
	v_pk_fma_f32 v[204:205], v[36:37], v[204:205], v[244:245] op_sel:[1,1,0] op_sel_hi:[1,0,1] neg_lo:[1,0,0]
	v_pk_fma_f32 v[206:207], v[38:39], v[206:207], v[254:255] op_sel:[1,1,0] op_sel_hi:[1,0,1] neg_lo:[1,0,0]
	v_cvt_pk_bf16_f32 v124, v200, v201
	v_cvt_pk_bf16_f32 v125, v202, v203
	v_cvt_pk_bf16_f32 v126, v204, v205
	v_cvt_pk_bf16_f32 v127, v206, v207
	ds_write_b128 v241, v[124:127] offset:4608
	v_pk_mov_b32 v[232:233], v[170:171], v[186:187] op_sel:[1,1]
	v_pk_mov_b32 v[234:235], v[174:175], v[190:191] op_sel:[1,1]
	v_pk_mov_b32 v[244:245], v[178:179], v[194:195] op_sel:[1,1]
	v_pk_mov_b32 v[254:255], v[182:183], v[198:199] op_sel:[1,1]
	v_pk_fma_f32 v[232:233], v[32:33], v[200:201], v[232:233] op_sel_hi:[0,1,1]
	v_pk_fma_f32 v[234:235], v[34:35], v[202:203], v[234:235] op_sel_hi:[0,1,1]
	v_pk_fma_f32 v[244:245], v[36:37], v[204:205], v[244:245] op_sel_hi:[0,1,1]
	v_pk_fma_f32 v[254:255], v[38:39], v[206:207], v[254:255] op_sel_hi:[0,1,1]
	v_pk_fma_f32 v[200:201], v[32:33], v[200:201], v[232:233] op_sel:[1,1,0] op_sel_hi:[1,0,1] neg_lo:[1,0,0]
	v_pk_fma_f32 v[202:203], v[34:35], v[202:203], v[234:235] op_sel:[1,1,0] op_sel_hi:[1,0,1] neg_lo:[1,0,0]
	v_pk_fma_f32 v[204:205], v[36:37], v[204:205], v[244:245] op_sel:[1,1,0] op_sel_hi:[1,0,1] neg_lo:[1,0,0]
	v_pk_fma_f32 v[206:207], v[38:39], v[206:207], v[254:255] op_sel:[1,1,0] op_sel_hi:[1,0,1] neg_lo:[1,0,0]
	v_cvt_pk_bf16_f32 v124, v200, v201
	v_cvt_pk_bf16_f32 v125, v202, v203
	v_cvt_pk_bf16_f32 v126, v204, v205
	v_cvt_pk_bf16_f32 v127, v206, v207
	ds_write_b128 v241, v[124:127] offset:4864
	global_load_dwordx4 v[100:103], v238, s[20:21]
	v_add_u32_e32 v238, v238, v243
	v_cvt_pk_bf16_f32 v124, v120, v121
	v_cvt_pk_bf16_f32 v125, v122, v123
	s_nop 0
	global_store_dwordx2 v239, v[124:125], s[24:25]
	v_add_u32_e32 v239, v239, v243
	s_waitcnt vmcnt(33)
; __device__ __forceinline__ unsigned f2bf(float f) { unsigned u = __builtin_bit_cast(unsigned, f); return (u + 0x7fffu + ((u >> 16) & 1u)) >> 16; }
; __device__ __forceinline__ bf16x8 pack8(const float (&f)[8]) { u32x4 h; h.x = pk2(f[0], f[1]); h.y = pk2(f[2], f[3]); h.z = pk2(f[4], f[5]); h.w = pk2(f[6], f[7]); return __builtin_bit_cast(bf16x8, h); }
; template <bool FINAL> __device__ __forceinline__ void phase_s5_scan(const Fr& F) {
;     ...
;         for (int sub = 0; sub < 4; ++sub) {
;             const bf16x8 A1 = __builtin_bit_cast(bf16x8, uc[sub]);
; #pragma unroll
;             for (int nt = 0; nt < 8; ++nt) {
;                 f32x4 acc = {0.f, 0.f, 0.f, 0.f};
;                 acc = __builtin_amdgcn_mfma_f32_16x16x32_bf16(A1, B1[nt], acc, 0, 0, 0);
; #pragma unroll
;                 for (int reg = 0; reg < 4; ++reg) BUl[(4 * lq + reg) * 132 + 16 * nt + l15] = acc[reg];
;             }
;             asm volatile("s_waitcnt lgkmcnt(0)" ::: "memory");
; #pragma unroll 4
;             for (int jj = 0; jj < 16; ++jj) {
;                 const float br_ = BUl[jj * 132 + lane], bi_ = BUl[jj * 132 + 64 + lane];
;                 const float nr = ar * xr - ai * xi + br_, ni = ar * xi + ai * xr + bi_; xr = nr; xi = ni;
;                 if (FINAL) { BUl[jj * 132 + lane] = xr; BUl[jj * 132 + 64 + lane] = xi; }
;             }
;             if (FINAL) {
;                 asm volatile("s_waitcnt lgkmcnt(0)" ::: "memory");
;                 f32x4 acc = {0.f, 0.f, 0.f, 0.f};
; #pragma unroll
;                 for (int ks = 0; ks < 4; ++ks) {
;                     const f32x4 t0 = *(const f32x4*)(BUl + l15 * 132 + 32 * ks + 8 * lq), t1 = *(const f32x4*)(BUl + l15 * 132 + 32 * ks + 8 * lq + 4);
;                     const float xf[8] = {t0.x, t0.y, t0.z, t0.w, t1.x, t1.y, t1.z, t1.w};
;                     acc = __builtin_amdgcn_mfma_f32_16x16x32_bf16(pack8(xf), Chi[ks], acc, 0, 0, 0);
;                 }
; #pragma unroll
;                 for (int reg = 0; reg < 4; ++reg) { const int tok = tokof(s, chunk * 64 + sub * 16 + 4 * lq + reg);
;                     Yb[((size_t)b * TB + tok) * D + g * 16 + l15] = (bf16)f2bf(acc[reg]); }
;                 asm volatile("s_waitcnt lgkmcnt(0)" ::: "memory");
	v_mfma_f32_16x16x32_bf16 v[168:171], v[108:111], v[0:3], 0
	v_mfma_f32_16x16x32_bf16 v[172:175], v[108:111], v[4:7], 0
	v_mfma_f32_16x16x32_bf16 v[176:179], v[108:111], v[8:11], 0
	v_mfma_f32_16x16x32_bf16 v[180:183], v[108:111], v[12:15], 0
	v_mfma_f32_16x16x32_bf16 v[184:187], v[108:111], v[16:19], 0
	v_mfma_f32_16x16x32_bf16 v[188:191], v[108:111], v[20:23], 0
	v_mfma_f32_16x16x32_bf16 v[192:195], v[108:111], v[24:27], 0
	v_mfma_f32_16x16x32_bf16 v[196:199], v[108:111], v[28:31], 0
	ds_read_b128 v[216:219], v242 offset:4096
	ds_read_b128 v[220:223], v242 offset:4160
	ds_read_b128 v[224:227], v242 offset:4224
	ds_read_b128 v[228:231], v242 offset:4288
	v_pk_mov_b32 v[232:233], v[136:137], v[152:153] op_sel:[0,0]
	v_pk_mov_b32 v[234:235], v[140:141], v[156:157] op_sel:[0,0]
	v_pk_mov_b32 v[244:245], v[144:145], v[160:161] op_sel:[0,0]
	v_pk_mov_b32 v[254:255], v[148:149], v[164:165] op_sel:[0,0]
	v_pk_fma_f32 v[232:233], v[32:33], v[200:201], v[232:233] op_sel_hi:[0,1,1]
	v_pk_fma_f32 v[234:235], v[34:35], v[202:203], v[234:235] op_sel_hi:[0,1,1]
	v_pk_fma_f32 v[244:245], v[36:37], v[204:205], v[244:245] op_sel_hi:[0,1,1]
	v_pk_fma_f32 v[254:255], v[38:39], v[206:207], v[254:255] op_sel_hi:[0,1,1]
	v_pk_fma_f32 v[200:201], v[32:33], v[200:201], v[232:233] op_sel:[1,1,0] op_sel_hi:[1,0,1] neg_lo:[1,0,0]
	v_pk_fma_f32 v[202:203], v[34:35], v[202:203], v[234:235] op_sel:[1,1,0] op_sel_hi:[1,0,1] neg_lo:[1,0,0]
	v_pk_fma_f32 v[204:205], v[36:37], v[204:205], v[244:245] op_sel:[1,1,0] op_sel_hi:[1,0,1] neg_lo:[1,0,0]
	v_pk_fma_f32 v[206:207], v[38:39], v[206:207], v[254:255] op_sel:[1,1,0] op_sel_hi:[1,0,1] neg_lo:[1,0,0]
	v_cvt_pk_bf16_f32 v124, v200, v201
	v_cvt_pk_bf16_f32 v125, v202, v203
	v_cvt_pk_bf16_f32 v126, v204, v205
	v_cvt_pk_bf16_f32 v127, v206, v207
	ds_write_b128 v241, v[124:127] offset:0
	v_pk_mov_b32 v[232:233], v[136:137], v[152:153] op_sel:[1,1]
	v_pk_mov_b32 v[234:235], v[140:141], v[156:157] op_sel:[1,1]
	v_pk_mov_b32 v[244:245], v[144:145], v[160:161] op_sel:[1,1]
	v_pk_mov_b32 v[254:255], v[148:149], v[164:165] op_sel:[1,1]
	v_pk_fma_f32 v[232:233], v[32:33], v[200:201], v[232:233] op_sel_hi:[0,1,1]
	v_pk_fma_f32 v[234:235], v[34:35], v[202:203], v[234:235] op_sel_hi:[0,1,1]
	v_pk_fma_f32 v[244:245], v[36:37], v[204:205], v[244:245] op_sel_hi:[0,1,1]
	v_pk_fma_f32 v[254:255], v[38:39], v[206:207], v[254:255] op_sel_hi:[0,1,1]
	v_pk_fma_f32 v[200:201], v[32:33], v[200:201], v[232:233] op_sel:[1,1,0] op_sel_hi:[1,0,1] neg_lo:[1,0,0]
	v_pk_fma_f32 v[202:203], v[34:35], v[202:203], v[234:235] op_sel:[1,1,0] op_sel_hi:[1,0,1] neg_lo:[1,0,0]
	v_pk_fma_f32 v[204:205], v[36:37], v[204:205], v[244:245] op_sel:[1,1,0] op_sel_hi:[1,0,1] neg_lo:[1,0,0]
	v_pk_fma_f32 v[206:207], v[38:39], v[206:207], v[254:255] op_sel:[1,1,0] op_sel_hi:[1,0,1] neg_lo:[1,0,0]
	v_cvt_pk_bf16_f32 v124, v200, v201
	v_cvt_pk_bf16_f32 v125, v202, v203
	v_cvt_pk_bf16_f32 v126, v204, v205
	v_cvt_pk_bf16_f32 v127, v206, v207
	ds_write_b128 v241, v[124:127] offset:256
	s_waitcnt lgkmcnt(2)
	v_mfma_f32_16x16x32_bf16 v[120:123], v[40:43], v[216:219], 0
	v_mfma_f32_16x16x32_bf16 v[120:123], v[44:47], v[220:223], v[120:123]
	v_mfma_f32_16x16x32_bf16 v[120:123], v[48:51], v[224:227], v[120:123]
	v_mfma_f32_16x16x32_bf16 v[120:123], v[52:55], v[228:231], v[120:123]
	v_pk_mov_b32 v[232:233], v[138:139], v[154:155] op_sel:[0,0]
	v_pk_mov_b32 v[234:235], v[142:143], v[158:159] op_sel:[0,0]
	v_pk_mov_b32 v[244:245], v[146:147], v[162:163] op_sel:[0,0]
	v_pk_mov_b32 v[254:255], v[150:151], v[166:167] op_sel:[0,0]
	v_pk_fma_f32 v[232:233], v[32:33], v[200:201], v[232:233] op_sel_hi:[0,1,1]
	v_pk_fma_f32 v[234:235], v[34:35], v[202:203], v[234:235] op_sel_hi:[0,1,1]
	v_pk_fma_f32 v[244:245], v[36:37], v[204:205], v[244:245] op_sel_hi:[0,1,1]
	v_pk_fma_f32 v[254:255], v[38:39], v[206:207], v[254:255] op_sel_hi:[0,1,1]
	v_pk_fma_f32 v[200:201], v[32:33], v[200:201], v[232:233] op_sel:[1,1,0] op_sel_hi:[1,0,1] neg_lo:[1,0,0]
	v_pk_fma_f32 v[202:203], v[34:35], v[202:203], v[234:235] op_sel:[1,1,0] op_sel_hi:[1,0,1] neg_lo:[1,0,0]
	v_pk_fma_f32 v[204:205], v[36:37], v[204:205], v[244:245] op_sel:[1,1,0] op_sel_hi:[1,0,1] neg_lo:[1,0,0]
	v_pk_fma_f32 v[206:207], v[38:39], v[206:207], v[254:255] op_sel:[1,1,0] op_sel_hi:[1,0,1] neg_lo:[1,0,0]
	v_cvt_pk_bf16_f32 v124, v200, v201
	v_cvt_pk_bf16_f32 v125, v202, v203
	v_cvt_pk_bf16_f32 v126, v204, v205
	v_cvt_pk_bf16_f32 v127, v206, v207
	ds_write_b128 v241, v[124:127] offset:512
	v_pk_mov_b32 v[232:233], v[138:139], v[154:155] op_sel:[1,1]
	v_pk_mov_b32 v[234:235], v[142:143], v[158:159] op_sel:[1,1]
	v_pk_mov_b32 v[244:245], v[146:147], v[162:163] op_sel:[1,1]
	v_pk_mov_b32 v[254:255], v[150:151], v[166:167] op_sel:[1,1]
	v_pk_fma_f32 v[232:233], v[32:33], v[200:201], v[232:233] op_sel_hi:[0,1,1]
	v_pk_fma_f32 v[234:235], v[34:35], v[202:203], v[234:235] op_sel_hi:[0,1,1]
	v_pk_fma_f32 v[244:245], v[36:37], v[204:205], v[244:245] op_sel_hi:[0,1,1]
	v_pk_fma_f32 v[254:255], v[38:39], v[206:207], v[254:255] op_sel_hi:[0,1,1]
	v_pk_fma_f32 v[200:201], v[32:33], v[200:201], v[232:233] op_sel:[1,1,0] op_sel_hi:[1,0,1] neg_lo:[1,0,0]
	v_pk_fma_f32 v[202:203], v[34:35], v[202:203], v[234:235] op_sel:[1,1,0] op_sel_hi:[1,0,1] neg_lo:[1,0,0]
	v_pk_fma_f32 v[204:205], v[36:37], v[204:205], v[244:245] op_sel:[1,1,0] op_sel_hi:[1,0,1] neg_lo:[1,0,0]
	v_pk_fma_f32 v[206:207], v[38:39], v[206:207], v[254:255] op_sel:[1,1,0] op_sel_hi:[1,0,1] neg_lo:[1,0,0]
	v_cvt_pk_bf16_f32 v124, v200, v201
	v_cvt_pk_bf16_f32 v125, v202, v203
	v_cvt_pk_bf16_f32 v126, v204, v205
	v_cvt_pk_bf16_f32 v127, v206, v207
	ds_write_b128 v241, v[124:127] offset:768
	global_load_dwordx4 v[104:107], v238, s[20:21]
	v_add_u32_e32 v238, v238, v243
	v_cvt_pk_bf16_f32 v124, v120, v121
	v_cvt_pk_bf16_f32 v125, v122, v123
	s_nop 0
	global_store_dwordx2 v239, v[124:125], s[24:25]
	v_add_u32_e32 v239, v239, v243
	s_waitcnt vmcnt(33)
; __device__ __forceinline__ unsigned f2bf(float f) { unsigned u = __builtin_bit_cast(unsigned, f); return (u + 0x7fffu + ((u >> 16) & 1u)) >> 16; }
; __device__ __forceinline__ bf16x8 pack8(const float (&f)[8]) { u32x4 h; h.x = pk2(f[0], f[1]); h.y = pk2(f[2], f[3]); h.z = pk2(f[4], f[5]); h.w = pk2(f[6], f[7]); return __builtin_bit_cast(bf16x8, h); }
; template <bool FINAL> __device__ __forceinline__ void phase_s5_scan(const Fr& F) {
;     ...
;         for (int sub = 0; sub < 4; ++sub) {
;             const bf16x8 A1 = __builtin_bit_cast(bf16x8, uc[sub]);
; #pragma unroll
;             for (int nt = 0; nt < 8; ++nt) {
;                 f32x4 acc = {0.f, 0.f, 0.f, 0.f};
;                 acc = __builtin_amdgcn_mfma_f32_16x16x32_bf16(A1, B1[nt], acc, 0, 0, 0);
; #pragma unroll
;                 for (int reg = 0; reg < 4; ++reg) BUl[(4 * lq + reg) * 132 + 16 * nt + l15] = acc[reg];
;             }
;             asm volatile("s_waitcnt lgkmcnt(0)" ::: "memory");
; #pragma unroll 4
;             for (int jj = 0; jj < 16; ++jj) {
;                 const float br_ = BUl[jj * 132 + lane], bi_ = BUl[jj * 132 + 64 + lane];
;                 const float nr = ar * xr - ai * xi + br_, ni = ar * xi + ai * xr + bi_; xr = nr; xi = ni;
;                 if (FINAL) { BUl[jj * 132 + lane] = xr; BUl[jj * 132 + 64 + lane] = xi; }
;             }
;             if (FINAL) {
;                 asm volatile("s_waitcnt lgkmcnt(0)" ::: "memory");
;                 f32x4 acc = {0.f, 0.f, 0.f, 0.f};
; #pragma unroll
;                 for (int ks = 0; ks < 4; ++ks) {
;                     const f32x4 t0 = *(const f32x4*)(BUl + l15 * 132 + 32 * ks + 8 * lq), t1 = *(const f32x4*)(BUl + l15 * 132 + 32 * ks + 8 * lq + 4);
;                     const float xf[8] = {t0.x, t0.y, t0.z, t0.w, t1.x, t1.y, t1.z, t1.w};
;                     acc = __builtin_amdgcn_mfma_f32_16x16x32_bf16(pack8(xf), Chi[ks], acc, 0, 0, 0);
;                 }
; #pragma unroll
;                 for (int reg = 0; reg < 4; ++reg) { const int tok = tokof(s, chunk * 64 + sub * 16 + 4 * lq + reg);
;                     Yb[((size_t)b * TB + tok) * D + g * 16 + l15] = (bf16)f2bf(acc[reg]); }
;                 asm volatile("s_waitcnt lgkmcnt(0)" ::: "memory");
	v_mfma_f32_16x16x32_bf16 v[136:139], v[112:115], v[0:3], 0
	v_mfma_f32_16x16x32_bf16 v[140:143], v[112:115], v[4:7], 0
	v_mfma_f32_16x16x32_bf16 v[144:147], v[112:115], v[8:11], 0
	v_mfma_f32_16x16x32_bf16 v[148:151], v[112:115], v[12:15], 0
	v_mfma_f32_16x16x32_bf16 v[152:155], v[112:115], v[16:19], 0
	v_mfma_f32_16x16x32_bf16 v[156:159], v[112:115], v[20:23], 0
	v_mfma_f32_16x16x32_bf16 v[160:163], v[112:115], v[24:27], 0
	v_mfma_f32_16x16x32_bf16 v[164:167], v[112:115], v[28:31], 0
	ds_read_b128 v[216:219], v242 offset:0
	ds_read_b128 v[220:223], v242 offset:64
	ds_read_b128 v[224:227], v242 offset:128
	ds_read_b128 v[228:231], v242 offset:192
	v_pk_mov_b32 v[232:233], v[168:169], v[184:185] op_sel:[0,0]
	v_pk_mov_b32 v[234:235], v[172:173], v[188:189] op_sel:[0,0]
	v_pk_mov_b32 v[244:245], v[176:177], v[192:193] op_sel:[0,0]
	v_pk_mov_b32 v[254:255], v[180:181], v[196:197] op_sel:[0,0]
	v_pk_fma_f32 v[232:233], v[32:33], v[200:201], v[232:233] op_sel_hi:[0,1,1]
	v_pk_fma_f32 v[234:235], v[34:35], v[202:203], v[234:235] op_sel_hi:[0,1,1]
	v_pk_fma_f32 v[244:245], v[36:37], v[204:205], v[244:245] op_sel_hi:[0,1,1]
	v_pk_fma_f32 v[254:255], v[38:39], v[206:207], v[254:255] op_sel_hi:[0,1,1]
	v_pk_fma_f32 v[200:201], v[32:33], v[200:201], v[232:233] op_sel:[1,1,0] op_sel_hi:[1,0,1] neg_lo:[1,0,0]
	v_pk_fma_f32 v[202:203], v[34:35], v[202:203], v[234:235] op_sel:[1,1,0] op_sel_hi:[1,0,1] neg_lo:[1,0,0]
	v_pk_fma_f32 v[204:205], v[36:37], v[204:205], v[244:245] op_sel:[1,1,0] op_sel_hi:[1,0,1] neg_lo:[1,0,0]
	v_pk_fma_f32 v[206:207], v[38:39], v[206:207], v[254:255] op_sel:[1,1,0] op_sel_hi:[1,0,1] neg_lo:[1,0,0]
	v_cvt_pk_bf16_f32 v124, v200, v201
	v_cvt_pk_bf16_f32 v125, v202, v203
	v_cvt_pk_bf16_f32 v126, v204, v205
	v_cvt_pk_bf16_f32 v127, v206, v207
	ds_write_b128 v241, v[124:127] offset:4096
	v_pk_mov_b32 v[232:233], v[168:169], v[184:185] op_sel:[1,1]
	v_pk_mov_b32 v[234:235], v[172:173], v[188:189] op_sel:[1,1]
	v_pk_mov_b32 v[244:245], v[176:177], v[192:193] op_sel:[1,1]
	v_pk_mov_b32 v[254:255], v[180:181], v[196:197] op_sel:[1,1]
	v_pk_fma_f32 v[232:233], v[32:33], v[200:201], v[232:233] op_sel_hi:[0,1,1]
	v_pk_fma_f32 v[234:235], v[34:35], v[202:203], v[234:235] op_sel_hi:[0,1,1]
	v_pk_fma_f32 v[244:245], v[36:37], v[204:205], v[244:245] op_sel_hi:[0,1,1]
	v_pk_fma_f32 v[254:255], v[38:39], v[206:207], v[254:255] op_sel_hi:[0,1,1]
	v_pk_fma_f32 v[200:201], v[32:33], v[200:201], v[232:233] op_sel:[1,1,0] op_sel_hi:[1,0,1] neg_lo:[1,0,0]
	v_pk_fma_f32 v[202:203], v[34:35], v[202:203], v[234:235] op_sel:[1,1,0] op_sel_hi:[1,0,1] neg_lo:[1,0,0]
	v_pk_fma_f32 v[204:205], v[36:37], v[204:205], v[244:245] op_sel:[1,1,0] op_sel_hi:[1,0,1] neg_lo:[1,0,0]
	v_pk_fma_f32 v[206:207], v[38:39], v[206:207], v[254:255] op_sel:[1,1,0] op_sel_hi:[1,0,1] neg_lo:[1,0,0]
	v_cvt_pk_bf16_f32 v124, v200, v201
	v_cvt_pk_bf16_f32 v125, v202, v203
	v_cvt_pk_bf16_f32 v126, v204, v205
	v_cvt_pk_bf16_f32 v127, v206, v207
	ds_write_b128 v241, v[124:127] offset:4352
	s_waitcnt lgkmcnt(2)
	v_mfma_f32_16x16x32_bf16 v[120:123], v[40:43], v[216:219], 0
	v_mfma_f32_16x16x32_bf16 v[120:123], v[44:47], v[220:223], v[120:123]
	v_mfma_f32_16x16x32_bf16 v[120:123], v[48:51], v[224:227], v[120:123]
	v_mfma_f32_16x16x32_bf16 v[120:123], v[52:55], v[228:231], v[120:123]
	v_pk_mov_b32 v[232:233], v[170:171], v[186:187] op_sel:[0,0]
	v_pk_mov_b32 v[234:235], v[174:175], v[190:191] op_sel:[0,0]
	v_pk_mov_b32 v[244:245], v[178:179], v[194:195] op_sel:[0,0]
	v_pk_mov_b32 v[254:255], v[182:183], v[198:199] op_sel:[0,0]
	v_pk_fma_f32 v[232:233], v[32:33], v[200:201], v[232:233] op_sel_hi:[0,1,1]
	v_pk_fma_f32 v[234:235], v[34:35], v[202:203], v[234:235] op_sel_hi:[0,1,1]
	v_pk_fma_f32 v[244:245], v[36:37], v[204:205], v[244:245] op_sel_hi:[0,1,1]
	v_pk_fma_f32 v[254:255], v[38:39], v[206:207], v[254:255] op_sel_hi:[0,1,1]
	v_pk_fma_f32 v[200:201], v[32:33], v[200:201], v[232:233] op_sel:[1,1,0] op_sel_hi:[1,0,1] neg_lo:[1,0,0]
	v_pk_fma_f32 v[202:203], v[34:35], v[202:203], v[234:235] op_sel:[1,1,0] op_sel_hi:[1,0,1] neg_lo:[1,0,0]
	v_pk_fma_f32 v[204:205], v[36:37], v[204:205], v[244:245] op_sel:[1,1,0] op_sel_hi:[1,0,1] neg_lo:[1,0,0]
	v_pk_fma_f32 v[206:207], v[38:39], v[206:207], v[254:255] op_sel:[1,1,0] op_sel_hi:[1,0,1] neg_lo:[1,0,0]
	v_cvt_pk_bf16_f32 v124, v200, v201
	v_cvt_pk_bf16_f32 v125, v202, v203
	v_cvt_pk_bf16_f32 v126, v204, v205
	v_cvt_pk_bf16_f32 v127, v206, v207
	ds_write_b128 v241, v[124:127] offset:4608
	v_pk_mov_b32 v[232:233], v[170:171], v[186:187] op_sel:[1,1]
	v_pk_mov_b32 v[234:235], v[174:175], v[190:191] op_sel:[1,1]
	v_pk_mov_b32 v[244:245], v[178:179], v[194:195] op_sel:[1,1]
	v_pk_mov_b32 v[254:255], v[182:183], v[198:199] op_sel:[1,1]
	v_pk_fma_f32 v[232:233], v[32:33], v[200:201], v[232:233] op_sel_hi:[0,1,1]
	v_pk_fma_f32 v[234:235], v[34:35], v[202:203], v[234:235] op_sel_hi:[0,1,1]
	v_pk_fma_f32 v[244:245], v[36:37], v[204:205], v[244:245] op_sel_hi:[0,1,1]
	v_pk_fma_f32 v[254:255], v[38:39], v[206:207], v[254:255] op_sel_hi:[0,1,1]
	v_pk_fma_f32 v[200:201], v[32:33], v[200:201], v[232:233] op_sel:[1,1,0] op_sel_hi:[1,0,1] neg_lo:[1,0,0]
	v_pk_fma_f32 v[202:203], v[34:35], v[202:203], v[234:235] op_sel:[1,1,0] op_sel_hi:[1,0,1] neg_lo:[1,0,0]
	v_pk_fma_f32 v[204:205], v[36:37], v[204:205], v[244:245] op_sel:[1,1,0] op_sel_hi:[1,0,1] neg_lo:[1,0,0]
	v_pk_fma_f32 v[206:207], v[38:39], v[206:207], v[254:255] op_sel:[1,1,0] op_sel_hi:[1,0,1] neg_lo:[1,0,0]
	v_cvt_pk_bf16_f32 v124, v200, v201
	v_cvt_pk_bf16_f32 v125, v202, v203
	v_cvt_pk_bf16_f32 v126, v204, v205
	v_cvt_pk_bf16_f32 v127, v206, v207
	ds_write_b128 v241, v[124:127] offset:4864
	global_load_dwordx4 v[108:111], v238, s[20:21]
	v_add_u32_e32 v238, v238, v243
	v_cvt_pk_bf16_f32 v124, v120, v121
	v_cvt_pk_bf16_f32 v125, v122, v123
	s_nop 0
	global_store_dwordx2 v239, v[124:125], s[24:25]
	v_add_u32_e32 v239, v239, v243
	s_waitcnt vmcnt(33)
; __device__ __forceinline__ unsigned f2bf(float f) { unsigned u = __builtin_bit_cast(unsigned, f); return (u + 0x7fffu + ((u >> 16) & 1u)) >> 16; }
; __device__ __forceinline__ bf16x8 pack8(const float (&f)[8]) { u32x4 h; h.x = pk2(f[0], f[1]); h.y = pk2(f[2], f[3]); h.z = pk2(f[4], f[5]); h.w = pk2(f[6], f[7]); return __builtin_bit_cast(bf16x8, h); }
; template <bool FINAL> __device__ __forceinline__ void phase_s5_scan(const Fr& F) {
;     ...
;         for (int sub = 0; sub < 4; ++sub) {
;             const bf16x8 A1 = __builtin_bit_cast(bf16x8, uc[sub]);
; #pragma unroll
;             for (int nt = 0; nt < 8; ++nt) {
;                 f32x4 acc = {0.f, 0.f, 0.f, 0.f};
;                 acc = __builtin_amdgcn_mfma_f32_16x16x32_bf16(A1, B1[nt], acc, 0, 0, 0);
; #pragma unroll
;                 for (int reg = 0; reg < 4; ++reg) BUl[(4 * lq + reg) * 132 + 16 * nt + l15] = acc[reg];
;             }
;             asm volatile("s_waitcnt lgkmcnt(0)" ::: "memory");
; #pragma unroll 4
;             for (int jj = 0; jj < 16; ++jj) {
;                 const float br_ = BUl[jj * 132 + lane], bi_ = BUl[jj * 132 + 64 + lane];
;                 const float nr = ar * xr - ai * xi + br_, ni = ar * xi + ai * xr + bi_; xr = nr; xi = ni;
;                 if (FINAL) { BUl[jj * 132 + lane] = xr; BUl[jj * 132 + 64 + lane] = xi; }
;             }
;             if (FINAL) {
;                 asm volatile("s_waitcnt lgkmcnt(0)" ::: "memory");
;                 f32x4 acc = {0.f, 0.f, 0.f, 0.f};
; #pragma unroll
;                 for (int ks = 0; ks < 4; ++ks) {
;                     const f32x4 t0 = *(const f32x4*)(BUl + l15 * 132 + 32 * ks + 8 * lq), t1 = *(const f32x4*)(BUl + l15 * 132 + 32 * ks + 8 * lq + 4);
;                     const float xf[8] = {t0.x, t0.y, t0.z, t0.w, t1.x, t1.y, t1.z, t1.w};
;                     acc = __builtin_amdgcn_mfma_f32_16x16x32_bf16(pack8(xf), Chi[ks], acc, 0, 0, 0);
;                 }
; #pragma unroll
;                 for (int reg = 0; reg < 4; ++reg) { const int tok = tokof(s, chunk * 64 + sub * 16 + 4 * lq + reg);
;                     Yb[((size_t)b * TB + tok) * D + g * 16 + l15] = (bf16)f2bf(acc[reg]); }
;                 asm volatile("s_waitcnt lgkmcnt(0)" ::: "memory");
	v_mfma_f32_16x16x32_bf16 v[168:171], v[116:119], v[0:3], 0
	v_mfma_f32_16x16x32_bf16 v[172:175], v[116:119], v[4:7], 0
	v_mfma_f32_16x16x32_bf16 v[176:179], v[116:119], v[8:11], 0
	v_mfma_f32_16x16x32_bf16 v[180:183], v[116:119], v[12:15], 0
	v_mfma_f32_16x16x32_bf16 v[184:187], v[116:119], v[16:19], 0
	v_mfma_f32_16x16x32_bf16 v[188:191], v[116:119], v[20:23], 0
	v_mfma_f32_16x16x32_bf16 v[192:195], v[116:119], v[24:27], 0
	v_mfma_f32_16x16x32_bf16 v[196:199], v[116:119], v[28:31], 0
	ds_read_b128 v[216:219], v242 offset:4096
	ds_read_b128 v[220:223], v242 offset:4160
	ds_read_b128 v[224:227], v242 offset:4224
	ds_read_b128 v[228:231], v242 offset:4288
	v_pk_mov_b32 v[232:233], v[136:137], v[152:153] op_sel:[0,0]
	v_pk_mov_b32 v[234:235], v[140:141], v[156:157] op_sel:[0,0]
	v_pk_mov_b32 v[244:245], v[144:145], v[160:161] op_sel:[0,0]
	v_pk_mov_b32 v[254:255], v[148:149], v[164:165] op_sel:[0,0]
	v_pk_fma_f32 v[232:233], v[32:33], v[200:201], v[232:233] op_sel_hi:[0,1,1]
	v_pk_fma_f32 v[234:235], v[34:35], v[202:203], v[234:235] op_sel_hi:[0,1,1]
	v_pk_fma_f32 v[244:245], v[36:37], v[204:205], v[244:245] op_sel_hi:[0,1,1]
	v_pk_fma_f32 v[254:255], v[38:39], v[206:207], v[254:255] op_sel_hi:[0,1,1]
	v_pk_fma_f32 v[200:201], v[32:33], v[200:201], v[232:233] op_sel:[1,1,0] op_sel_hi:[1,0,1] neg_lo:[1,0,0]
	v_pk_fma_f32 v[202:203], v[34:35], v[202:203], v[234:235] op_sel:[1,1,0] op_sel_hi:[1,0,1] neg_lo:[1,0,0]
	v_pk_fma_f32 v[204:205], v[36:37], v[204:205], v[244:245] op_sel:[1,1,0] op_sel_hi:[1,0,1] neg_lo:[1,0,0]
	v_pk_fma_f32 v[206:207], v[38:39], v[206:207], v[254:255] op_sel:[1,1,0] op_sel_hi:[1,0,1] neg_lo:[1,0,0]
	v_cvt_pk_bf16_f32 v124, v200, v201
	v_cvt_pk_bf16_f32 v125, v202, v203
	v_cvt_pk_bf16_f32 v126, v204, v205
	v_cvt_pk_bf16_f32 v127, v206, v207
	ds_write_b128 v241, v[124:127] offset:0
	v_pk_mov_b32 v[232:233], v[136:137], v[152:153] op_sel:[1,1]
	v_pk_mov_b32 v[234:235], v[140:141], v[156:157] op_sel:[1,1]
	v_pk_mov_b32 v[244:245], v[144:145], v[160:161] op_sel:[1,1]
	v_pk_mov_b32 v[254:255], v[148:149], v[164:165] op_sel:[1,1]
	v_pk_fma_f32 v[232:233], v[32:33], v[200:201], v[232:233] op_sel_hi:[0,1,1]
	v_pk_fma_f32 v[234:235], v[34:35], v[202:203], v[234:235] op_sel_hi:[0,1,1]
	v_pk_fma_f32 v[244:245], v[36:37], v[204:205], v[244:245] op_sel_hi:[0,1,1]
	v_pk_fma_f32 v[254:255], v[38:39], v[206:207], v[254:255] op_sel_hi:[0,1,1]
	v_pk_fma_f32 v[200:201], v[32:33], v[200:201], v[232:233] op_sel:[1,1,0] op_sel_hi:[1,0,1] neg_lo:[1,0,0]
	v_pk_fma_f32 v[202:203], v[34:35], v[202:203], v[234:235] op_sel:[1,1,0] op_sel_hi:[1,0,1] neg_lo:[1,0,0]
	v_pk_fma_f32 v[204:205], v[36:37], v[204:205], v[244:245] op_sel:[1,1,0] op_sel_hi:[1,0,1] neg_lo:[1,0,0]
	v_pk_fma_f32 v[206:207], v[38:39], v[206:207], v[254:255] op_sel:[1,1,0] op_sel_hi:[1,0,1] neg_lo:[1,0,0]
	v_cvt_pk_bf16_f32 v124, v200, v201
	v_cvt_pk_bf16_f32 v125, v202, v203
	v_cvt_pk_bf16_f32 v126, v204, v205
	v_cvt_pk_bf16_f32 v127, v206, v207
	ds_write_b128 v241, v[124:127] offset:256
	s_waitcnt lgkmcnt(2)
	v_mfma_f32_16x16x32_bf16 v[120:123], v[40:43], v[216:219], 0
	v_mfma_f32_16x16x32_bf16 v[120:123], v[44:47], v[220:223], v[120:123]
	v_mfma_f32_16x16x32_bf16 v[120:123], v[48:51], v[224:227], v[120:123]
	v_mfma_f32_16x16x32_bf16 v[120:123], v[52:55], v[228:231], v[120:123]
	v_pk_mov_b32 v[232:233], v[138:139], v[154:155] op_sel:[0,0]
	v_pk_mov_b32 v[234:235], v[142:143], v[158:159] op_sel:[0,0]
	v_pk_mov_b32 v[244:245], v[146:147], v[162:163] op_sel:[0,0]
	v_pk_mov_b32 v[254:255], v[150:151], v[166:167] op_sel:[0,0]
	v_pk_fma_f32 v[232:233], v[32:33], v[200:201], v[232:233] op_sel_hi:[0,1,1]
	v_pk_fma_f32 v[234:235], v[34:35], v[202:203], v[234:235] op_sel_hi:[0,1,1]
	v_pk_fma_f32 v[244:245], v[36:37], v[204:205], v[244:245] op_sel_hi:[0,1,1]
	v_pk_fma_f32 v[254:255], v[38:39], v[206:207], v[254:255] op_sel_hi:[0,1,1]
	v_pk_fma_f32 v[200:201], v[32:33], v[200:201], v[232:233] op_sel:[1,1,0] op_sel_hi:[1,0,1] neg_lo:[1,0,0]
	v_pk_fma_f32 v[202:203], v[34:35], v[202:203], v[234:235] op_sel:[1,1,0] op_sel_hi:[1,0,1] neg_lo:[1,0,0]
	v_pk_fma_f32 v[204:205], v[36:37], v[204:205], v[244:245] op_sel:[1,1,0] op_sel_hi:[1,0,1] neg_lo:[1,0,0]
	v_pk_fma_f32 v[206:207], v[38:39], v[206:207], v[254:255] op_sel:[1,1,0] op_sel_hi:[1,0,1] neg_lo:[1,0,0]
	v_cvt_pk_bf16_f32 v124, v200, v201
	v_cvt_pk_bf16_f32 v125, v202, v203
	v_cvt_pk_bf16_f32 v126, v204, v205
	v_cvt_pk_bf16_f32 v127, v206, v207
	ds_write_b128 v241, v[124:127] offset:512
	v_pk_mov_b32 v[232:233], v[138:139], v[154:155] op_sel:[1,1]
	v_pk_mov_b32 v[234:235], v[142:143], v[158:159] op_sel:[1,1]
	v_pk_mov_b32 v[244:245], v[146:147], v[162:163] op_sel:[1,1]
	v_pk_mov_b32 v[254:255], v[150:151], v[166:167] op_sel:[1,1]
	v_pk_fma_f32 v[232:233], v[32:33], v[200:201], v[232:233] op_sel_hi:[0,1,1]
	v_pk_fma_f32 v[234:235], v[34:35], v[202:203], v[234:235] op_sel_hi:[0,1,1]
	v_pk_fma_f32 v[244:245], v[36:37], v[204:205], v[244:245] op_sel_hi:[0,1,1]
	v_pk_fma_f32 v[254:255], v[38:39], v[206:207], v[254:255] op_sel_hi:[0,1,1]
	v_pk_fma_f32 v[200:201], v[32:33], v[200:201], v[232:233] op_sel:[1,1,0] op_sel_hi:[1,0,1] neg_lo:[1,0,0]
	v_pk_fma_f32 v[202:203], v[34:35], v[202:203], v[234:235] op_sel:[1,1,0] op_sel_hi:[1,0,1] neg_lo:[1,0,0]
	v_pk_fma_f32 v[204:205], v[36:37], v[204:205], v[244:245] op_sel:[1,1,0] op_sel_hi:[1,0,1] neg_lo:[1,0,0]
	v_pk_fma_f32 v[206:207], v[38:39], v[206:207], v[254:255] op_sel:[1,1,0] op_sel_hi:[1,0,1] neg_lo:[1,0,0]
	v_cvt_pk_bf16_f32 v124, v200, v201
	v_cvt_pk_bf16_f32 v125, v202, v203
	v_cvt_pk_bf16_f32 v126, v204, v205
	v_cvt_pk_bf16_f32 v127, v206, v207
	ds_write_b128 v241, v[124:127] offset:768
; __device__ __forceinline__ unsigned f2bf(float f) { unsigned u = __builtin_bit_cast(unsigned, f); return (u + 0x7fffu + ((u >> 16) & 1u)) >> 16; }
; __device__ __forceinline__ bf16x8 pack8(const float (&f)[8]) { u32x4 h; h.x = pk2(f[0], f[1]); h.y = pk2(f[2], f[3]); h.z = pk2(f[4], f[5]); h.w = pk2(f[6], f[7]); return __builtin_bit_cast(bf16x8, h); }
; template <bool FINAL> __device__ __forceinline__ void phase_s5_scan(const Fr& F) {
;     ...
;             if (FINAL) {
;                 asm volatile("s_waitcnt lgkmcnt(0)" ::: "memory");
;                 f32x4 acc = {0.f, 0.f, 0.f, 0.f};
; #pragma unroll
;                 for (int ks = 0; ks < 4; ++ks) {
;                     const f32x4 t0 = *(const f32x4*)(BUl + l15 * 132 + 32 * ks + 8 * lq), t1 = *(const f32x4*)(BUl + l15 * 132 + 32 * ks + 8 * lq + 4);
;                     const float xf[8] = {t0.x, t0.y, t0.z, t0.w, t1.x, t1.y, t1.z, t1.w};
;                     acc = __builtin_amdgcn_mfma_f32_16x16x32_bf16(pack8(xf), Chi[ks], acc, 0, 0, 0);
;                 }
; #pragma unroll
;                 for (int reg = 0; reg < 4; ++reg) { const int tok = tokof(s, chunk * 64 + sub * 16 + 4 * lq + reg);
;                     Yb[((size_t)b * TB + tok) * D + g * 16 + l15] = (bf16)f2bf(acc[reg]); }
;                 asm volatile("s_waitcnt lgkmcnt(0)" ::: "memory");
;             }
;         }
	global_load_dwordx4 v[112:115], v238, s[20:21]
	v_add_u32_e32 v238, v238, v243
	v_cvt_pk_bf16_f32 v124, v120, v121
	v_cvt_pk_bf16_f32 v125, v122, v123
	s_nop 0
	global_store_dwordx2 v239, v[124:125], s[24:25]
	v_add_u32_e32 v239, v239, v243
	ds_read_b128 v[216:219], v242 offset:0
	ds_read_b128 v[220:223], v242 offset:64
	ds_read_b128 v[224:227], v242 offset:128
	ds_read_b128 v[228:231], v242 offset:192
	v_pk_mov_b32 v[232:233], v[168:169], v[184:185] op_sel:[0,0]
	v_pk_mov_b32 v[234:235], v[172:173], v[188:189] op_sel:[0,0]
	v_pk_mov_b32 v[244:245], v[176:177], v[192:193] op_sel:[0,0]
	v_pk_mov_b32 v[254:255], v[180:181], v[196:197] op_sel:[0,0]
	v_pk_fma_f32 v[232:233], v[32:33], v[200:201], v[232:233] op_sel_hi:[0,1,1]
	v_pk_fma_f32 v[234:235], v[34:35], v[202:203], v[234:235] op_sel_hi:[0,1,1]
	v_pk_fma_f32 v[244:245], v[36:37], v[204:205], v[244:245] op_sel_hi:[0,1,1]
	v_pk_fma_f32 v[254:255], v[38:39], v[206:207], v[254:255] op_sel_hi:[0,1,1]
	v_pk_fma_f32 v[200:201], v[32:33], v[200:201], v[232:233] op_sel:[1,1,0] op_sel_hi:[1,0,1] neg_lo:[1,0,0]
	v_pk_fma_f32 v[202:203], v[34:35], v[202:203], v[234:235] op_sel:[1,1,0] op_sel_hi:[1,0,1] neg_lo:[1,0,0]
	v_pk_fma_f32 v[204:205], v[36:37], v[204:205], v[244:245] op_sel:[1,1,0] op_sel_hi:[1,0,1] neg_lo:[1,0,0]
	v_pk_fma_f32 v[206:207], v[38:39], v[206:207], v[254:255] op_sel:[1,1,0] op_sel_hi:[1,0,1] neg_lo:[1,0,0]
	v_cvt_pk_bf16_f32 v124, v200, v201
	v_cvt_pk_bf16_f32 v125, v202, v203
	v_cvt_pk_bf16_f32 v126, v204, v205
	v_cvt_pk_bf16_f32 v127, v206, v207
	ds_write_b128 v241, v[124:127] offset:4096
	v_pk_mov_b32 v[232:233], v[168:169], v[184:185] op_sel:[1,1]
	v_pk_mov_b32 v[234:235], v[172:173], v[188:189] op_sel:[1,1]
	v_pk_mov_b32 v[244:245], v[176:177], v[192:193] op_sel:[1,1]
	v_pk_mov_b32 v[254:255], v[180:181], v[196:197] op_sel:[1,1]
	v_pk_fma_f32 v[232:233], v[32:33], v[200:201], v[232:233] op_sel_hi:[0,1,1]
	v_pk_fma_f32 v[234:235], v[34:35], v[202:203], v[234:235] op_sel_hi:[0,1,1]
	v_pk_fma_f32 v[244:245], v[36:37], v[204:205], v[244:245] op_sel_hi:[0,1,1]
	v_pk_fma_f32 v[254:255], v[38:39], v[206:207], v[254:255] op_sel_hi:[0,1,1]
	v_pk_fma_f32 v[200:201], v[32:33], v[200:201], v[232:233] op_sel:[1,1,0] op_sel_hi:[1,0,1] neg_lo:[1,0,0]
	v_pk_fma_f32 v[202:203], v[34:35], v[202:203], v[234:235] op_sel:[1,1,0] op_sel_hi:[1,0,1] neg_lo:[1,0,0]
	v_pk_fma_f32 v[204:205], v[36:37], v[204:205], v[244:245] op_sel:[1,1,0] op_sel_hi:[1,0,1] neg_lo:[1,0,0]
	v_pk_fma_f32 v[206:207], v[38:39], v[206:207], v[254:255] op_sel:[1,1,0] op_sel_hi:[1,0,1] neg_lo:[1,0,0]
	v_cvt_pk_bf16_f32 v124, v200, v201
	v_cvt_pk_bf16_f32 v125, v202, v203
	v_cvt_pk_bf16_f32 v126, v204, v205
	v_cvt_pk_bf16_f32 v127, v206, v207
	ds_write_b128 v241, v[124:127] offset:4352
	s_waitcnt lgkmcnt(2)
	v_mfma_f32_16x16x32_bf16 v[120:123], v[40:43], v[216:219], 0
	v_mfma_f32_16x16x32_bf16 v[120:123], v[44:47], v[220:223], v[120:123]
	v_mfma_f32_16x16x32_bf16 v[120:123], v[48:51], v[224:227], v[120:123]
	v_mfma_f32_16x16x32_bf16 v[120:123], v[52:55], v[228:231], v[120:123]
	v_pk_mov_b32 v[232:233], v[170:171], v[186:187] op_sel:[0,0]
	v_pk_mov_b32 v[234:235], v[174:175], v[190:191] op_sel:[0,0]
	v_pk_mov_b32 v[244:245], v[178:179], v[194:195] op_sel:[0,0]
	v_pk_mov_b32 v[254:255], v[182:183], v[198:199] op_sel:[0,0]
	v_pk_fma_f32 v[232:233], v[32:33], v[200:201], v[232:233] op_sel_hi:[0,1,1]
	v_pk_fma_f32 v[234:235], v[34:35], v[202:203], v[234:235] op_sel_hi:[0,1,1]
	v_pk_fma_f32 v[244:245], v[36:37], v[204:205], v[244:245] op_sel_hi:[0,1,1]
	v_pk_fma_f32 v[254:255], v[38:39], v[206:207], v[254:255] op_sel_hi:[0,1,1]
	v_pk_fma_f32 v[200:201], v[32:33], v[200:201], v[232:233] op_sel:[1,1,0] op_sel_hi:[1,0,1] neg_lo:[1,0,0]
	v_pk_fma_f32 v[202:203], v[34:35], v[202:203], v[234:235] op_sel:[1,1,0] op_sel_hi:[1,0,1] neg_lo:[1,0,0]
	v_pk_fma_f32 v[204:205], v[36:37], v[204:205], v[244:245] op_sel:[1,1,0] op_sel_hi:[1,0,1] neg_lo:[1,0,0]
	v_pk_fma_f32 v[206:207], v[38:39], v[206:207], v[254:255] op_sel:[1,1,0] op_sel_hi:[1,0,1] neg_lo:[1,0,0]
	v_cvt_pk_bf16_f32 v124, v200, v201
	v_cvt_pk_bf16_f32 v125, v202, v203
	v_cvt_pk_bf16_f32 v126, v204, v205
	v_cvt_pk_bf16_f32 v127, v206, v207
	ds_write_b128 v241, v[124:127] offset:4608
	v_pk_mov_b32 v[232:233], v[170:171], v[186:187] op_sel:[1,1]
	v_pk_mov_b32 v[234:235], v[174:175], v[190:191] op_sel:[1,1]
	v_pk_mov_b32 v[244:245], v[178:179], v[194:195] op_sel:[1,1]
	v_pk_mov_b32 v[254:255], v[182:183], v[198:199] op_sel:[1,1]
	v_pk_fma_f32 v[232:233], v[32:33], v[200:201], v[232:233] op_sel_hi:[0,1,1]
	v_pk_fma_f32 v[234:235], v[34:35], v[202:203], v[234:235] op_sel_hi:[0,1,1]
	v_pk_fma_f32 v[244:245], v[36:37], v[204:205], v[244:245] op_sel_hi:[0,1,1]
	v_pk_fma_f32 v[254:255], v[38:39], v[206:207], v[254:255] op_sel_hi:[0,1,1]
	v_pk_fma_f32 v[200:201], v[32:33], v[200:201], v[232:233] op_sel:[1,1,0] op_sel_hi:[1,0,1] neg_lo:[1,0,0]
	v_pk_fma_f32 v[202:203], v[34:35], v[202:203], v[234:235] op_sel:[1,1,0] op_sel_hi:[1,0,1] neg_lo:[1,0,0]
	v_pk_fma_f32 v[204:205], v[36:37], v[204:205], v[244:245] op_sel:[1,1,0] op_sel_hi:[1,0,1] neg_lo:[1,0,0]
	v_pk_fma_f32 v[206:207], v[38:39], v[206:207], v[254:255] op_sel:[1,1,0] op_sel_hi:[1,0,1] neg_lo:[1,0,0]
	v_cvt_pk_bf16_f32 v124, v200, v201
	v_cvt_pk_bf16_f32 v125, v202, v203
	v_cvt_pk_bf16_f32 v126, v204, v205
	v_cvt_pk_bf16_f32 v127, v206, v207
	ds_write_b128 v241, v[124:127] offset:4864
	global_load_dwordx4 v[116:119], v238, s[20:21]
	v_add_u32_e32 v238, v238, v243
	v_cvt_pk_bf16_f32 v124, v120, v121
	v_cvt_pk_bf16_f32 v125, v122, v123
	s_nop 0
	global_store_dwordx2 v239, v[124:125], s[24:25]
	v_add_u32_e32 v239, v239, v243
	ds_read_b128 v[216:219], v242 offset:4096
	ds_read_b128 v[220:223], v242 offset:4160
	ds_read_b128 v[224:227], v242 offset:4224
	ds_read_b128 v[228:231], v242 offset:4288
	s_waitcnt lgkmcnt(0)
	v_mfma_f32_16x16x32_bf16 v[120:123], v[40:43], v[216:219], 0
	v_mfma_f32_16x16x32_bf16 v[120:123], v[44:47], v[220:223], v[120:123]
	v_mfma_f32_16x16x32_bf16 v[120:123], v[48:51], v[224:227], v[120:123]
	v_mfma_f32_16x16x32_bf16 v[120:123], v[52:55], v[228:231], v[120:123]
	s_nop 7
	s_nop 1
	v_cvt_pk_bf16_f32 v124, v120, v121
	v_cvt_pk_bf16_f32 v125, v122, v123
	s_nop 0
	global_store_dwordx2 v239, v[124:125], s[24:25]
	v_add_u32_e32 v239, v239, v243
	s_add_i32 s14, s14, 16
	s_add_i32 s19, s19, 1
	s_cmp_lt_u32 s19, s56
	s_cbranch_scc1 .Ls5b_grp
	s_waitcnt vmcnt(0) lgkmcnt(0)
	v_mov_b32_e32 v2, s34
	v_mov_b32_e32 v3, s35

; __global__ void __launch_bounds__(NTHR) fwd_kernel(Args args) {
	.amdhsa_kernel _Z10fwd_kernel4Args
		.amdhsa_group_segment_fixed_size 0
		.amdhsa_private_segment_fixed_size 0
		.amdhsa_kernarg_size 584
		.amdhsa_user_sgpr_count 2
		.amdhsa_user_sgpr_dispatch_ptr 0
		.amdhsa_user_sgpr_queue_ptr 0
		.amdhsa_user_sgpr_kernarg_segment_ptr 1
		.amdhsa_user_sgpr_dispatch_id 0
		.amdhsa_user_sgpr_kernarg_preload_length 0
		.amdhsa_user_sgpr_kernarg_preload_offset 0
		.amdhsa_user_sgpr_private_segment_size 0
		.amdhsa_uses_dynamic_stack 0
		.amdhsa_enable_private_segment 0
		.amdhsa_system_sgpr_workgroup_id_x 1
		.amdhsa_system_sgpr_workgroup_id_y 0
		.amdhsa_system_sgpr_workgroup_id_z 0
		.amdhsa_system_sgpr_workgroup_info 0
		.amdhsa_system_vgpr_workitem_id 2
		.amdhsa_next_free_vgpr 256
		.amdhsa_next_free_sgpr 97
		.amdhsa_accum_offset 256
		.amdhsa_reserve_vcc 1
		.amdhsa_float_round_mode_32 0
		.amdhsa_float_round_mode_16_64 0
		.amdhsa_float_denorm_mode_32 3
		.amdhsa_float_denorm_mode_16_64 3
		.amdhsa_dx10_clamp 1
		.amdhsa_ieee_mode 1
		.amdhsa_fp16_overflow 0
		.amdhsa_tg_split 0
		.amdhsa_exception_fp_ieee_invalid_op 0
		.amdhsa_exception_fp_denorm_src 0
		.amdhsa_exception_fp_ieee_div_zero 0
		.amdhsa_exception_fp_ieee_overflow 0
		.amdhsa_exception_fp_ieee_underflow 0
		.amdhsa_exception_fp_ieee_inexact 0
		.amdhsa_exception_int_div_zero 0
	.end_amdhsa_kernel

; __global__ void __launch_bounds__(NTHR) fwd_kernel(Args args) {
amdhsa.kernels:
  - .agpr_count:     0
    .args:
      - .offset:         0
        .size:           328
        .value_kind:     by_value
      - .offset:         328
        .size:           4
        .value_kind:     hidden_block_count_x
      - .offset:         332
        .size:           4
        .value_kind:     hidden_block_count_y
      - .offset:         336
        .size:           4
        .value_kind:     hidden_block_count_z
      - .offset:         340
        .size:           2
        .value_kind:     hidden_group_size_x
      - .offset:         342
        .size:           2
        .value_kind:     hidden_group_size_y
      - .offset:         344
        .size:           2
        .value_kind:     hidden_group_size_z
      - .offset:         346
        .size:           2
        .value_kind:     hidden_remainder_x
      - .offset:         348
        .size:           2
        .value_kind:     hidden_remainder_y
      - .offset:         350
        .size:           2
        .value_kind:     hidden_remainder_z
      - .offset:         368
        .size:           8
        .value_kind:     hidden_global_offset_x
      - .offset:         376
        .size:           8
        .value_kind:     hidden_global_offset_y
      - .offset:         384
        .size:           8
        .value_kind:     hidden_global_offset_z
      - .offset:         392
        .size:           2
        .value_kind:     hidden_grid_dims
      - .offset:         416
        .size:           8
        .value_kind:     hidden_multigrid_sync_arg
      - .offset:         448
        .size:           4
        .value_kind:     hidden_dynamic_lds_size
    .group_segment_fixed_size: 0
    .kernarg_segment_align: 8
    .kernarg_segment_size: 584
    .language:       OpenCL C
    .language_version:
      - 2
      - 0
    .max_flat_workgroup_size: 512
    .name:           _Z10fwd_kernel4Args
    .private_segment_fixed_size: 0
    .sgpr_count:     103
    .sgpr_spill_count: 0
    .symbol:         _Z10fwd_kernel4Args.kd
    .uniform_work_group_size: 1
    .uses_dynamic_stack: false
    .vgpr_count:     256
    .vgpr_spill_count: 0
    .wavefront_size: 64
